# GEMM K-loops: m0 write moved ahead of the address add so the LDS-DMA hazard slot needs no s_nop
# speedup vs baseline: 1.0008x; 1.0008x over previous
; #define STAGE(P, BASE, br, kt) STAGET(tid_, P, BASE, br, kt)
; #define LDA(dst, b, h) UFOR(m, 4) UFOR(k, 2) \
;     dst[m][k] = *reinterpret_cast<const bf16x8*>((char*)SA(b, h) + lds_byte(wr * 64 + m * 16 + fr, k * 32 + fq * 8))
; #define LDB(dst, b, h) UFOR(n, 2) UFOR(k, 2) \
;     dst[n][k] = *reinterpret_cast<const bf16x8*>((char*)SB(b, h) + lds_byte(wc * 32 + n * 16 + fr, k * 32 + fq * 8))
; #define MMA(ai, bj, At, Bq) do { __builtin_amdgcn_s_setprio(1); \
;     UFOR(m, 4) UFOR(n, 2) UFOR(k, 2) \
;       acc[ai][bj][m][n] = __builtin_amdgcn_mfma_f32_16x16x32_bf16(Bq[n][k], At[m][k], acc[ai][bj][m][n], 0, 0, 0); \
;     __builtin_amdgcn_s_setprio(0); } while (0)
; #define WAIT_L(n) asm volatile("s_waitcnt lgkmcnt(" #n ")" ::: "memory")
; #define BAR __builtin_amdgcn_s_barrier()
; #define SCHED __builtin_amdgcn_sched_barrier(0)
; template <int EPI, int K, int KL> ...
;     ...
;     LDB(B0, 0, 0); SCHED; LDA(At, 0, 0); STAGE(SA(1, 1), A, brow + HALF, t + 1);
;     WAIT_L(8); BAR; WAIT_L(0); MMA(0, 0, At, B0); BAR; SCHED;
;     LDB(B1, 0, 1); STAGE(SB(0, 0), Bt, bcol, t + 2);
;     BAR; WAIT_L(0); MMA(0, 1, At, B1); BAR;
;     LDA(At, 0, 1); STAGE(SA(0, 0), A, brow, t + 2);
;     BAR; WAIT_L(0); MMA(1, 0, At, B0); BAR; SCHED;
.LBB0_236:
	ds_read_b128 v[174:177], v170
	ds_read_b128 v[178:181], v170 offset:1024
	ds_read_b128 v[182:185], v170 offset:2048
	ds_read_b128 v[186:189], v170 offset:3072
	ds_read_b128 v[190:193], v162
	ds_read_b128 v[194:197], v162 offset:1024
	ds_read_b128 v[198:201], v161
	ds_read_b128 v[202:205], v161 offset:1024
	ds_read_b128 v[218:221], v160
	ds_read_b128 v[222:225], v160 offset:1024
	ds_read_b128 v[226:229], v159
	ds_read_b128 v[230:233], v159 offset:1024
	v_add_u32_e32 v171, 0xc000, v157
	v_lshl_add_u64 v[136:137], s[92:93], 0, v[150:151]
	v_readfirstlane_b32 s18, v171
	v_lshl_add_u64 v[138:139], v[136:137], 0, s[88:89]
	s_mov_b32 m0, s18
	v_add_u32_e32 v172, 0xe000, v157
	global_load_lds_dwordx4 v[138:139], off
	v_lshl_add_u64 v[138:139], s[92:93], 0, v[152:153]
	v_readfirstlane_b32 s18, v172
	s_mov_b32 m0, s18
	v_lshl_add_u64 v[208:209], v[138:139], 0, s[88:89]
	global_load_lds_dwordx4 v[208:209], off
	s_waitcnt lgkmcnt(8)
	s_barrier
	s_waitcnt lgkmcnt(0)
	s_waitcnt lgkmcnt(0)
	v_mfma_f32_16x16x32_bf16 v[124:127], v[174:177], v[190:193], v[124:127]
	v_mfma_f32_16x16x32_bf16 v[120:123], v[182:185], v[190:193], v[120:123]
	v_mfma_f32_16x16x32_bf16 v[116:119], v[174:177], v[198:201], v[116:119]
	v_mfma_f32_16x16x32_bf16 v[112:115], v[182:185], v[198:201], v[112:115]
	v_mfma_f32_16x16x32_bf16 v[108:111], v[174:177], v[218:221], v[108:111]
	v_mfma_f32_16x16x32_bf16 v[104:107], v[182:185], v[218:221], v[104:107]
	v_mfma_f32_16x16x32_bf16 v[100:103], v[174:177], v[226:229], v[100:103]
	v_mfma_f32_16x16x32_bf16 v[96:99], v[182:185], v[226:229], v[96:99]
	v_mfma_f32_16x16x32_bf16 v[124:127], v[178:181], v[194:197], v[124:127]
	v_mfma_f32_16x16x32_bf16 v[120:123], v[186:189], v[194:197], v[120:123]
	v_mfma_f32_16x16x32_bf16 v[116:119], v[178:181], v[202:205], v[116:119]
	v_mfma_f32_16x16x32_bf16 v[112:115], v[186:189], v[202:205], v[112:115]
	v_mfma_f32_16x16x32_bf16 v[108:111], v[178:181], v[222:225], v[108:111]
	v_mfma_f32_16x16x32_bf16 v[104:107], v[186:189], v[222:225], v[104:107]
	v_mfma_f32_16x16x32_bf16 v[100:103], v[178:181], v[230:233], v[100:103]
	v_mfma_f32_16x16x32_bf16 v[96:99], v[186:189], v[230:233], v[96:99]
	s_barrier
	ds_read_b128 v[234:237], v168
	ds_read_b128 v[238:241], v168 offset:1024
	ds_read_b128 v[242:245], v168 offset:2048
	ds_read_b128 v[246:249], v168 offset:3072
	v_lshl_add_u64 v[208:209], s[92:93], 0, v[146:147]
	v_readfirstlane_b32 s18, v156
	v_lshl_add_u64 v[210:211], v[208:209], 0, s[52:53]
	s_mov_b32 m0, s18
	v_add_u32_e32 v134, 0x2000, v156
	global_load_lds_dwordx4 v[210:211], off
	v_lshl_add_u64 v[210:211], s[92:93], 0, v[148:149]
	v_readfirstlane_b32 s18, v134
	s_mov_b32 m0, s18
	v_lshl_add_u64 v[214:215], v[210:211], 0, s[52:53]
	global_load_lds_dwordx4 v[214:215], off
	s_barrier
	s_waitcnt lgkmcnt(0)
	s_waitcnt lgkmcnt(0)
	v_mfma_f32_16x16x32_bf16 v[92:95], v[234:237], v[190:193], v[92:95]
	v_mfma_f32_16x16x32_bf16 v[88:91], v[242:245], v[190:193], v[88:91]
	v_mfma_f32_16x16x32_bf16 v[84:87], v[234:237], v[198:201], v[84:87]
	v_mfma_f32_16x16x32_bf16 v[80:83], v[242:245], v[198:201], v[80:83]
	v_mfma_f32_16x16x32_bf16 v[76:79], v[234:237], v[218:221], v[76:79]
	v_mfma_f32_16x16x32_bf16 v[72:75], v[242:245], v[218:221], v[72:75]
	v_mfma_f32_16x16x32_bf16 v[68:71], v[234:237], v[226:229], v[68:71]
	v_mfma_f32_16x16x32_bf16 v[64:67], v[242:245], v[226:229], v[64:67]
	v_mfma_f32_16x16x32_bf16 v[92:95], v[238:241], v[194:197], v[92:95]
	v_mfma_f32_16x16x32_bf16 v[88:91], v[246:249], v[194:197], v[88:91]
	v_mfma_f32_16x16x32_bf16 v[84:87], v[238:241], v[202:205], v[84:87]
	v_mfma_f32_16x16x32_bf16 v[80:83], v[246:249], v[202:205], v[80:83]
	v_mfma_f32_16x16x32_bf16 v[76:79], v[238:241], v[222:225], v[76:79]
	v_mfma_f32_16x16x32_bf16 v[72:75], v[246:249], v[222:225], v[72:75]
	v_mfma_f32_16x16x32_bf16 v[68:71], v[238:241], v[230:233], v[68:71]
	v_mfma_f32_16x16x32_bf16 v[64:67], v[246:249], v[230:233], v[64:67]
	v_readfirstlane_b32 s18, v157
	v_add_u32_e32 v134, 0x2000, v157
	v_lshl_add_u64 v[214:215], v[136:137], 0, s[8:9]
	s_mov_b32 m0, s18
	v_readfirstlane_b32 s18, v134
	s_barrier
	ds_read_b128 v[190:193], v162 offset:16384
	ds_read_b128 v[194:197], v162 offset:17408
	ds_read_b128 v[198:201], v161 offset:16384
	ds_read_b128 v[202:205], v161 offset:17408
	ds_read_b128 v[218:221], v160 offset:16384
	ds_read_b128 v[222:225], v160 offset:17408
	ds_read_b128 v[226:229], v159 offset:16384
	ds_read_b128 v[230:233], v159 offset:17408
	global_load_lds_dwordx4 v[214:215], off
	s_mov_b32 m0, s18
	v_lshl_add_u64 v[214:215], v[138:139], 0, s[8:9]
	global_load_lds_dwordx4 v[214:215], off
	s_barrier
	s_waitcnt lgkmcnt(0)
	s_waitcnt lgkmcnt(0)
	v_mfma_f32_16x16x32_bf16 v[60:63], v[174:177], v[190:193], v[60:63]
	v_mfma_f32_16x16x32_bf16 v[56:59], v[182:185], v[190:193], v[56:59]
	v_mfma_f32_16x16x32_bf16 v[52:55], v[174:177], v[198:201], v[52:55]
	v_mfma_f32_16x16x32_bf16 v[48:51], v[182:185], v[198:201], v[48:51]
	v_mfma_f32_16x16x32_bf16 v[44:47], v[174:177], v[218:221], v[44:47]
	v_mfma_f32_16x16x32_bf16 v[40:43], v[182:185], v[218:221], v[40:43]
	v_mfma_f32_16x16x32_bf16 v[36:39], v[174:177], v[226:229], v[36:39]
	v_mfma_f32_16x16x32_bf16 v[32:35], v[182:185], v[226:229], v[32:35]
	v_mfma_f32_16x16x32_bf16 v[60:63], v[178:181], v[194:197], v[60:63]
	v_mfma_f32_16x16x32_bf16 v[56:59], v[186:189], v[194:197], v[56:59]
	v_mfma_f32_16x16x32_bf16 v[52:55], v[178:181], v[202:205], v[52:55]
	v_mfma_f32_16x16x32_bf16 v[48:51], v[186:189], v[202:205], v[48:51]
	v_mfma_f32_16x16x32_bf16 v[44:47], v[178:181], v[222:225], v[44:47]
	v_mfma_f32_16x16x32_bf16 v[40:43], v[186:189], v[222:225], v[40:43]
	v_mfma_f32_16x16x32_bf16 v[36:39], v[178:181], v[230:233], v[36:39]
	v_mfma_f32_16x16x32_bf16 v[32:35], v[186:189], v[230:233], v[32:35]
	s_barrier
; #define STAGE(P, BASE, br, kt) STAGET(tid_, P, BASE, br, kt)
; #define LDA(dst, b, h) UFOR(m, 4) UFOR(k, 2) \
;     dst[m][k] = *reinterpret_cast<const bf16x8*>((char*)SA(b, h) + lds_byte(wr * 64 + m * 16 + fr, k * 32 + fq * 8))
; #define LDB(dst, b, h) UFOR(n, 2) UFOR(k, 2) \
;     dst[n][k] = *reinterpret_cast<const bf16x8*>((char*)SB(b, h) + lds_byte(wc * 32 + n * 16 + fr, k * 32 + fq * 8))
; #define MMA(ai, bj, At, Bq) do { __builtin_amdgcn_s_setprio(1); \
;     UFOR(m, 4) UFOR(n, 2) UFOR(k, 2) \
;       acc[ai][bj][m][n] = __builtin_amdgcn_mfma_f32_16x16x32_bf16(Bq[n][k], At[m][k], acc[ai][bj][m][n], 0, 0, 0); \
;     __builtin_amdgcn_s_setprio(0); } while (0)
; #define WAIT_V(n) asm volatile("s_waitcnt vmcnt(" #n ")" ::: "memory")
; #define WAIT_L(n) asm volatile("s_waitcnt lgkmcnt(" #n ")" ::: "memory")
; #define BAR __builtin_amdgcn_s_barrier()
; #define SCHED __builtin_amdgcn_sched_barrier(0)
; template <int EPI, int K, int KL> ...
;     ...
;     STAGE(SB(0, 1), Bt, bcol + HALF, t + 2);
;     WAIT_V(6); BAR; MMA(1, 1, At, B1); BAR;
;     LDB(B0, 1, 0); SCHED; LDA(At, 1, 0); STAGE(SA(0, 1), A, brow + HALF, t + 2);
;     WAIT_L(8); BAR; WAIT_L(0); MMA(0, 0, At, B0); BAR; SCHED;
;     LDB(B1, 1, 1); STAGE(SB(1, 0), Bt, bcol, t + 3);
;     BAR; WAIT_L(0); MMA(0, 1, At, B1); BAR;
;     LDA(At, 1, 1); STAGE(SA(1, 0), A, brow, t + 3);
	v_readfirstlane_b32 s18, v158
	v_add_u32_e32 v134, 0x2000, v158
	v_lshl_add_u64 v[174:175], v[208:209], 0, s[54:55]
	s_mov_b32 m0, s18
	v_readfirstlane_b32 s18, v134
	global_load_lds_dwordx4 v[174:175], off
	s_mov_b32 m0, s18
	v_lshl_add_u64 v[174:175], v[210:211], 0, s[54:55]
	global_load_lds_dwordx4 v[174:175], off
	s_waitcnt vmcnt(6)
	s_barrier
	v_mfma_f32_16x16x32_bf16 v[28:31], v[234:237], v[190:193], v[28:31]
	v_mfma_f32_16x16x32_bf16 v[24:27], v[242:245], v[190:193], v[24:27]
	v_mfma_f32_16x16x32_bf16 v[20:23], v[234:237], v[198:201], v[20:23]
	v_mfma_f32_16x16x32_bf16 v[16:19], v[242:245], v[198:201], v[16:19]
	v_mfma_f32_16x16x32_bf16 v[12:15], v[234:237], v[218:221], v[12:15]
	v_mfma_f32_16x16x32_bf16 v[8:11], v[242:245], v[218:221], v[8:11]
	v_mfma_f32_16x16x32_bf16 v[4:7], v[234:237], v[226:229], v[4:7]
	v_mfma_f32_16x16x32_bf16 v[0:3], v[242:245], v[226:229], v[0:3]
	v_mfma_f32_16x16x32_bf16 v[28:31], v[238:241], v[194:197], v[28:31]
	v_mfma_f32_16x16x32_bf16 v[24:27], v[246:249], v[194:197], v[24:27]
	v_mfma_f32_16x16x32_bf16 v[20:23], v[238:241], v[202:205], v[20:23]
	v_mfma_f32_16x16x32_bf16 v[16:19], v[246:249], v[202:205], v[16:19]
	v_mfma_f32_16x16x32_bf16 v[12:15], v[238:241], v[222:225], v[12:15]
	v_mfma_f32_16x16x32_bf16 v[8:11], v[246:249], v[222:225], v[8:11]
	v_mfma_f32_16x16x32_bf16 v[4:7], v[238:241], v[230:233], v[4:7]
	v_mfma_f32_16x16x32_bf16 v[0:3], v[246:249], v[230:233], v[0:3]
	s_barrier
	ds_read_b128 v[174:177], v164
	ds_read_b128 v[178:181], v164 offset:1024
	ds_read_b128 v[182:185], v164 offset:2048
	ds_read_b128 v[186:189], v164 offset:3072
	ds_read_b128 v[190:193], v162 offset:32768
	ds_read_b128 v[194:197], v162 offset:33792
	ds_read_b128 v[198:201], v161 offset:32768
	ds_read_b128 v[202:205], v161 offset:33792
	ds_read_b128 v[218:221], v160 offset:32768
	ds_read_b128 v[222:225], v160 offset:33792
	ds_read_b128 v[226:229], v159 offset:32768
	ds_read_b128 v[230:233], v159 offset:33792
	v_add_u32_e32 v134, 0x4000, v157
	v_lshl_add_u64 v[214:215], v[136:137], 0, s[12:13]
	v_readfirstlane_b32 s18, v134
	v_add_u32_e32 v134, 0x6000, v157
	s_mov_b32 m0, s18
	v_readfirstlane_b32 s18, v134
	global_load_lds_dwordx4 v[214:215], off
	s_mov_b32 m0, s18
	v_lshl_add_u64 v[214:215], v[138:139], 0, s[12:13]
	global_load_lds_dwordx4 v[214:215], off
	s_waitcnt lgkmcnt(8)
	s_barrier
	s_waitcnt lgkmcnt(0)
	s_waitcnt lgkmcnt(0)
	v_mfma_f32_16x16x32_bf16 v[124:127], v[174:177], v[190:193], v[124:127]
	v_mfma_f32_16x16x32_bf16 v[120:123], v[182:185], v[190:193], v[120:123]
	v_mfma_f32_16x16x32_bf16 v[116:119], v[174:177], v[198:201], v[116:119]
	v_mfma_f32_16x16x32_bf16 v[112:115], v[182:185], v[198:201], v[112:115]
	v_mfma_f32_16x16x32_bf16 v[108:111], v[174:177], v[218:221], v[108:111]
	v_mfma_f32_16x16x32_bf16 v[104:107], v[182:185], v[218:221], v[104:107]
	v_mfma_f32_16x16x32_bf16 v[100:103], v[174:177], v[226:229], v[100:103]
	v_mfma_f32_16x16x32_bf16 v[96:99], v[182:185], v[226:229], v[96:99]
	v_mfma_f32_16x16x32_bf16 v[124:127], v[178:181], v[194:197], v[124:127]
	v_mfma_f32_16x16x32_bf16 v[120:123], v[186:189], v[194:197], v[120:123]
	v_mfma_f32_16x16x32_bf16 v[116:119], v[178:181], v[202:205], v[116:119]
	v_mfma_f32_16x16x32_bf16 v[112:115], v[186:189], v[202:205], v[112:115]
	v_mfma_f32_16x16x32_bf16 v[108:111], v[178:181], v[222:225], v[108:111]
	v_mfma_f32_16x16x32_bf16 v[104:107], v[186:189], v[222:225], v[104:107]
	v_mfma_f32_16x16x32_bf16 v[100:103], v[178:181], v[230:233], v[100:103]
	v_mfma_f32_16x16x32_bf16 v[96:99], v[186:189], v[230:233], v[96:99]
	s_barrier
	ds_read_b128 v[234:237], v163
	ds_read_b128 v[238:241], v163 offset:1024
	ds_read_b128 v[242:245], v163 offset:2048
	ds_read_b128 v[246:249], v163 offset:3072
	v_readfirstlane_b32 s18, v165
	v_add_u32_e32 v134, 0x2000, v165
	v_lshl_add_u64 v[214:215], v[208:209], 0, s[56:57]
	s_mov_b32 m0, s18
	v_readfirstlane_b32 s18, v134
	global_load_lds_dwordx4 v[214:215], off
	s_mov_b32 m0, s18
	v_lshl_add_u64 v[214:215], v[210:211], 0, s[56:57]
	global_load_lds_dwordx4 v[214:215], off
	s_barrier
	s_waitcnt lgkmcnt(0)
	s_waitcnt lgkmcnt(0)
	v_mfma_f32_16x16x32_bf16 v[92:95], v[234:237], v[190:193], v[92:95]
	v_mfma_f32_16x16x32_bf16 v[88:91], v[242:245], v[190:193], v[88:91]
	v_mfma_f32_16x16x32_bf16 v[84:87], v[234:237], v[198:201], v[84:87]
	v_mfma_f32_16x16x32_bf16 v[80:83], v[242:245], v[198:201], v[80:83]
	v_mfma_f32_16x16x32_bf16 v[76:79], v[234:237], v[218:221], v[76:79]
	v_mfma_f32_16x16x32_bf16 v[72:75], v[242:245], v[218:221], v[72:75]
	v_mfma_f32_16x16x32_bf16 v[68:71], v[234:237], v[226:229], v[68:71]
	v_mfma_f32_16x16x32_bf16 v[64:67], v[242:245], v[226:229], v[64:67]
	v_mfma_f32_16x16x32_bf16 v[92:95], v[238:241], v[194:197], v[92:95]
	v_mfma_f32_16x16x32_bf16 v[88:91], v[246:249], v[194:197], v[88:91]
	v_mfma_f32_16x16x32_bf16 v[84:87], v[238:241], v[202:205], v[84:87]
	v_mfma_f32_16x16x32_bf16 v[80:83], v[246:249], v[202:205], v[80:83]
	v_mfma_f32_16x16x32_bf16 v[76:79], v[238:241], v[222:225], v[76:79]
	v_mfma_f32_16x16x32_bf16 v[72:75], v[246:249], v[222:225], v[72:75]
	v_mfma_f32_16x16x32_bf16 v[68:71], v[238:241], v[230:233], v[68:71]
	v_mfma_f32_16x16x32_bf16 v[64:67], v[246:249], v[230:233], v[64:67]
	v_readfirstlane_b32 s18, v166
	v_lshl_add_u64 v[136:137], v[136:137], 0, s[16:17]
	s_mov_b32 m0, s18
	v_readfirstlane_b32 s18, v167
	s_barrier
	ds_read_b128 v[190:193], v162 offset:49152
	ds_read_b128 v[194:197], v162 offset:50176
	ds_read_b128 v[198:201], v161 offset:49152
	ds_read_b128 v[202:205], v161 offset:50176
	ds_read_b128 v[218:221], v160 offset:49152
	ds_read_b128 v[222:225], v160 offset:50176
	ds_read_b128 v[226:229], v159 offset:49152
	ds_read_b128 v[230:233], v159 offset:50176
	global_load_lds_dwordx4 v[136:137], off
	s_mov_b32 m0, s18
	v_lshl_add_u64 v[136:137], v[138:139], 0, s[16:17]
	global_load_lds_dwordx4 v[136:137], off
	s_barrier
; #define STAGE(P, BASE, br, kt) STAGET(tid_, P, BASE, br, kt)
; #define LDA(dst, b, h) UFOR(m, 4) UFOR(k, 2) \
;     dst[m][k] = *reinterpret_cast<const bf16x8*>((char*)SA(b, h) + lds_byte(wr * 64 + m * 16 + fr, k * 32 + fq * 8))
; #define LDB(dst, b, h) UFOR(n, 2) UFOR(k, 2) \
;     dst[n][k] = *reinterpret_cast<const bf16x8*>((char*)SB(b, h) + lds_byte(wc * 32 + n * 16 + fr, k * 32 + fq * 8))
; #define MMA(ai, bj, At, Bq) do { __builtin_amdgcn_s_setprio(1); \
;     UFOR(m, 4) UFOR(n, 2) UFOR(k, 2) \
;       acc[ai][bj][m][n] = __builtin_amdgcn_mfma_f32_16x16x32_bf16(Bq[n][k], At[m][k], acc[ai][bj][m][n], 0, 0, 0); \
;     __builtin_amdgcn_s_setprio(0); } while (0)
; #define WAIT_V(n) asm volatile("s_waitcnt vmcnt(" #n ")" ::: "memory")
; #define WAIT_L(n) asm volatile("s_waitcnt lgkmcnt(" #n ")" ::: "memory")
; #define BAR __builtin_amdgcn_s_barrier()
; #define SCHED __builtin_amdgcn_sched_barrier(0)
; template <int EPI, int K, int KL> ...
;     ...
;     BAR; WAIT_L(0); MMA(1, 0, At, B0); BAR; SCHED;
;     STAGE(SB(1, 1), Bt, bcol + HALF, t + 3);
;     WAIT_V(6); BAR; MMA(1, 1, At, B1); BAR;
;   }
;   { LDB(B0, 0, 0); LDA(At, 0, 0); STAGE(SA(1, 1), A, brow + HALF, nt - 1);
;     BAR; WAIT_L(0); MMA(0, 0, At, B0); BAR;
;     LDB(B1, 0, 1); BAR; WAIT_L(0); MMA(0, 1, At, B1); BAR;
;     LDA(At, 0, 1); WAIT_V(4); BAR; WAIT_L(0); MMA(1, 0, At, B0); MMA(1, 1, At, B1); BAR; }
	s_waitcnt lgkmcnt(0)
	s_waitcnt lgkmcnt(0)
	v_mfma_f32_16x16x32_bf16 v[60:63], v[174:177], v[190:193], v[60:63]
	v_mfma_f32_16x16x32_bf16 v[56:59], v[182:185], v[190:193], v[56:59]
	v_mfma_f32_16x16x32_bf16 v[52:55], v[174:177], v[198:201], v[52:55]
	v_mfma_f32_16x16x32_bf16 v[48:51], v[182:185], v[198:201], v[48:51]
	v_mfma_f32_16x16x32_bf16 v[44:47], v[174:177], v[218:221], v[44:47]
	v_mfma_f32_16x16x32_bf16 v[40:43], v[182:185], v[218:221], v[40:43]
	v_mfma_f32_16x16x32_bf16 v[36:39], v[174:177], v[226:229], v[36:39]
	v_mfma_f32_16x16x32_bf16 v[32:35], v[182:185], v[226:229], v[32:35]
	v_mfma_f32_16x16x32_bf16 v[60:63], v[178:181], v[194:197], v[60:63]
	v_mfma_f32_16x16x32_bf16 v[56:59], v[186:189], v[194:197], v[56:59]
	v_mfma_f32_16x16x32_bf16 v[52:55], v[178:181], v[202:205], v[52:55]
	v_mfma_f32_16x16x32_bf16 v[48:51], v[186:189], v[202:205], v[48:51]
	v_mfma_f32_16x16x32_bf16 v[44:47], v[178:181], v[222:225], v[44:47]
	v_mfma_f32_16x16x32_bf16 v[40:43], v[186:189], v[222:225], v[40:43]
	v_mfma_f32_16x16x32_bf16 v[36:39], v[178:181], v[230:233], v[36:39]
	v_mfma_f32_16x16x32_bf16 v[32:35], v[186:189], v[230:233], v[32:35]
	s_barrier
	v_readfirstlane_b32 s18, v169
	v_add_u32_e32 v134, 0x2000, v169
	v_lshl_add_u64 v[136:137], v[208:209], 0, s[58:59]
	s_mov_b32 m0, s18
	v_readfirstlane_b32 s18, v134
	global_load_lds_dwordx4 v[136:137], off
	s_mov_b32 m0, s18
	v_lshl_add_u64 v[136:137], v[210:211], 0, s[58:59]
	global_load_lds_dwordx4 v[136:137], off
	s_waitcnt vmcnt(6)
	s_barrier
	v_mfma_f32_16x16x32_bf16 v[28:31], v[234:237], v[190:193], v[28:31]
	v_mfma_f32_16x16x32_bf16 v[24:27], v[242:245], v[190:193], v[24:27]
	v_mfma_f32_16x16x32_bf16 v[20:23], v[234:237], v[198:201], v[20:23]
	v_mfma_f32_16x16x32_bf16 v[16:19], v[242:245], v[198:201], v[16:19]
	v_mfma_f32_16x16x32_bf16 v[12:15], v[234:237], v[218:221], v[12:15]
	v_mfma_f32_16x16x32_bf16 v[8:11], v[242:245], v[218:221], v[8:11]
	v_mfma_f32_16x16x32_bf16 v[4:7], v[234:237], v[226:229], v[4:7]
	v_mfma_f32_16x16x32_bf16 v[0:3], v[242:245], v[226:229], v[0:3]
	v_mfma_f32_16x16x32_bf16 v[28:31], v[238:241], v[194:197], v[28:31]
	v_mfma_f32_16x16x32_bf16 v[24:27], v[246:249], v[194:197], v[24:27]
	v_mfma_f32_16x16x32_bf16 v[20:23], v[238:241], v[202:205], v[20:23]
	v_mfma_f32_16x16x32_bf16 v[16:19], v[246:249], v[202:205], v[16:19]
	v_mfma_f32_16x16x32_bf16 v[12:15], v[238:241], v[222:225], v[12:15]
	v_mfma_f32_16x16x32_bf16 v[8:11], v[246:249], v[222:225], v[8:11]
	v_mfma_f32_16x16x32_bf16 v[4:7], v[238:241], v[230:233], v[4:7]
	v_mfma_f32_16x16x32_bf16 v[0:3], v[246:249], v[230:233], v[0:3]
	s_add_i32 s15, s15, 2
	v_lshl_add_u64 v[146:147], v[146:147], 0, s[20:21]
	v_lshl_add_u64 v[148:149], v[148:149], 0, s[20:21]
	v_lshl_add_u64 v[150:151], v[150:151], 0, s[20:21]
	s_cmp_lt_u32 s15, 28
	v_lshl_add_u64 v[152:153], v[152:153], 0, s[20:21]
	s_cbranch_scc1 .Lkrot_236
	s_barrier
	s_add_u32 s18, s50, 0x80f80
	s_addc_u32 s19, s51, 0
	v_lshl_add_u64 v[136:137], s[18:19], 0, v[140:141]
	v_readfirstlane_b32 s15, v171
	v_lshl_add_u64 v[130:131], v[130:131], 1, v[136:137]
	s_mov_b32 m0, s15
	ds_read_b128 v[146:149], v170
	ds_read_b128 v[150:153], v170 offset:1024
	ds_read_b128 v[174:177], v170 offset:2048
	ds_read_b128 v[178:181], v170 offset:3072
	ds_read_b128 v[182:185], v162
	ds_read_b128 v[186:189], v162 offset:1024
	ds_read_b128 v[190:193], v161
	ds_read_b128 v[194:197], v161 offset:1024
	ds_read_b128 v[198:201], v160
	ds_read_b128 v[202:205], v160 offset:1024
	ds_read_b128 v[218:221], v159
	ds_read_b128 v[222:225], v159 offset:1024
	global_load_lds_dwordx4 v[130:131], off
	v_lshl_add_u64 v[130:131], s[18:19], 0, v[144:145]
	v_readfirstlane_b32 s15, v172
	v_lshl_add_u64 v[130:131], v[142:143], 1, v[130:131]
	s_mov_b32 m0, s15
	s_nop 0
	global_load_lds_dwordx4 v[130:131], off
	s_barrier
	s_waitcnt lgkmcnt(0)
	s_waitcnt lgkmcnt(0)
	v_mfma_f32_16x16x32_bf16 v[124:127], v[146:149], v[182:185], v[124:127]
	v_mfma_f32_16x16x32_bf16 v[120:123], v[174:177], v[182:185], v[120:123]
	v_mfma_f32_16x16x32_bf16 v[116:119], v[146:149], v[190:193], v[116:119]
	v_mfma_f32_16x16x32_bf16 v[112:115], v[174:177], v[190:193], v[112:115]
	v_mfma_f32_16x16x32_bf16 v[108:111], v[146:149], v[198:201], v[108:111]
	v_mfma_f32_16x16x32_bf16 v[104:107], v[174:177], v[198:201], v[104:107]
	v_mfma_f32_16x16x32_bf16 v[100:103], v[146:149], v[218:221], v[100:103]
	v_mfma_f32_16x16x32_bf16 v[96:99], v[174:177], v[218:221], v[96:99]
	v_mfma_f32_16x16x32_bf16 v[124:127], v[150:153], v[186:189], v[124:127]
	v_mfma_f32_16x16x32_bf16 v[120:123], v[178:181], v[186:189], v[120:123]
	v_mfma_f32_16x16x32_bf16 v[116:119], v[150:153], v[194:197], v[116:119]
	v_mfma_f32_16x16x32_bf16 v[112:115], v[178:181], v[194:197], v[112:115]
	v_mfma_f32_16x16x32_bf16 v[108:111], v[150:153], v[202:205], v[108:111]
	v_mfma_f32_16x16x32_bf16 v[104:107], v[178:181], v[202:205], v[104:107]
	v_mfma_f32_16x16x32_bf16 v[100:103], v[150:153], v[222:225], v[100:103]
	v_mfma_f32_16x16x32_bf16 v[96:99], v[178:181], v[222:225], v[96:99]
	s_barrier
	ds_read_b128 v[140:143], v168
	ds_read_b128 v[170:173], v168 offset:1024
	ds_read_b128 v[226:229], v168 offset:2048
	ds_read_b128 v[166:169], v168 offset:3072
	s_barrier
; #define LDA(dst, b, h) UFOR(m, 4) UFOR(k, 2) \
;     dst[m][k] = *reinterpret_cast<const bf16x8*>((char*)SA(b, h) + lds_byte(wr * 64 + m * 16 + fr, k * 32 + fq * 8))
; #define LDB(dst, b, h) UFOR(n, 2) UFOR(k, 2) \
;     dst[n][k] = *reinterpret_cast<const bf16x8*>((char*)SB(b, h) + lds_byte(wc * 32 + n * 16 + fr, k * 32 + fq * 8))
; #define MMA(ai, bj, At, Bq) do { __builtin_amdgcn_s_setprio(1); \
;     UFOR(m, 4) UFOR(n, 2) UFOR(k, 2) \
;       acc[ai][bj][m][n] = __builtin_amdgcn_mfma_f32_16x16x32_bf16(Bq[n][k], At[m][k], acc[ai][bj][m][n], 0, 0, 0); \
;     __builtin_amdgcn_s_setprio(0); } while (0)
; #define WAIT_V(n) asm volatile("s_waitcnt vmcnt(" #n ")" ::: "memory")
; #define WAIT_L(n) asm volatile("s_waitcnt lgkmcnt(" #n ")" ::: "memory")
; #define BAR __builtin_amdgcn_s_barrier()
; template <int EPI, int K, int KL> ...
;     ...
;     LDB(B1, 0, 1); BAR; WAIT_L(0); MMA(0, 1, At, B1); BAR;
;     LDA(At, 0, 1); WAIT_V(4); BAR; WAIT_L(0); MMA(1, 0, At, B0); MMA(1, 1, At, B1); BAR; }
;   { LDB(B0, 1, 0); LDA(At, 1, 0); WAIT_V(2); BAR; WAIT_L(0); MMA(0, 0, At, B0); BAR;
	s_waitcnt lgkmcnt(0)
	s_waitcnt lgkmcnt(0)
	v_mfma_f32_16x16x32_bf16 v[92:95], v[140:143], v[182:185], v[92:95]
	v_mfma_f32_16x16x32_bf16 v[88:91], v[226:229], v[182:185], v[88:91]
	v_mfma_f32_16x16x32_bf16 v[84:87], v[140:143], v[190:193], v[84:87]
	v_mfma_f32_16x16x32_bf16 v[80:83], v[226:229], v[190:193], v[80:83]
	v_mfma_f32_16x16x32_bf16 v[76:79], v[140:143], v[198:201], v[76:79]
	v_mfma_f32_16x16x32_bf16 v[72:75], v[226:229], v[198:201], v[72:75]
	v_mfma_f32_16x16x32_bf16 v[68:71], v[140:143], v[218:221], v[68:71]
	v_mfma_f32_16x16x32_bf16 v[64:67], v[226:229], v[218:221], v[64:67]
	v_mfma_f32_16x16x32_bf16 v[92:95], v[170:173], v[186:189], v[92:95]
	v_mfma_f32_16x16x32_bf16 v[88:91], v[166:169], v[186:189], v[88:91]
	v_mfma_f32_16x16x32_bf16 v[84:87], v[170:173], v[194:197], v[84:87]
	v_mfma_f32_16x16x32_bf16 v[80:83], v[166:169], v[194:197], v[80:83]
	v_mfma_f32_16x16x32_bf16 v[76:79], v[170:173], v[202:205], v[76:79]
	v_mfma_f32_16x16x32_bf16 v[72:75], v[166:169], v[202:205], v[72:75]
	v_mfma_f32_16x16x32_bf16 v[68:71], v[170:173], v[222:225], v[68:71]
	v_mfma_f32_16x16x32_bf16 v[64:67], v[166:169], v[222:225], v[64:67]
	s_barrier
	ds_read_b128 v[182:185], v162 offset:16384
	ds_read_b128 v[186:189], v162 offset:17408
	ds_read_b128 v[190:193], v161 offset:16384
	ds_read_b128 v[194:197], v161 offset:17408
	ds_read_b128 v[198:201], v160 offset:16384
	ds_read_b128 v[202:205], v160 offset:17408
	ds_read_b128 v[218:221], v159 offset:16384
	ds_read_b128 v[222:225], v159 offset:17408
	s_waitcnt vmcnt(4)
	s_barrier
	s_waitcnt lgkmcnt(0)
	s_waitcnt lgkmcnt(0)
	v_mfma_f32_16x16x32_bf16 v[60:63], v[146:149], v[182:185], v[60:63]
	v_mfma_f32_16x16x32_bf16 v[56:59], v[174:177], v[182:185], v[56:59]
	v_mfma_f32_16x16x32_bf16 v[52:55], v[146:149], v[190:193], v[52:55]
	v_mfma_f32_16x16x32_bf16 v[48:51], v[174:177], v[190:193], v[48:51]
	v_mfma_f32_16x16x32_bf16 v[44:47], v[146:149], v[198:201], v[44:47]
	v_mfma_f32_16x16x32_bf16 v[40:43], v[174:177], v[198:201], v[40:43]
	v_mfma_f32_16x16x32_bf16 v[36:39], v[146:149], v[218:221], v[36:39]
	v_mfma_f32_16x16x32_bf16 v[32:35], v[174:177], v[218:221], v[32:35]
	v_mfma_f32_16x16x32_bf16 v[60:63], v[150:153], v[186:189], v[60:63]
	v_mfma_f32_16x16x32_bf16 v[56:59], v[178:181], v[186:189], v[56:59]
	v_mfma_f32_16x16x32_bf16 v[52:55], v[150:153], v[194:197], v[52:55]
	v_mfma_f32_16x16x32_bf16 v[48:51], v[178:181], v[194:197], v[48:51]
	v_mfma_f32_16x16x32_bf16 v[44:47], v[150:153], v[202:205], v[44:47]
	v_mfma_f32_16x16x32_bf16 v[40:43], v[178:181], v[202:205], v[40:43]
	v_mfma_f32_16x16x32_bf16 v[36:39], v[150:153], v[222:225], v[36:39]
	v_mfma_f32_16x16x32_bf16 v[32:35], v[178:181], v[222:225], v[32:35]
	v_mfma_f32_16x16x32_bf16 v[28:31], v[140:143], v[182:185], v[28:31]
	v_mfma_f32_16x16x32_bf16 v[24:27], v[226:229], v[182:185], v[24:27]
	v_mfma_f32_16x16x32_bf16 v[20:23], v[140:143], v[190:193], v[20:23]
	v_mfma_f32_16x16x32_bf16 v[16:19], v[226:229], v[190:193], v[16:19]
	v_mfma_f32_16x16x32_bf16 v[12:15], v[140:143], v[198:201], v[12:15]
	v_mfma_f32_16x16x32_bf16 v[8:11], v[226:229], v[198:201], v[8:11]
	v_mfma_f32_16x16x32_bf16 v[4:7], v[140:143], v[218:221], v[4:7]
	v_mfma_f32_16x16x32_bf16 v[0:3], v[226:229], v[218:221], v[0:3]
	v_mfma_f32_16x16x32_bf16 v[28:31], v[170:173], v[186:189], v[28:31]
	v_mfma_f32_16x16x32_bf16 v[24:27], v[166:169], v[186:189], v[24:27]
	v_mfma_f32_16x16x32_bf16 v[20:23], v[170:173], v[194:197], v[20:23]
	v_mfma_f32_16x16x32_bf16 v[16:19], v[166:169], v[194:197], v[16:19]
	v_mfma_f32_16x16x32_bf16 v[12:15], v[170:173], v[202:205], v[12:15]
	v_mfma_f32_16x16x32_bf16 v[8:11], v[166:169], v[202:205], v[8:11]
	v_mfma_f32_16x16x32_bf16 v[4:7], v[170:173], v[222:225], v[4:7]
	v_mfma_f32_16x16x32_bf16 v[0:3], v[166:169], v[222:225], v[0:3]
	s_barrier
	ds_read_b128 v[140:143], v164
	ds_read_b128 v[144:147], v164 offset:1024
	ds_read_b128 v[148:151], v164 offset:2048
	ds_read_b128 v[164:167], v164 offset:3072
	ds_read_b128 v[168:171], v162 offset:32768
	ds_read_b128 v[172:175], v162 offset:33792
	ds_read_b128 v[176:179], v161 offset:32768
	ds_read_b128 v[180:183], v161 offset:33792
	ds_read_b128 v[184:187], v160 offset:32768
	ds_read_b128 v[188:191], v160 offset:33792
	ds_read_b128 v[192:195], v159 offset:32768
	ds_read_b128 v[196:199], v159 offset:33792
	s_waitcnt vmcnt(2)
	s_barrier
; #define LDA(dst, b, h) UFOR(m, 4) UFOR(k, 2) \
;     dst[m][k] = *reinterpret_cast<const bf16x8*>((char*)SA(b, h) + lds_byte(wr * 64 + m * 16 + fr, k * 32 + fq * 8))
; #define LDB(dst, b, h) UFOR(n, 2) UFOR(k, 2) \
;     dst[n][k] = *reinterpret_cast<const bf16x8*>((char*)SB(b, h) + lds_byte(wc * 32 + n * 16 + fr, k * 32 + fq * 8))
; #define MMA(ai, bj, At, Bq) do { __builtin_amdgcn_s_setprio(1); \
;     UFOR(m, 4) UFOR(n, 2) UFOR(k, 2) \
;       acc[ai][bj][m][n] = __builtin_amdgcn_mfma_f32_16x16x32_bf16(Bq[n][k], At[m][k], acc[ai][bj][m][n], 0, 0, 0); \
;     __builtin_amdgcn_s_setprio(0); } while (0)
; #define WAIT_V(n) asm volatile("s_waitcnt vmcnt(" #n ")" ::: "memory")
; #define WAIT_L(n) asm volatile("s_waitcnt lgkmcnt(" #n ")" ::: "memory")
; #define BAR __builtin_amdgcn_s_barrier()
; template <int EPI, int K, int KL> ...
;     ...
;   { LDB(B0, 1, 0); LDA(At, 1, 0); WAIT_V(2); BAR; WAIT_L(0); MMA(0, 0, At, B0); BAR;
;     LDB(B1, 1, 1); WAIT_V(0); BAR; WAIT_L(0); MMA(0, 1, At, B1); BAR;
;     LDA(At, 1, 1); BAR; WAIT_L(0); MMA(1, 0, At, B0); MMA(1, 1, At, B1); BAR; }
;   if (wr == 0) BAR;
	s_waitcnt lgkmcnt(0)
	s_waitcnt lgkmcnt(0)
	v_mfma_f32_16x16x32_bf16 v[124:127], v[140:143], v[168:171], v[124:127]
	v_mfma_f32_16x16x32_bf16 v[120:123], v[148:151], v[168:171], v[120:123]
	v_mfma_f32_16x16x32_bf16 v[116:119], v[140:143], v[176:179], v[116:119]
	v_mfma_f32_16x16x32_bf16 v[112:115], v[148:151], v[176:179], v[112:115]
	v_mfma_f32_16x16x32_bf16 v[108:111], v[140:143], v[184:187], v[108:111]
	v_mfma_f32_16x16x32_bf16 v[104:107], v[148:151], v[184:187], v[104:107]
	v_mfma_f32_16x16x32_bf16 v[100:103], v[140:143], v[192:195], v[100:103]
	v_mfma_f32_16x16x32_bf16 v[96:99], v[148:151], v[192:195], v[96:99]
	v_mfma_f32_16x16x32_bf16 v[124:127], v[144:147], v[172:175], v[124:127]
	v_mfma_f32_16x16x32_bf16 v[120:123], v[164:167], v[172:175], v[120:123]
	v_mfma_f32_16x16x32_bf16 v[116:119], v[144:147], v[180:183], v[116:119]
	v_mfma_f32_16x16x32_bf16 v[112:115], v[164:167], v[180:183], v[112:115]
	v_mfma_f32_16x16x32_bf16 v[108:111], v[144:147], v[188:191], v[108:111]
	v_mfma_f32_16x16x32_bf16 v[104:107], v[164:167], v[188:191], v[104:107]
	v_mfma_f32_16x16x32_bf16 v[100:103], v[144:147], v[196:199], v[100:103]
	v_mfma_f32_16x16x32_bf16 v[96:99], v[164:167], v[196:199], v[96:99]
	s_barrier
	ds_read_b128 v[200:203], v163
	ds_read_b128 v[218:221], v163 offset:1024
	ds_read_b128 v[222:225], v163 offset:2048
	ds_read_b128 v[226:229], v163 offset:3072
	s_waitcnt vmcnt(0)
	s_barrier
	s_waitcnt lgkmcnt(0)
	s_waitcnt lgkmcnt(0)
	v_mfma_f32_16x16x32_bf16 v[92:95], v[200:203], v[168:171], v[92:95]
	v_mfma_f32_16x16x32_bf16 v[88:91], v[222:225], v[168:171], v[88:91]
	v_mfma_f32_16x16x32_bf16 v[84:87], v[200:203], v[176:179], v[84:87]
	v_mfma_f32_16x16x32_bf16 v[80:83], v[222:225], v[176:179], v[80:83]
	v_mfma_f32_16x16x32_bf16 v[76:79], v[200:203], v[184:187], v[76:79]
	v_mfma_f32_16x16x32_bf16 v[72:75], v[222:225], v[184:187], v[72:75]
	v_mfma_f32_16x16x32_bf16 v[68:71], v[200:203], v[192:195], v[68:71]
	v_mfma_f32_16x16x32_bf16 v[64:67], v[222:225], v[192:195], v[64:67]
	v_mfma_f32_16x16x32_bf16 v[92:95], v[218:221], v[172:175], v[92:95]
	v_mfma_f32_16x16x32_bf16 v[88:91], v[226:229], v[172:175], v[88:91]
	v_mfma_f32_16x16x32_bf16 v[84:87], v[218:221], v[180:183], v[84:87]
	v_mfma_f32_16x16x32_bf16 v[80:83], v[226:229], v[180:183], v[80:83]
	v_mfma_f32_16x16x32_bf16 v[76:79], v[218:221], v[188:191], v[76:79]
	v_mfma_f32_16x16x32_bf16 v[72:75], v[226:229], v[188:191], v[72:75]
	v_mfma_f32_16x16x32_bf16 v[68:71], v[218:221], v[196:199], v[68:71]
	v_mfma_f32_16x16x32_bf16 v[64:67], v[226:229], v[196:199], v[64:67]
	s_barrier
	ds_read_b128 v[168:171], v162 offset:49152
	ds_read_b128 v[172:175], v162 offset:50176
	ds_read_b128 v[176:179], v161 offset:49152
	ds_read_b128 v[180:183], v161 offset:50176
	ds_read_b128 v[184:187], v160 offset:49152
	ds_read_b128 v[160:163], v160 offset:50176
	ds_read_b128 v[188:191], v159 offset:49152
	ds_read_b128 v[156:159], v159 offset:50176
	s_barrier
	s_waitcnt lgkmcnt(0)
	s_waitcnt lgkmcnt(0)
	v_mfma_f32_16x16x32_bf16 v[60:63], v[140:143], v[168:171], v[60:63]
	v_mfma_f32_16x16x32_bf16 v[56:59], v[148:151], v[168:171], v[56:59]
	v_mfma_f32_16x16x32_bf16 v[52:55], v[140:143], v[176:179], v[52:55]
	v_mfma_f32_16x16x32_bf16 v[48:51], v[148:151], v[176:179], v[48:51]
	v_mfma_f32_16x16x32_bf16 v[44:47], v[140:143], v[184:187], v[44:47]
	v_mfma_f32_16x16x32_bf16 v[40:43], v[148:151], v[184:187], v[40:43]
	v_mfma_f32_16x16x32_bf16 v[36:39], v[140:143], v[188:191], v[36:39]
	v_mfma_f32_16x16x32_bf16 v[32:35], v[148:151], v[188:191], v[32:35]
	v_mfma_f32_16x16x32_bf16 v[60:63], v[144:147], v[172:175], v[60:63]
	v_mfma_f32_16x16x32_bf16 v[56:59], v[164:167], v[172:175], v[56:59]
	v_mfma_f32_16x16x32_bf16 v[52:55], v[144:147], v[180:183], v[52:55]
	v_mfma_f32_16x16x32_bf16 v[48:51], v[164:167], v[180:183], v[48:51]
	v_mfma_f32_16x16x32_bf16 v[44:47], v[144:147], v[160:163], v[44:47]
	v_mfma_f32_16x16x32_bf16 v[40:43], v[164:167], v[160:163], v[40:43]
	v_mfma_f32_16x16x32_bf16 v[36:39], v[144:147], v[156:159], v[36:39]
	v_mfma_f32_16x16x32_bf16 v[32:35], v[164:167], v[156:159], v[32:35]
	v_mfma_f32_16x16x32_bf16 v[28:31], v[200:203], v[168:171], v[28:31]
	v_mfma_f32_16x16x32_bf16 v[24:27], v[222:225], v[168:171], v[24:27]
	v_mfma_f32_16x16x32_bf16 v[20:23], v[200:203], v[176:179], v[20:23]
	v_mfma_f32_16x16x32_bf16 v[16:19], v[222:225], v[176:179], v[16:19]
	v_mfma_f32_16x16x32_bf16 v[12:15], v[200:203], v[184:187], v[12:15]
	v_mfma_f32_16x16x32_bf16 v[8:11], v[222:225], v[184:187], v[8:11]
	v_mfma_f32_16x16x32_bf16 v[4:7], v[200:203], v[188:191], v[4:7]
	v_mfma_f32_16x16x32_bf16 v[0:3], v[222:225], v[188:191], v[0:3]
	v_mfma_f32_16x16x32_bf16 v[28:31], v[218:221], v[172:175], v[28:31]
	v_mfma_f32_16x16x32_bf16 v[24:27], v[226:229], v[172:175], v[24:27]
	v_mfma_f32_16x16x32_bf16 v[20:23], v[218:221], v[180:183], v[20:23]
	v_mfma_f32_16x16x32_bf16 v[16:19], v[226:229], v[180:183], v[16:19]
	v_mfma_f32_16x16x32_bf16 v[12:15], v[218:221], v[160:163], v[12:15]
	v_mfma_f32_16x16x32_bf16 v[8:11], v[226:229], v[160:163], v[8:11]
	v_mfma_f32_16x16x32_bf16 v[4:7], v[218:221], v[156:159], v[4:7]
	v_mfma_f32_16x16x32_bf16 v[0:3], v[226:229], v[156:159], v[0:3]
	s_movk_i32 s15, 0x100
	v_cmp_gt_u32_e32 vcc, s15, v129
	s_barrier
	s_and_saveexec_b64 s[50:51], vcc
	s_cbranch_execz .LBB0_239
	s_barrier

; #define STAGE(P, BASE, br, kt) STAGET(tid_, P, BASE, br, kt)
; #define LDA(dst, b, h) UFOR(m, 4) UFOR(k, 2) \
;     dst[m][k] = *reinterpret_cast<const bf16x8*>((char*)SA(b, h) + lds_byte(wr * 64 + m * 16 + fr, k * 32 + fq * 8))
; #define LDB(dst, b, h) UFOR(n, 2) UFOR(k, 2) \
;     dst[n][k] = *reinterpret_cast<const bf16x8*>((char*)SB(b, h) + lds_byte(wc * 32 + n * 16 + fr, k * 32 + fq * 8))
; #define MMA(ai, bj, At, Bq) do { __builtin_amdgcn_s_setprio(1); \
;     UFOR(m, 4) UFOR(n, 2) UFOR(k, 2) \
;       acc[ai][bj][m][n] = __builtin_amdgcn_mfma_f32_16x16x32_bf16(Bq[n][k], At[m][k], acc[ai][bj][m][n], 0, 0, 0); \
;     __builtin_amdgcn_s_setprio(0); } while (0)
; #define WAIT_L(n) asm volatile("s_waitcnt lgkmcnt(" #n ")" ::: "memory")
; #define BAR __builtin_amdgcn_s_barrier()
; #define SCHED __builtin_amdgcn_sched_barrier(0)
; template <int EPI, int K, int KL> ...
;     ...
;     LDB(B0, 0, 0); SCHED; LDA(At, 0, 0); STAGE(SA(1, 1), A, brow + HALF, t + 1);
;     WAIT_L(8); BAR; WAIT_L(0); MMA(0, 0, At, B0); BAR; SCHED;
;     LDB(B1, 0, 1); STAGE(SB(0, 0), Bt, bcol, t + 2);
;     BAR; WAIT_L(0); MMA(0, 1, At, B1); BAR;
;     LDA(At, 0, 1); STAGE(SA(0, 0), A, brow, t + 2);
;     BAR; WAIT_L(0); MMA(1, 0, At, B0); BAR; SCHED;
.LBB0_940:
	ds_read_b128 v[174:177], v170
	ds_read_b128 v[178:181], v170 offset:1024
	ds_read_b128 v[182:185], v170 offset:2048
	ds_read_b128 v[186:189], v170 offset:3072
	ds_read_b128 v[190:193], v162
	ds_read_b128 v[194:197], v162 offset:1024
	ds_read_b128 v[198:201], v161
	ds_read_b128 v[202:205], v161 offset:1024
	ds_read_b128 v[218:221], v160
	ds_read_b128 v[222:225], v160 offset:1024
	ds_read_b128 v[226:229], v159
	ds_read_b128 v[230:233], v159 offset:1024
	v_add_u32_e32 v171, 0xc000, v157
	v_lshl_add_u64 v[136:137], s[92:93], 0, v[148:149]
	v_readfirstlane_b32 s60, v171
	v_lshl_add_u64 v[138:139], v[136:137], 0, s[88:89]
	s_mov_b32 m0, s60
	v_add_u32_e32 v172, 0xe000, v157
	global_load_lds_dwordx4 v[138:139], off
	v_lshl_add_u64 v[138:139], s[92:93], 0, v[150:151]
	v_readfirstlane_b32 s60, v172
	s_mov_b32 m0, s60
	v_lshl_add_u64 v[208:209], v[138:139], 0, s[88:89]
	global_load_lds_dwordx4 v[208:209], off
	s_waitcnt lgkmcnt(8)
	s_barrier
	s_waitcnt lgkmcnt(0)
	s_waitcnt lgkmcnt(0)
	v_mfma_f32_16x16x32_bf16 v[124:127], v[174:177], v[190:193], v[124:127]
	v_mfma_f32_16x16x32_bf16 v[120:123], v[182:185], v[190:193], v[120:123]
	v_mfma_f32_16x16x32_bf16 v[116:119], v[174:177], v[198:201], v[116:119]
	v_mfma_f32_16x16x32_bf16 v[112:115], v[182:185], v[198:201], v[112:115]
	v_mfma_f32_16x16x32_bf16 v[108:111], v[174:177], v[218:221], v[108:111]
	v_mfma_f32_16x16x32_bf16 v[104:107], v[182:185], v[218:221], v[104:107]
	v_mfma_f32_16x16x32_bf16 v[100:103], v[174:177], v[226:229], v[100:103]
	v_mfma_f32_16x16x32_bf16 v[96:99], v[182:185], v[226:229], v[96:99]
	v_mfma_f32_16x16x32_bf16 v[124:127], v[178:181], v[194:197], v[124:127]
	v_mfma_f32_16x16x32_bf16 v[120:123], v[186:189], v[194:197], v[120:123]
	v_mfma_f32_16x16x32_bf16 v[116:119], v[178:181], v[202:205], v[116:119]
	v_mfma_f32_16x16x32_bf16 v[112:115], v[186:189], v[202:205], v[112:115]
	v_mfma_f32_16x16x32_bf16 v[108:111], v[178:181], v[222:225], v[108:111]
	v_mfma_f32_16x16x32_bf16 v[104:107], v[186:189], v[222:225], v[104:107]
	v_mfma_f32_16x16x32_bf16 v[100:103], v[178:181], v[230:233], v[100:103]
	v_mfma_f32_16x16x32_bf16 v[96:99], v[186:189], v[230:233], v[96:99]
	s_barrier
	ds_read_b128 v[234:237], v168
	ds_read_b128 v[238:241], v168 offset:1024
	ds_read_b128 v[242:245], v168 offset:2048
	ds_read_b128 v[246:249], v168 offset:3072
	v_lshl_add_u64 v[208:209], s[92:93], 0, v[144:145]
	v_readfirstlane_b32 s60, v156
	v_lshl_add_u64 v[210:211], v[208:209], 0, s[62:63]
	s_mov_b32 m0, s60
	v_add_u32_e32 v134, 0x2000, v156
	global_load_lds_dwordx4 v[210:211], off
	v_lshl_add_u64 v[210:211], s[92:93], 0, v[146:147]
	v_readfirstlane_b32 s60, v134
	s_mov_b32 m0, s60
	v_lshl_add_u64 v[214:215], v[210:211], 0, s[62:63]
	global_load_lds_dwordx4 v[214:215], off
	s_barrier
	s_waitcnt lgkmcnt(0)
	s_waitcnt lgkmcnt(0)
	v_mfma_f32_16x16x32_bf16 v[92:95], v[234:237], v[190:193], v[92:95]
	v_mfma_f32_16x16x32_bf16 v[88:91], v[242:245], v[190:193], v[88:91]
	v_mfma_f32_16x16x32_bf16 v[84:87], v[234:237], v[198:201], v[84:87]
	v_mfma_f32_16x16x32_bf16 v[80:83], v[242:245], v[198:201], v[80:83]
	v_mfma_f32_16x16x32_bf16 v[76:79], v[234:237], v[218:221], v[76:79]
	v_mfma_f32_16x16x32_bf16 v[72:75], v[242:245], v[218:221], v[72:75]
	v_mfma_f32_16x16x32_bf16 v[68:71], v[234:237], v[226:229], v[68:71]
	v_mfma_f32_16x16x32_bf16 v[64:67], v[242:245], v[226:229], v[64:67]
	v_mfma_f32_16x16x32_bf16 v[92:95], v[238:241], v[194:197], v[92:95]
	v_mfma_f32_16x16x32_bf16 v[88:91], v[246:249], v[194:197], v[88:91]
	v_mfma_f32_16x16x32_bf16 v[84:87], v[238:241], v[202:205], v[84:87]
	v_mfma_f32_16x16x32_bf16 v[80:83], v[246:249], v[202:205], v[80:83]
	v_mfma_f32_16x16x32_bf16 v[76:79], v[238:241], v[222:225], v[76:79]
	v_mfma_f32_16x16x32_bf16 v[72:75], v[246:249], v[222:225], v[72:75]
	v_mfma_f32_16x16x32_bf16 v[68:71], v[238:241], v[230:233], v[68:71]
	v_mfma_f32_16x16x32_bf16 v[64:67], v[246:249], v[230:233], v[64:67]
	v_readfirstlane_b32 s60, v157
	v_add_u32_e32 v134, 0x2000, v157
	v_lshl_add_u64 v[214:215], v[136:137], 0, s[8:9]
	s_mov_b32 m0, s60
	v_readfirstlane_b32 s60, v134
	s_barrier
	ds_read_b128 v[190:193], v162 offset:16384
	ds_read_b128 v[194:197], v162 offset:17408
	ds_read_b128 v[198:201], v161 offset:16384
	ds_read_b128 v[202:205], v161 offset:17408
	ds_read_b128 v[218:221], v160 offset:16384
	ds_read_b128 v[222:225], v160 offset:17408
	ds_read_b128 v[226:229], v159 offset:16384
	ds_read_b128 v[230:233], v159 offset:17408
	global_load_lds_dwordx4 v[214:215], off
	s_mov_b32 m0, s60
	v_lshl_add_u64 v[214:215], v[138:139], 0, s[8:9]
	global_load_lds_dwordx4 v[214:215], off
	s_barrier
	s_waitcnt lgkmcnt(0)
	s_waitcnt lgkmcnt(0)
	v_mfma_f32_16x16x32_bf16 v[60:63], v[174:177], v[190:193], v[60:63]
	v_mfma_f32_16x16x32_bf16 v[56:59], v[182:185], v[190:193], v[56:59]
	v_mfma_f32_16x16x32_bf16 v[52:55], v[174:177], v[198:201], v[52:55]
	v_mfma_f32_16x16x32_bf16 v[48:51], v[182:185], v[198:201], v[48:51]
	v_mfma_f32_16x16x32_bf16 v[44:47], v[174:177], v[218:221], v[44:47]
	v_mfma_f32_16x16x32_bf16 v[40:43], v[182:185], v[218:221], v[40:43]
	v_mfma_f32_16x16x32_bf16 v[36:39], v[174:177], v[226:229], v[36:39]
	v_mfma_f32_16x16x32_bf16 v[32:35], v[182:185], v[226:229], v[32:35]
	v_mfma_f32_16x16x32_bf16 v[60:63], v[178:181], v[194:197], v[60:63]
	v_mfma_f32_16x16x32_bf16 v[56:59], v[186:189], v[194:197], v[56:59]
	v_mfma_f32_16x16x32_bf16 v[52:55], v[178:181], v[202:205], v[52:55]
	v_mfma_f32_16x16x32_bf16 v[48:51], v[186:189], v[202:205], v[48:51]
	v_mfma_f32_16x16x32_bf16 v[44:47], v[178:181], v[222:225], v[44:47]
	v_mfma_f32_16x16x32_bf16 v[40:43], v[186:189], v[222:225], v[40:43]
	v_mfma_f32_16x16x32_bf16 v[36:39], v[178:181], v[230:233], v[36:39]
	v_mfma_f32_16x16x32_bf16 v[32:35], v[186:189], v[230:233], v[32:35]
	s_barrier
; #define STAGE(P, BASE, br, kt) STAGET(tid_, P, BASE, br, kt)
; #define LDA(dst, b, h) UFOR(m, 4) UFOR(k, 2) \
;     dst[m][k] = *reinterpret_cast<const bf16x8*>((char*)SA(b, h) + lds_byte(wr * 64 + m * 16 + fr, k * 32 + fq * 8))
; #define LDB(dst, b, h) UFOR(n, 2) UFOR(k, 2) \
;     dst[n][k] = *reinterpret_cast<const bf16x8*>((char*)SB(b, h) + lds_byte(wc * 32 + n * 16 + fr, k * 32 + fq * 8))
; #define MMA(ai, bj, At, Bq) do { __builtin_amdgcn_s_setprio(1); \
;     UFOR(m, 4) UFOR(n, 2) UFOR(k, 2) \
;       acc[ai][bj][m][n] = __builtin_amdgcn_mfma_f32_16x16x32_bf16(Bq[n][k], At[m][k], acc[ai][bj][m][n], 0, 0, 0); \
;     __builtin_amdgcn_s_setprio(0); } while (0)
; #define WAIT_V(n) asm volatile("s_waitcnt vmcnt(" #n ")" ::: "memory")
; #define WAIT_L(n) asm volatile("s_waitcnt lgkmcnt(" #n ")" ::: "memory")
; #define BAR __builtin_amdgcn_s_barrier()
; #define SCHED __builtin_amdgcn_sched_barrier(0)
; template <int EPI, int K, int KL> ...
;     ...
;     STAGE(SB(0, 1), Bt, bcol + HALF, t + 2);
;     WAIT_V(6); BAR; MMA(1, 1, At, B1); BAR;
;     LDB(B0, 1, 0); SCHED; LDA(At, 1, 0); STAGE(SA(0, 1), A, brow + HALF, t + 2);
;     WAIT_L(8); BAR; WAIT_L(0); MMA(0, 0, At, B0); BAR; SCHED;
;     LDB(B1, 1, 1); STAGE(SB(1, 0), Bt, bcol, t + 3);
;     BAR; WAIT_L(0); MMA(0, 1, At, B1); BAR;
;     LDA(At, 1, 1); STAGE(SA(1, 0), A, brow, t + 3);
	v_readfirstlane_b32 s60, v158
	v_add_u32_e32 v134, 0x2000, v158
	v_lshl_add_u64 v[174:175], v[208:209], 0, s[66:67]
	s_mov_b32 m0, s60
	v_readfirstlane_b32 s60, v134
	global_load_lds_dwordx4 v[174:175], off
	s_mov_b32 m0, s60
	v_lshl_add_u64 v[174:175], v[210:211], 0, s[66:67]
	global_load_lds_dwordx4 v[174:175], off
	s_waitcnt vmcnt(6)
	s_barrier
	v_mfma_f32_16x16x32_bf16 v[28:31], v[234:237], v[190:193], v[28:31]
	v_mfma_f32_16x16x32_bf16 v[24:27], v[242:245], v[190:193], v[24:27]
	v_mfma_f32_16x16x32_bf16 v[20:23], v[234:237], v[198:201], v[20:23]
	v_mfma_f32_16x16x32_bf16 v[16:19], v[242:245], v[198:201], v[16:19]
	v_mfma_f32_16x16x32_bf16 v[12:15], v[234:237], v[218:221], v[12:15]
	v_mfma_f32_16x16x32_bf16 v[8:11], v[242:245], v[218:221], v[8:11]
	v_mfma_f32_16x16x32_bf16 v[4:7], v[234:237], v[226:229], v[4:7]
	v_mfma_f32_16x16x32_bf16 v[0:3], v[242:245], v[226:229], v[0:3]
	v_mfma_f32_16x16x32_bf16 v[28:31], v[238:241], v[194:197], v[28:31]
	v_mfma_f32_16x16x32_bf16 v[24:27], v[246:249], v[194:197], v[24:27]
	v_mfma_f32_16x16x32_bf16 v[20:23], v[238:241], v[202:205], v[20:23]
	v_mfma_f32_16x16x32_bf16 v[16:19], v[246:249], v[202:205], v[16:19]
	v_mfma_f32_16x16x32_bf16 v[12:15], v[238:241], v[222:225], v[12:15]
	v_mfma_f32_16x16x32_bf16 v[8:11], v[246:249], v[222:225], v[8:11]
	v_mfma_f32_16x16x32_bf16 v[4:7], v[238:241], v[230:233], v[4:7]
	v_mfma_f32_16x16x32_bf16 v[0:3], v[246:249], v[230:233], v[0:3]
	s_barrier
	ds_read_b128 v[174:177], v165
	ds_read_b128 v[178:181], v165 offset:1024
	ds_read_b128 v[182:185], v165 offset:2048
	ds_read_b128 v[186:189], v165 offset:3072
	ds_read_b128 v[190:193], v162 offset:32768
	ds_read_b128 v[194:197], v162 offset:33792
	ds_read_b128 v[198:201], v161 offset:32768
	ds_read_b128 v[202:205], v161 offset:33792
	ds_read_b128 v[218:221], v160 offset:32768
	ds_read_b128 v[222:225], v160 offset:33792
	ds_read_b128 v[226:229], v159 offset:32768
	ds_read_b128 v[230:233], v159 offset:33792
	v_add_u32_e32 v134, 0x4000, v157
	v_lshl_add_u64 v[214:215], v[136:137], 0, s[12:13]
	v_readfirstlane_b32 s60, v134
	v_add_u32_e32 v134, 0x6000, v157
	s_mov_b32 m0, s60
	v_readfirstlane_b32 s60, v134
	global_load_lds_dwordx4 v[214:215], off
	s_mov_b32 m0, s60
	v_lshl_add_u64 v[214:215], v[138:139], 0, s[12:13]
	global_load_lds_dwordx4 v[214:215], off
	s_waitcnt lgkmcnt(8)
	s_barrier
	s_waitcnt lgkmcnt(0)
	s_waitcnt lgkmcnt(0)
	v_mfma_f32_16x16x32_bf16 v[124:127], v[174:177], v[190:193], v[124:127]
	v_mfma_f32_16x16x32_bf16 v[120:123], v[182:185], v[190:193], v[120:123]
	v_mfma_f32_16x16x32_bf16 v[116:119], v[174:177], v[198:201], v[116:119]
	v_mfma_f32_16x16x32_bf16 v[112:115], v[182:185], v[198:201], v[112:115]
	v_mfma_f32_16x16x32_bf16 v[108:111], v[174:177], v[218:221], v[108:111]
	v_mfma_f32_16x16x32_bf16 v[104:107], v[182:185], v[218:221], v[104:107]
	v_mfma_f32_16x16x32_bf16 v[100:103], v[174:177], v[226:229], v[100:103]
	v_mfma_f32_16x16x32_bf16 v[96:99], v[182:185], v[226:229], v[96:99]
	v_mfma_f32_16x16x32_bf16 v[124:127], v[178:181], v[194:197], v[124:127]
	v_mfma_f32_16x16x32_bf16 v[120:123], v[186:189], v[194:197], v[120:123]
	v_mfma_f32_16x16x32_bf16 v[116:119], v[178:181], v[202:205], v[116:119]
	v_mfma_f32_16x16x32_bf16 v[112:115], v[186:189], v[202:205], v[112:115]
	v_mfma_f32_16x16x32_bf16 v[108:111], v[178:181], v[222:225], v[108:111]
	v_mfma_f32_16x16x32_bf16 v[104:107], v[186:189], v[222:225], v[104:107]
	v_mfma_f32_16x16x32_bf16 v[100:103], v[178:181], v[230:233], v[100:103]
	v_mfma_f32_16x16x32_bf16 v[96:99], v[186:189], v[230:233], v[96:99]
	s_barrier
	ds_read_b128 v[234:237], v163
	ds_read_b128 v[238:241], v163 offset:1024
	ds_read_b128 v[242:245], v163 offset:2048
	ds_read_b128 v[246:249], v163 offset:3072
	v_readfirstlane_b32 s60, v164
	v_add_u32_e32 v134, 0x2000, v164
	v_lshl_add_u64 v[214:215], v[208:209], 0, s[70:71]
	s_mov_b32 m0, s60
	v_readfirstlane_b32 s60, v134
	global_load_lds_dwordx4 v[214:215], off
	s_mov_b32 m0, s60
	v_lshl_add_u64 v[214:215], v[210:211], 0, s[70:71]
	global_load_lds_dwordx4 v[214:215], off
	s_barrier
	s_waitcnt lgkmcnt(0)
	s_waitcnt lgkmcnt(0)
	v_mfma_f32_16x16x32_bf16 v[92:95], v[234:237], v[190:193], v[92:95]
	v_mfma_f32_16x16x32_bf16 v[88:91], v[242:245], v[190:193], v[88:91]
	v_mfma_f32_16x16x32_bf16 v[84:87], v[234:237], v[198:201], v[84:87]
	v_mfma_f32_16x16x32_bf16 v[80:83], v[242:245], v[198:201], v[80:83]
	v_mfma_f32_16x16x32_bf16 v[76:79], v[234:237], v[218:221], v[76:79]
	v_mfma_f32_16x16x32_bf16 v[72:75], v[242:245], v[218:221], v[72:75]
	v_mfma_f32_16x16x32_bf16 v[68:71], v[234:237], v[226:229], v[68:71]
	v_mfma_f32_16x16x32_bf16 v[64:67], v[242:245], v[226:229], v[64:67]
	v_mfma_f32_16x16x32_bf16 v[92:95], v[238:241], v[194:197], v[92:95]
	v_mfma_f32_16x16x32_bf16 v[88:91], v[246:249], v[194:197], v[88:91]
	v_mfma_f32_16x16x32_bf16 v[84:87], v[238:241], v[202:205], v[84:87]
	v_mfma_f32_16x16x32_bf16 v[80:83], v[246:249], v[202:205], v[80:83]
	v_mfma_f32_16x16x32_bf16 v[76:79], v[238:241], v[222:225], v[76:79]
	v_mfma_f32_16x16x32_bf16 v[72:75], v[246:249], v[222:225], v[72:75]
	v_mfma_f32_16x16x32_bf16 v[68:71], v[238:241], v[230:233], v[68:71]
	v_mfma_f32_16x16x32_bf16 v[64:67], v[246:249], v[230:233], v[64:67]
	v_readfirstlane_b32 s60, v166
	v_lshl_add_u64 v[136:137], v[136:137], 0, s[16:17]
	s_mov_b32 m0, s60
	v_readfirstlane_b32 s60, v167
	s_barrier
	ds_read_b128 v[190:193], v162 offset:49152
	ds_read_b128 v[194:197], v162 offset:50176
	ds_read_b128 v[198:201], v161 offset:49152
	ds_read_b128 v[202:205], v161 offset:50176
	ds_read_b128 v[218:221], v160 offset:49152
	ds_read_b128 v[222:225], v160 offset:50176
	ds_read_b128 v[226:229], v159 offset:49152
	ds_read_b128 v[230:233], v159 offset:50176
	global_load_lds_dwordx4 v[136:137], off
	s_mov_b32 m0, s60
	v_lshl_add_u64 v[136:137], v[138:139], 0, s[16:17]
	global_load_lds_dwordx4 v[136:137], off
	s_barrier
; #define STAGE(P, BASE, br, kt) STAGET(tid_, P, BASE, br, kt)
; #define LDA(dst, b, h) UFOR(m, 4) UFOR(k, 2) \
;     dst[m][k] = *reinterpret_cast<const bf16x8*>((char*)SA(b, h) + lds_byte(wr * 64 + m * 16 + fr, k * 32 + fq * 8))
; #define LDB(dst, b, h) UFOR(n, 2) UFOR(k, 2) \
;     dst[n][k] = *reinterpret_cast<const bf16x8*>((char*)SB(b, h) + lds_byte(wc * 32 + n * 16 + fr, k * 32 + fq * 8))
; #define MMA(ai, bj, At, Bq) do { __builtin_amdgcn_s_setprio(1); \
;     UFOR(m, 4) UFOR(n, 2) UFOR(k, 2) \
;       acc[ai][bj][m][n] = __builtin_amdgcn_mfma_f32_16x16x32_bf16(Bq[n][k], At[m][k], acc[ai][bj][m][n], 0, 0, 0); \
;     __builtin_amdgcn_s_setprio(0); } while (0)
; #define WAIT_V(n) asm volatile("s_waitcnt vmcnt(" #n ")" ::: "memory")
; #define WAIT_L(n) asm volatile("s_waitcnt lgkmcnt(" #n ")" ::: "memory")
; #define BAR __builtin_amdgcn_s_barrier()
; #define SCHED __builtin_amdgcn_sched_barrier(0)
; template <int EPI, int K, int KL> ...
;     ...
;     BAR; WAIT_L(0); MMA(1, 0, At, B0); BAR; SCHED;
;     STAGE(SB(1, 1), Bt, bcol + HALF, t + 3);
;     WAIT_V(6); BAR; MMA(1, 1, At, B1); BAR;
;   }
;   { LDB(B0, 0, 0); LDA(At, 0, 0); STAGE(SA(1, 1), A, brow + HALF, nt - 1);
;     BAR; WAIT_L(0); MMA(0, 0, At, B0); BAR;
;     LDB(B1, 0, 1); BAR; WAIT_L(0); MMA(0, 1, At, B1); BAR;
;     LDA(At, 0, 1); WAIT_V(4); BAR; WAIT_L(0); MMA(1, 0, At, B0); MMA(1, 1, At, B1); BAR; }
	s_waitcnt lgkmcnt(0)
	s_waitcnt lgkmcnt(0)
	v_mfma_f32_16x16x32_bf16 v[60:63], v[174:177], v[190:193], v[60:63]
	v_mfma_f32_16x16x32_bf16 v[56:59], v[182:185], v[190:193], v[56:59]
	v_mfma_f32_16x16x32_bf16 v[52:55], v[174:177], v[198:201], v[52:55]
	v_mfma_f32_16x16x32_bf16 v[48:51], v[182:185], v[198:201], v[48:51]
	v_mfma_f32_16x16x32_bf16 v[44:47], v[174:177], v[218:221], v[44:47]
	v_mfma_f32_16x16x32_bf16 v[40:43], v[182:185], v[218:221], v[40:43]
	v_mfma_f32_16x16x32_bf16 v[36:39], v[174:177], v[226:229], v[36:39]
	v_mfma_f32_16x16x32_bf16 v[32:35], v[182:185], v[226:229], v[32:35]
	v_mfma_f32_16x16x32_bf16 v[60:63], v[178:181], v[194:197], v[60:63]
	v_mfma_f32_16x16x32_bf16 v[56:59], v[186:189], v[194:197], v[56:59]
	v_mfma_f32_16x16x32_bf16 v[52:55], v[178:181], v[202:205], v[52:55]
	v_mfma_f32_16x16x32_bf16 v[48:51], v[186:189], v[202:205], v[48:51]
	v_mfma_f32_16x16x32_bf16 v[44:47], v[178:181], v[222:225], v[44:47]
	v_mfma_f32_16x16x32_bf16 v[40:43], v[186:189], v[222:225], v[40:43]
	v_mfma_f32_16x16x32_bf16 v[36:39], v[178:181], v[230:233], v[36:39]
	v_mfma_f32_16x16x32_bf16 v[32:35], v[186:189], v[230:233], v[32:35]
	s_barrier
	v_readfirstlane_b32 s60, v169
	v_add_u32_e32 v134, 0x2000, v169
	v_lshl_add_u64 v[136:137], v[208:209], 0, s[74:75]
	s_mov_b32 m0, s60
	v_readfirstlane_b32 s60, v134
	global_load_lds_dwordx4 v[136:137], off
	s_mov_b32 m0, s60
	v_lshl_add_u64 v[136:137], v[210:211], 0, s[74:75]
	global_load_lds_dwordx4 v[136:137], off
	s_waitcnt vmcnt(6)
	s_barrier
	v_mfma_f32_16x16x32_bf16 v[28:31], v[234:237], v[190:193], v[28:31]
	v_mfma_f32_16x16x32_bf16 v[24:27], v[242:245], v[190:193], v[24:27]
	v_mfma_f32_16x16x32_bf16 v[20:23], v[234:237], v[198:201], v[20:23]
	v_mfma_f32_16x16x32_bf16 v[16:19], v[242:245], v[198:201], v[16:19]
	v_mfma_f32_16x16x32_bf16 v[12:15], v[234:237], v[218:221], v[12:15]
	v_mfma_f32_16x16x32_bf16 v[8:11], v[242:245], v[218:221], v[8:11]
	v_mfma_f32_16x16x32_bf16 v[4:7], v[234:237], v[226:229], v[4:7]
	v_mfma_f32_16x16x32_bf16 v[0:3], v[242:245], v[226:229], v[0:3]
	v_mfma_f32_16x16x32_bf16 v[28:31], v[238:241], v[194:197], v[28:31]
	v_mfma_f32_16x16x32_bf16 v[24:27], v[246:249], v[194:197], v[24:27]
	v_mfma_f32_16x16x32_bf16 v[20:23], v[238:241], v[202:205], v[20:23]
	v_mfma_f32_16x16x32_bf16 v[16:19], v[246:249], v[202:205], v[16:19]
	v_mfma_f32_16x16x32_bf16 v[12:15], v[238:241], v[222:225], v[12:15]
	v_mfma_f32_16x16x32_bf16 v[8:11], v[246:249], v[222:225], v[8:11]
	v_mfma_f32_16x16x32_bf16 v[4:7], v[238:241], v[230:233], v[4:7]
	v_mfma_f32_16x16x32_bf16 v[0:3], v[246:249], v[230:233], v[0:3]
	s_add_i32 s55, s55, 2
	v_lshl_add_u64 v[144:145], v[144:145], 0, s[20:21]
	v_lshl_add_u64 v[146:147], v[146:147], 0, s[20:21]
	v_lshl_add_u64 v[148:149], v[148:149], 0, s[20:21]
	s_cmp_lt_u32 s55, 28
	v_lshl_add_u64 v[150:151], v[150:151], 0, s[20:21]
	s_cbranch_scc1 .Lkrot_940
	s_barrier
	s_add_u32 s58, s58, 0x80f80
	s_addc_u32 s59, s59, 0
	v_lshl_add_u64 v[130:131], s[58:59], 0, v[130:131]
	v_readfirstlane_b32 s55, v171
	v_lshl_add_u64 v[128:129], v[128:129], 1, v[130:131]
	s_mov_b32 m0, s55
	ds_read_b128 v[144:147], v170
	ds_read_b128 v[148:151], v170 offset:1024
	ds_read_b128 v[174:177], v170 offset:2048
	ds_read_b128 v[178:181], v170 offset:3072
	ds_read_b128 v[182:185], v162
	ds_read_b128 v[186:189], v162 offset:1024
	ds_read_b128 v[190:193], v161
	ds_read_b128 v[194:197], v161 offset:1024
	ds_read_b128 v[198:201], v160
	ds_read_b128 v[202:205], v160 offset:1024
	ds_read_b128 v[218:221], v159
	ds_read_b128 v[222:225], v159 offset:1024
	global_load_lds_dwordx4 v[128:129], off
	v_lshl_add_u64 v[128:129], s[58:59], 0, v[142:143]
	v_readfirstlane_b32 s55, v172
	v_lshl_add_u64 v[128:129], v[140:141], 1, v[128:129]
	s_mov_b32 m0, s55
	s_nop 0
	global_load_lds_dwordx4 v[128:129], off
	s_barrier
	s_waitcnt lgkmcnt(0)
	s_waitcnt lgkmcnt(0)
	v_mfma_f32_16x16x32_bf16 v[124:127], v[144:147], v[182:185], v[124:127]
	v_mfma_f32_16x16x32_bf16 v[120:123], v[174:177], v[182:185], v[120:123]
	v_mfma_f32_16x16x32_bf16 v[116:119], v[144:147], v[190:193], v[116:119]
	v_mfma_f32_16x16x32_bf16 v[112:115], v[174:177], v[190:193], v[112:115]
	v_mfma_f32_16x16x32_bf16 v[108:111], v[144:147], v[198:201], v[108:111]
	v_mfma_f32_16x16x32_bf16 v[104:107], v[174:177], v[198:201], v[104:107]
	v_mfma_f32_16x16x32_bf16 v[100:103], v[144:147], v[218:221], v[100:103]
	v_mfma_f32_16x16x32_bf16 v[96:99], v[174:177], v[218:221], v[96:99]
	v_mfma_f32_16x16x32_bf16 v[124:127], v[148:151], v[186:189], v[124:127]
	v_mfma_f32_16x16x32_bf16 v[120:123], v[178:181], v[186:189], v[120:123]
	v_mfma_f32_16x16x32_bf16 v[116:119], v[148:151], v[194:197], v[116:119]
	v_mfma_f32_16x16x32_bf16 v[112:115], v[178:181], v[194:197], v[112:115]
	v_mfma_f32_16x16x32_bf16 v[108:111], v[148:151], v[202:205], v[108:111]
	v_mfma_f32_16x16x32_bf16 v[104:107], v[178:181], v[202:205], v[104:107]
	v_mfma_f32_16x16x32_bf16 v[100:103], v[148:151], v[222:225], v[100:103]
	v_mfma_f32_16x16x32_bf16 v[96:99], v[178:181], v[222:225], v[96:99]
	s_barrier
	ds_read_b128 v[128:131], v168
	ds_read_b128 v[140:143], v168 offset:1024
	ds_read_b128 v[170:173], v168 offset:2048
	ds_read_b128 v[166:169], v168 offset:3072
	s_barrier
; #define LDA(dst, b, h) UFOR(m, 4) UFOR(k, 2) \
;     dst[m][k] = *reinterpret_cast<const bf16x8*>((char*)SA(b, h) + lds_byte(wr * 64 + m * 16 + fr, k * 32 + fq * 8))
; #define LDB(dst, b, h) UFOR(n, 2) UFOR(k, 2) \
;     dst[n][k] = *reinterpret_cast<const bf16x8*>((char*)SB(b, h) + lds_byte(wc * 32 + n * 16 + fr, k * 32 + fq * 8))
; #define MMA(ai, bj, At, Bq) do { __builtin_amdgcn_s_setprio(1); \
;     UFOR(m, 4) UFOR(n, 2) UFOR(k, 2) \
;       acc[ai][bj][m][n] = __builtin_amdgcn_mfma_f32_16x16x32_bf16(Bq[n][k], At[m][k], acc[ai][bj][m][n], 0, 0, 0); \
;     __builtin_amdgcn_s_setprio(0); } while (0)
; #define WAIT_V(n) asm volatile("s_waitcnt vmcnt(" #n ")" ::: "memory")
; #define WAIT_L(n) asm volatile("s_waitcnt lgkmcnt(" #n ")" ::: "memory")
; #define BAR __builtin_amdgcn_s_barrier()
; template <int EPI, int K, int KL> ...
;     ...
;     LDB(B1, 0, 1); BAR; WAIT_L(0); MMA(0, 1, At, B1); BAR;
;     LDA(At, 0, 1); WAIT_V(4); BAR; WAIT_L(0); MMA(1, 0, At, B0); MMA(1, 1, At, B1); BAR; }
;   { LDB(B0, 1, 0); LDA(At, 1, 0); WAIT_V(2); BAR; WAIT_L(0); MMA(0, 0, At, B0); BAR;
	s_waitcnt lgkmcnt(0)
	s_waitcnt lgkmcnt(0)
	v_mfma_f32_16x16x32_bf16 v[80:83], v[170:173], v[190:193], v[80:83]
	v_mfma_f32_16x16x32_bf16 v[72:75], v[170:173], v[198:201], v[72:75]
	v_mfma_f32_16x16x32_bf16 v[68:71], v[128:131], v[218:221], v[68:71]
	v_mfma_f32_16x16x32_bf16 v[64:67], v[170:173], v[218:221], v[64:67]
	v_mfma_f32_16x16x32_bf16 v[92:95], v[128:131], v[182:185], v[92:95]
	v_mfma_f32_16x16x32_bf16 v[88:91], v[170:173], v[182:185], v[88:91]
	v_mfma_f32_16x16x32_bf16 v[84:87], v[128:131], v[190:193], v[84:87]
	v_mfma_f32_16x16x32_bf16 v[80:83], v[166:169], v[194:197], v[80:83]
	v_mfma_f32_16x16x32_bf16 v[76:79], v[128:131], v[198:201], v[76:79]
	v_mfma_f32_16x16x32_bf16 v[72:75], v[166:169], v[202:205], v[72:75]
	v_mfma_f32_16x16x32_bf16 v[68:71], v[140:143], v[222:225], v[68:71]
	v_mfma_f32_16x16x32_bf16 v[64:67], v[166:169], v[222:225], v[64:67]
	v_mfma_f32_16x16x32_bf16 v[226:229], v[140:143], v[186:189], v[92:95]
	v_mfma_f32_16x16x32_bf16 v[182:185], v[166:169], v[186:189], v[88:91]
	v_mfma_f32_16x16x32_bf16 v[186:189], v[140:143], v[194:197], v[84:87]
	v_mfma_f32_16x16x32_bf16 v[190:193], v[140:143], v[202:205], v[76:79]
	s_barrier
	s_nop 0
	ds_read_b128 v[76:79], v162 offset:16384
	ds_read_b128 v[84:87], v162 offset:17408
	ds_read_b128 v[88:91], v161 offset:16384
	ds_read_b128 v[92:95], v161 offset:17408
	ds_read_b128 v[194:197], v160 offset:16384
	ds_read_b128 v[198:201], v160 offset:17408
	ds_read_b128 v[202:205], v159 offset:16384
	ds_read_b128 v[218:221], v159 offset:17408
	s_waitcnt vmcnt(4)
	s_barrier
	s_waitcnt lgkmcnt(0)
	s_waitcnt lgkmcnt(0)
	v_mfma_f32_16x16x32_bf16 v[48:51], v[174:177], v[88:91], v[48:51]
	v_mfma_f32_16x16x32_bf16 v[40:43], v[174:177], v[194:197], v[40:43]
	v_mfma_f32_16x16x32_bf16 v[36:39], v[144:147], v[202:205], v[36:39]
	v_mfma_f32_16x16x32_bf16 v[32:35], v[174:177], v[202:205], v[32:35]
	v_mfma_f32_16x16x32_bf16 v[60:63], v[144:147], v[76:79], v[60:63]
	v_mfma_f32_16x16x32_bf16 v[56:59], v[174:177], v[76:79], v[56:59]
	v_mfma_f32_16x16x32_bf16 v[52:55], v[144:147], v[88:91], v[52:55]
	v_mfma_f32_16x16x32_bf16 v[48:51], v[178:181], v[92:95], v[48:51]
	v_mfma_f32_16x16x32_bf16 v[44:47], v[144:147], v[194:197], v[44:47]
	v_mfma_f32_16x16x32_bf16 v[40:43], v[178:181], v[198:201], v[40:43]
	v_mfma_f32_16x16x32_bf16 v[36:39], v[148:151], v[218:221], v[36:39]
	v_mfma_f32_16x16x32_bf16 v[32:35], v[178:181], v[218:221], v[32:35]
	v_mfma_f32_16x16x32_bf16 v[222:225], v[148:151], v[84:87], v[60:63]
	v_mfma_f32_16x16x32_bf16 v[230:233], v[178:181], v[84:87], v[56:59]
	v_mfma_f32_16x16x32_bf16 v[234:237], v[148:151], v[92:95], v[52:55]
	v_mfma_f32_16x16x32_bf16 v[238:241], v[148:151], v[198:201], v[44:47]
	v_mfma_f32_16x16x32_bf16 v[0:3], v[170:173], v[202:205], v[0:3]
	v_mfma_f32_16x16x32_bf16 v[28:31], v[128:131], v[76:79], v[28:31]
	v_mfma_f32_16x16x32_bf16 v[24:27], v[170:173], v[76:79], v[24:27]
	v_mfma_f32_16x16x32_bf16 v[20:23], v[128:131], v[88:91], v[20:23]
	v_mfma_f32_16x16x32_bf16 v[16:19], v[170:173], v[88:91], v[16:19]
	v_mfma_f32_16x16x32_bf16 v[12:15], v[128:131], v[194:197], v[12:15]
	v_mfma_f32_16x16x32_bf16 v[8:11], v[170:173], v[194:197], v[8:11]
	v_mfma_f32_16x16x32_bf16 v[4:7], v[128:131], v[202:205], v[4:7]
	v_mfma_f32_16x16x32_bf16 v[0:3], v[166:169], v[218:221], v[0:3]
	v_mfma_f32_16x16x32_bf16 v[144:147], v[140:143], v[84:87], v[28:31]
	v_mfma_f32_16x16x32_bf16 v[148:151], v[166:169], v[84:87], v[24:27]
	v_mfma_f32_16x16x32_bf16 v[174:177], v[140:143], v[92:95], v[20:23]
	v_mfma_f32_16x16x32_bf16 v[178:181], v[166:169], v[92:95], v[16:19]
	v_mfma_f32_16x16x32_bf16 v[242:245], v[140:143], v[198:201], v[12:15]
	v_mfma_f32_16x16x32_bf16 v[194:197], v[166:169], v[198:201], v[8:11]
	v_mfma_f32_16x16x32_bf16 v[128:131], v[140:143], v[218:221], v[4:7]
	s_barrier
	s_nop 0
	ds_read_b128 v[4:7], v165
	ds_read_b128 v[8:11], v165 offset:1024
	ds_read_b128 v[16:19], v165 offset:2048
	ds_read_b128 v[140:143], v165 offset:3072
	ds_read_b128 v[12:15], v162 offset:32768
	ds_read_b128 v[20:23], v162 offset:33792
	ds_read_b128 v[24:27], v161 offset:32768
	ds_read_b128 v[44:47], v161 offset:33792
	ds_read_b128 v[164:167], v160 offset:32768
	ds_read_b128 v[168:171], v160 offset:33792
	ds_read_b128 v[198:201], v159 offset:32768
	ds_read_b128 v[202:205], v159 offset:33792
	s_waitcnt vmcnt(2)
	s_barrier
; #define LDA(dst, b, h) UFOR(m, 4) UFOR(k, 2) \
;     dst[m][k] = *reinterpret_cast<const bf16x8*>((char*)SA(b, h) + lds_byte(wr * 64 + m * 16 + fr, k * 32 + fq * 8))
; #define LDB(dst, b, h) UFOR(n, 2) UFOR(k, 2) \
;     dst[n][k] = *reinterpret_cast<const bf16x8*>((char*)SB(b, h) + lds_byte(wc * 32 + n * 16 + fr, k * 32 + fq * 8))
; #define MMA(ai, bj, At, Bq) do { __builtin_amdgcn_s_setprio(1); \
;     UFOR(m, 4) UFOR(n, 2) UFOR(k, 2) \
;       acc[ai][bj][m][n] = __builtin_amdgcn_mfma_f32_16x16x32_bf16(Bq[n][k], At[m][k], acc[ai][bj][m][n], 0, 0, 0); \
;     __builtin_amdgcn_s_setprio(0); } while (0)
; #define WAIT_V(n) asm volatile("s_waitcnt vmcnt(" #n ")" ::: "memory")
; #define WAIT_L(n) asm volatile("s_waitcnt lgkmcnt(" #n ")" ::: "memory")
; #define BAR __builtin_amdgcn_s_barrier()
; template <int EPI, int K, int KL> ...
;     ...
;   { LDB(B0, 1, 0); LDA(At, 1, 0); WAIT_V(2); BAR; WAIT_L(0); MMA(0, 0, At, B0); BAR;
;     LDB(B1, 1, 1); WAIT_V(0); BAR; WAIT_L(0); MMA(0, 1, At, B1); BAR;
;     LDA(At, 1, 1); BAR; WAIT_L(0); MMA(1, 0, At, B0); MMA(1, 1, At, B1); BAR; }
;   if (wr == 0) BAR;
	s_waitcnt lgkmcnt(0)
	s_waitcnt lgkmcnt(0)
	v_mfma_f32_16x16x32_bf16 v[28:31], v[4:7], v[12:15], v[124:127]
	v_mfma_f32_16x16x32_bf16 v[124:127], v[8:11], v[20:23], v[28:31]
	v_mfma_f32_16x16x32_bf16 v[28:31], v[16:19], v[12:15], v[120:123]
	v_mfma_f32_16x16x32_bf16 v[92:95], v[140:143], v[20:23], v[28:31]
	v_mfma_f32_16x16x32_bf16 v[28:31], v[4:7], v[24:27], v[116:119]
	v_mfma_f32_16x16x32_bf16 v[120:123], v[8:11], v[44:47], v[28:31]
	v_mfma_f32_16x16x32_bf16 v[28:31], v[16:19], v[24:27], v[112:115]
	v_mfma_f32_16x16x32_bf16 v[88:91], v[140:143], v[44:47], v[28:31]
	v_mfma_f32_16x16x32_bf16 v[28:31], v[4:7], v[164:167], v[108:111]
	v_mfma_f32_16x16x32_bf16 v[116:119], v[8:11], v[168:171], v[28:31]
	v_mfma_f32_16x16x32_bf16 v[28:31], v[16:19], v[164:167], v[104:107]
	v_mfma_f32_16x16x32_bf16 v[84:87], v[140:143], v[168:171], v[28:31]
	v_mfma_f32_16x16x32_bf16 v[28:31], v[4:7], v[198:201], v[100:103]
	v_mfma_f32_16x16x32_bf16 v[108:111], v[8:11], v[202:205], v[28:31]
	v_mfma_f32_16x16x32_bf16 v[28:31], v[16:19], v[198:201], v[96:99]
	v_mfma_f32_16x16x32_bf16 v[76:79], v[140:143], v[202:205], v[28:31]
	s_barrier
	ds_read_b128 v[218:221], v163
	ds_read_b128 v[246:249], v163 offset:1024
	ds_read_b128 v[136:139], v163 offset:2048
	ds_read_b128 v[208:211], v163 offset:3072
	s_waitcnt vmcnt(0)
	s_barrier
	s_waitcnt lgkmcnt(0)
	s_waitcnt lgkmcnt(0)
	v_mfma_f32_16x16x32_bf16 v[28:31], v[218:221], v[12:15], v[226:229]
	v_mfma_f32_16x16x32_bf16 v[12:15], v[136:139], v[12:15], v[182:185]
	v_mfma_f32_16x16x32_bf16 v[60:63], v[246:249], v[20:23], v[28:31]
	v_mfma_f32_16x16x32_bf16 v[28:31], v[208:211], v[20:23], v[12:15]
	v_mfma_f32_16x16x32_bf16 v[12:15], v[218:221], v[24:27], v[186:189]
	v_mfma_f32_16x16x32_bf16 v[56:59], v[246:249], v[44:47], v[12:15]
	v_mfma_f32_16x16x32_bf16 v[12:15], v[136:139], v[24:27], v[80:83]
	v_mfma_f32_16x16x32_bf16 v[24:27], v[208:211], v[44:47], v[12:15]
	v_mfma_f32_16x16x32_bf16 v[12:15], v[218:221], v[164:167], v[190:193]
	v_mfma_f32_16x16x32_bf16 v[52:55], v[246:249], v[168:171], v[12:15]
	v_mfma_f32_16x16x32_bf16 v[12:15], v[136:139], v[164:167], v[72:75]
	v_mfma_f32_16x16x32_bf16 v[20:23], v[208:211], v[168:171], v[12:15]
	v_mfma_f32_16x16x32_bf16 v[12:15], v[218:221], v[198:201], v[68:71]
	v_mfma_f32_16x16x32_bf16 v[44:47], v[246:249], v[202:205], v[12:15]
	v_mfma_f32_16x16x32_bf16 v[12:15], v[136:139], v[198:201], v[64:67]
	v_mfma_f32_16x16x32_bf16 v[12:15], v[208:211], v[202:205], v[12:15]
	s_barrier
	ds_read_b128 v[164:167], v162 offset:49152
	ds_read_b128 v[168:171], v162 offset:50176
	ds_read_b128 v[182:185], v161 offset:49152
	ds_read_b128 v[186:189], v161 offset:50176
	ds_read_b128 v[190:193], v160 offset:49152
	ds_read_b128 v[160:163], v160 offset:50176
	ds_read_b128 v[198:201], v159 offset:49152
	ds_read_b128 v[156:159], v159 offset:50176
	s_barrier
	s_waitcnt lgkmcnt(0)
	s_waitcnt lgkmcnt(0)
	v_mfma_f32_16x16x32_bf16 v[64:67], v[4:7], v[164:167], v[222:225]
	v_mfma_f32_16x16x32_bf16 v[112:115], v[8:11], v[168:171], v[64:67]
	v_mfma_f32_16x16x32_bf16 v[64:67], v[16:19], v[164:167], v[230:233]
	v_mfma_f32_16x16x32_bf16 v[48:51], v[16:19], v[182:185], v[48:51]
	v_mfma_f32_16x16x32_bf16 v[80:83], v[140:143], v[168:171], v[64:67]
	v_mfma_f32_16x16x32_bf16 v[64:67], v[4:7], v[182:185], v[234:237]
	v_mfma_f32_16x16x32_bf16 v[72:75], v[140:143], v[186:189], v[48:51]
	v_mfma_f32_16x16x32_bf16 v[48:51], v[4:7], v[190:193], v[238:241]
	v_mfma_f32_16x16x32_bf16 v[4:7], v[4:7], v[198:201], v[36:39]
	v_mfma_f32_16x16x32_bf16 v[40:43], v[16:19], v[190:193], v[40:43]
	v_mfma_f32_16x16x32_bf16 v[96:99], v[8:11], v[156:159], v[4:7]
	v_mfma_f32_16x16x32_bf16 v[4:7], v[16:19], v[198:201], v[32:35]
	v_mfma_f32_16x16x32_bf16 v[104:107], v[8:11], v[186:189], v[64:67]
	v_mfma_f32_16x16x32_bf16 v[100:103], v[8:11], v[160:163], v[48:51]
	v_mfma_f32_16x16x32_bf16 v[68:71], v[140:143], v[160:163], v[40:43]
	v_mfma_f32_16x16x32_bf16 v[64:67], v[140:143], v[156:159], v[4:7]
	v_mfma_f32_16x16x32_bf16 v[4:7], v[218:221], v[164:167], v[144:147]
	v_mfma_f32_16x16x32_bf16 v[48:51], v[246:249], v[168:171], v[4:7]
	v_mfma_f32_16x16x32_bf16 v[4:7], v[136:139], v[164:167], v[148:151]
	v_mfma_f32_16x16x32_bf16 v[16:19], v[208:211], v[168:171], v[4:7]
	v_mfma_f32_16x16x32_bf16 v[4:7], v[218:221], v[182:185], v[174:177]
	v_mfma_f32_16x16x32_bf16 v[40:43], v[246:249], v[186:189], v[4:7]
	v_mfma_f32_16x16x32_bf16 v[4:7], v[136:139], v[182:185], v[178:181]
	v_mfma_f32_16x16x32_bf16 v[8:11], v[208:211], v[186:189], v[4:7]
	v_mfma_f32_16x16x32_bf16 v[4:7], v[218:221], v[190:193], v[242:245]
	v_mfma_f32_16x16x32_bf16 v[36:39], v[246:249], v[160:163], v[4:7]
	v_mfma_f32_16x16x32_bf16 v[4:7], v[136:139], v[190:193], v[194:197]
	v_mfma_f32_16x16x32_bf16 v[32:35], v[218:221], v[198:201], v[128:131]
	v_mfma_f32_16x16x32_bf16 v[0:3], v[136:139], v[198:201], v[0:3]
	v_mfma_f32_16x16x32_bf16 v[4:7], v[208:211], v[160:163], v[4:7]
	v_mfma_f32_16x16x32_bf16 v[32:35], v[246:249], v[156:159], v[32:35]
	v_mfma_f32_16x16x32_bf16 v[0:3], v[208:211], v[156:159], v[0:3]
	s_movk_i32 s55, 0x100
	v_cmp_gt_u32_e32 vcc, s55, v154
	s_barrier
	s_and_saveexec_b64 s[58:59], vcc
	s_cbranch_execz .LBB0_943
	s_barrier

; #define STAGE(P, BASE, br, kt) STAGET(tid_, P, BASE, br, kt)
; #define LDA(dst, b, h) UFOR(m, 4) UFOR(k, 2) \
;     dst[m][k] = *reinterpret_cast<const bf16x8*>((char*)SA(b, h) + lds_byte(wr * 64 + m * 16 + fr, k * 32 + fq * 8))
; #define LDB(dst, b, h) UFOR(n, 2) UFOR(k, 2) \
;     dst[n][k] = *reinterpret_cast<const bf16x8*>((char*)SB(b, h) + lds_byte(wc * 32 + n * 16 + fr, k * 32 + fq * 8))
; #define MMA(ai, bj, At, Bq) do { __builtin_amdgcn_s_setprio(1); \
;     UFOR(m, 4) UFOR(n, 2) UFOR(k, 2) \
;       acc[ai][bj][m][n] = __builtin_amdgcn_mfma_f32_16x16x32_bf16(Bq[n][k], At[m][k], acc[ai][bj][m][n], 0, 0, 0); \
;     __builtin_amdgcn_s_setprio(0); } while (0)
; #define WAIT_L(n) asm volatile("s_waitcnt lgkmcnt(" #n ")" ::: "memory")
; #define BAR __builtin_amdgcn_s_barrier()
; #define SCHED __builtin_amdgcn_sched_barrier(0)
; template <int EPI, int K, int KL> ...
;     ...
;     LDB(B0, 0, 0); SCHED; LDA(At, 0, 0); STAGE(SA(1, 1), A, brow + HALF, t + 1);
;     WAIT_L(8); BAR; WAIT_L(0); MMA(0, 0, At, B0); BAR; SCHED;
;     LDB(B1, 0, 1); STAGE(SB(0, 0), Bt, bcol, t + 2);
;     BAR; WAIT_L(0); MMA(0, 1, At, B1); BAR;
;     LDA(At, 0, 1); STAGE(SA(0, 0), A, brow, t + 2);
;     BAR; WAIT_L(0); MMA(1, 0, At, B0); BAR; SCHED;
.LBB0_1107:
	ds_read_b128 v[136:139], v171
	ds_read_b128 v[174:177], v171 offset:1024
	ds_read_b128 v[178:181], v171 offset:2048
	ds_read_b128 v[182:185], v171 offset:3072
	ds_read_b128 v[186:189], v163
	ds_read_b128 v[190:193], v163 offset:1024
	ds_read_b128 v[194:197], v162
	ds_read_b128 v[198:201], v162 offset:1024
	ds_read_b128 v[202:205], v161
	ds_read_b128 v[208:211], v161 offset:1024
	ds_read_b128 v[218:221], v160
	ds_read_b128 v[222:225], v160 offset:1024
	v_add_u32_e32 v172, 0xc000, v158
	v_lshl_add_u64 v[214:215], s[92:93], 0, v[148:149]
	v_readfirstlane_b32 s56, v172
	v_lshl_add_u64 v[216:217], v[214:215], 0, s[88:89]
	s_mov_b32 m0, s56
	v_add_u32_e32 v173, 0xe000, v158
	global_load_lds_dwordx4 v[216:217], off
	v_lshl_add_u64 v[216:217], s[92:93], 0, v[150:151]
	v_readfirstlane_b32 s56, v173
	s_mov_b32 m0, s56
	v_lshl_add_u64 v[226:227], v[216:217], 0, s[88:89]
	global_load_lds_dwordx4 v[226:227], off
	s_waitcnt lgkmcnt(8)
	s_barrier
	s_waitcnt lgkmcnt(0)
	s_waitcnt lgkmcnt(0)
	v_mfma_f32_16x16x32_bf16 v[0:3], v[136:139], v[186:189], v[0:3]
	v_mfma_f32_16x16x32_bf16 v[4:7], v[178:181], v[186:189], v[4:7]
	v_mfma_f32_16x16x32_bf16 v[8:11], v[136:139], v[194:197], v[8:11]
	v_mfma_f32_16x16x32_bf16 v[16:19], v[178:181], v[194:197], v[16:19]
	v_mfma_f32_16x16x32_bf16 v[28:31], v[136:139], v[202:205], v[28:31]
	v_mfma_f32_16x16x32_bf16 v[40:43], v[178:181], v[202:205], v[40:43]
	v_mfma_f32_16x16x32_bf16 v[52:55], v[136:139], v[218:221], v[52:55]
	v_mfma_f32_16x16x32_bf16 v[64:67], v[178:181], v[218:221], v[64:67]
	v_mfma_f32_16x16x32_bf16 v[0:3], v[174:177], v[190:193], v[0:3]
	v_mfma_f32_16x16x32_bf16 v[4:7], v[182:185], v[190:193], v[4:7]
	v_mfma_f32_16x16x32_bf16 v[8:11], v[174:177], v[198:201], v[8:11]
	v_mfma_f32_16x16x32_bf16 v[16:19], v[182:185], v[198:201], v[16:19]
	v_mfma_f32_16x16x32_bf16 v[28:31], v[174:177], v[208:211], v[28:31]
	v_mfma_f32_16x16x32_bf16 v[40:43], v[182:185], v[208:211], v[40:43]
	v_mfma_f32_16x16x32_bf16 v[52:55], v[174:177], v[222:225], v[52:55]
	v_mfma_f32_16x16x32_bf16 v[64:67], v[182:185], v[222:225], v[64:67]
	s_barrier
	ds_read_b128 v[226:229], v169
	ds_read_b128 v[230:233], v169 offset:1024
	ds_read_b128 v[234:237], v169 offset:2048
	ds_read_b128 v[238:241], v169 offset:3072
	v_lshl_add_u64 v[242:243], s[92:93], 0, v[144:145]
	v_readfirstlane_b32 s56, v157
	v_lshl_add_u64 v[244:245], v[242:243], 0, s[2:3]
	s_mov_b32 m0, s56
	v_add_u32_e32 v134, 0x2000, v157
	global_load_lds_dwordx4 v[244:245], off
	v_lshl_add_u64 v[244:245], s[92:93], 0, v[146:147]
	v_readfirstlane_b32 s56, v134
	s_mov_b32 m0, s56
	v_lshl_add_u64 v[246:247], v[244:245], 0, s[2:3]
	global_load_lds_dwordx4 v[246:247], off
	s_barrier
	s_waitcnt lgkmcnt(0)
	s_waitcnt lgkmcnt(0)
	v_mfma_f32_16x16x32_bf16 v[12:15], v[226:229], v[186:189], v[12:15]
	v_mfma_f32_16x16x32_bf16 v[24:27], v[234:237], v[186:189], v[24:27]
	v_mfma_f32_16x16x32_bf16 v[36:39], v[226:229], v[194:197], v[36:39]
	v_mfma_f32_16x16x32_bf16 v[48:51], v[234:237], v[194:197], v[48:51]
	v_mfma_f32_16x16x32_bf16 v[60:63], v[226:229], v[202:205], v[60:63]
	v_mfma_f32_16x16x32_bf16 v[72:75], v[234:237], v[202:205], v[72:75]
	v_mfma_f32_16x16x32_bf16 v[80:83], v[226:229], v[218:221], v[80:83]
	v_mfma_f32_16x16x32_bf16 v[88:91], v[234:237], v[218:221], v[88:91]
	v_mfma_f32_16x16x32_bf16 v[12:15], v[230:233], v[190:193], v[12:15]
	v_mfma_f32_16x16x32_bf16 v[24:27], v[238:241], v[190:193], v[24:27]
	v_mfma_f32_16x16x32_bf16 v[36:39], v[230:233], v[198:201], v[36:39]
	v_mfma_f32_16x16x32_bf16 v[48:51], v[238:241], v[198:201], v[48:51]
	v_mfma_f32_16x16x32_bf16 v[60:63], v[230:233], v[208:211], v[60:63]
	v_mfma_f32_16x16x32_bf16 v[72:75], v[238:241], v[208:211], v[72:75]
	v_mfma_f32_16x16x32_bf16 v[80:83], v[230:233], v[222:225], v[80:83]
	v_mfma_f32_16x16x32_bf16 v[88:91], v[238:241], v[222:225], v[88:91]
	v_readfirstlane_b32 s56, v158
	v_add_u32_e32 v134, 0x2000, v158
	v_lshl_add_u64 v[246:247], v[214:215], 0, s[8:9]
	s_mov_b32 m0, s56
	v_readfirstlane_b32 s56, v134
	s_barrier
	ds_read_b128 v[186:189], v163 offset:16384
	ds_read_b128 v[190:193], v163 offset:17408
	ds_read_b128 v[194:197], v162 offset:16384
	ds_read_b128 v[198:201], v162 offset:17408
	ds_read_b128 v[202:205], v161 offset:16384
	ds_read_b128 v[208:211], v161 offset:17408
	ds_read_b128 v[218:221], v160 offset:16384
	ds_read_b128 v[222:225], v160 offset:17408
	global_load_lds_dwordx4 v[246:247], off
	s_mov_b32 m0, s56
	v_lshl_add_u64 v[246:247], v[216:217], 0, s[8:9]
	global_load_lds_dwordx4 v[246:247], off
	s_barrier
	s_waitcnt lgkmcnt(0)
	s_waitcnt lgkmcnt(0)
	v_mfma_f32_16x16x32_bf16 v[20:23], v[136:139], v[186:189], v[20:23]
	v_mfma_f32_16x16x32_bf16 v[32:35], v[178:181], v[186:189], v[32:35]
	v_mfma_f32_16x16x32_bf16 v[44:47], v[136:139], v[194:197], v[44:47]
	v_mfma_f32_16x16x32_bf16 v[56:59], v[178:181], v[194:197], v[56:59]
	v_mfma_f32_16x16x32_bf16 v[68:71], v[136:139], v[202:205], v[68:71]
	v_mfma_f32_16x16x32_bf16 v[76:79], v[178:181], v[202:205], v[76:79]
	v_mfma_f32_16x16x32_bf16 v[84:87], v[136:139], v[218:221], v[84:87]
	v_mfma_f32_16x16x32_bf16 v[92:95], v[178:181], v[218:221], v[92:95]
	v_mfma_f32_16x16x32_bf16 v[20:23], v[174:177], v[190:193], v[20:23]
	v_mfma_f32_16x16x32_bf16 v[32:35], v[182:185], v[190:193], v[32:35]
	v_mfma_f32_16x16x32_bf16 v[44:47], v[174:177], v[198:201], v[44:47]
	v_mfma_f32_16x16x32_bf16 v[56:59], v[182:185], v[198:201], v[56:59]
	v_mfma_f32_16x16x32_bf16 v[68:71], v[174:177], v[208:211], v[68:71]
	v_mfma_f32_16x16x32_bf16 v[76:79], v[182:185], v[208:211], v[76:79]
	v_mfma_f32_16x16x32_bf16 v[84:87], v[174:177], v[222:225], v[84:87]
	v_mfma_f32_16x16x32_bf16 v[92:95], v[182:185], v[222:225], v[92:95]
	s_barrier
; #define STAGE(P, BASE, br, kt) STAGET(tid_, P, BASE, br, kt)
; #define LDA(dst, b, h) UFOR(m, 4) UFOR(k, 2) \
;     dst[m][k] = *reinterpret_cast<const bf16x8*>((char*)SA(b, h) + lds_byte(wr * 64 + m * 16 + fr, k * 32 + fq * 8))
; #define LDB(dst, b, h) UFOR(n, 2) UFOR(k, 2) \
;     dst[n][k] = *reinterpret_cast<const bf16x8*>((char*)SB(b, h) + lds_byte(wc * 32 + n * 16 + fr, k * 32 + fq * 8))
; #define MMA(ai, bj, At, Bq) do { __builtin_amdgcn_s_setprio(1); \
;     UFOR(m, 4) UFOR(n, 2) UFOR(k, 2) \
;       acc[ai][bj][m][n] = __builtin_amdgcn_mfma_f32_16x16x32_bf16(Bq[n][k], At[m][k], acc[ai][bj][m][n], 0, 0, 0); \
;     __builtin_amdgcn_s_setprio(0); } while (0)
; #define WAIT_V(n) asm volatile("s_waitcnt vmcnt(" #n ")" ::: "memory")
; #define WAIT_L(n) asm volatile("s_waitcnt lgkmcnt(" #n ")" ::: "memory")
; #define BAR __builtin_amdgcn_s_barrier()
; #define SCHED __builtin_amdgcn_sched_barrier(0)
; template <int EPI, int K, int KL> ...
;     ...
;   for (int t = 0; t < nt - 2; t += 2) {
;     LDB(B0, 0, 0); SCHED; LDA(At, 0, 0); STAGE(SA(1, 1), A, brow + HALF, t + 1);
;     WAIT_L(8); BAR; WAIT_L(0); MMA(0, 0, At, B0); BAR; SCHED;
;     LDB(B1, 0, 1); STAGE(SB(0, 0), Bt, bcol, t + 2);
;     BAR; WAIT_L(0); MMA(0, 1, At, B1); BAR;
;     LDA(At, 0, 1); STAGE(SA(0, 0), A, brow, t + 2);
;     BAR; WAIT_L(0); MMA(1, 0, At, B0); BAR; SCHED;
;     STAGE(SB(0, 1), Bt, bcol + HALF, t + 2);
;     WAIT_V(6); BAR; MMA(1, 1, At, B1); BAR;
;     LDB(B0, 1, 0); SCHED; LDA(At, 1, 0); STAGE(SA(0, 1), A, brow + HALF, t + 2);
;     WAIT_L(8); BAR; WAIT_L(0); MMA(0, 0, At, B0); BAR; SCHED;
;     LDB(B1, 1, 1); STAGE(SB(1, 0), Bt, bcol, t + 3);
;     BAR; WAIT_L(0); MMA(0, 1, At, B1); BAR;
;     LDA(At, 1, 1); STAGE(SA(1, 0), A, brow, t + 3);
;     BAR; WAIT_L(0); MMA(1, 0, At, B0); BAR; SCHED;
;     STAGE(SB(1, 1), Bt, bcol + HALF, t + 3);
;     WAIT_V(6); BAR; MMA(1, 1, At, B1); BAR;
;   }
	v_readfirstlane_b32 s56, v159
	v_add_u32_e32 v134, 0x2000, v159
	v_lshl_add_u64 v[136:137], v[242:243], 0, s[96:97]
	s_mov_b32 m0, s56
	v_readfirstlane_b32 s56, v134
	global_load_lds_dwordx4 v[136:137], off
	s_mov_b32 m0, s56
	v_lshl_add_u64 v[136:137], v[244:245], 0, s[96:97]
	global_load_lds_dwordx4 v[136:137], off
	s_waitcnt vmcnt(6)
	s_barrier
	v_mfma_f32_16x16x32_bf16 v[96:99], v[226:229], v[186:189], v[96:99]
	v_mfma_f32_16x16x32_bf16 v[100:103], v[234:237], v[186:189], v[100:103]
	v_mfma_f32_16x16x32_bf16 v[104:107], v[226:229], v[194:197], v[104:107]
	v_mfma_f32_16x16x32_bf16 v[108:111], v[234:237], v[194:197], v[108:111]
	v_mfma_f32_16x16x32_bf16 v[112:115], v[226:229], v[202:205], v[112:115]
	v_mfma_f32_16x16x32_bf16 v[116:119], v[234:237], v[202:205], v[116:119]
	v_mfma_f32_16x16x32_bf16 v[120:123], v[226:229], v[218:221], v[120:123]
	v_mfma_f32_16x16x32_bf16 v[124:127], v[234:237], v[218:221], v[124:127]
	v_mfma_f32_16x16x32_bf16 v[96:99], v[230:233], v[190:193], v[96:99]
	v_mfma_f32_16x16x32_bf16 v[100:103], v[238:241], v[190:193], v[100:103]
	v_mfma_f32_16x16x32_bf16 v[104:107], v[230:233], v[198:201], v[104:107]
	v_mfma_f32_16x16x32_bf16 v[108:111], v[238:241], v[198:201], v[108:111]
	v_mfma_f32_16x16x32_bf16 v[112:115], v[230:233], v[208:211], v[112:115]
	v_mfma_f32_16x16x32_bf16 v[116:119], v[238:241], v[208:211], v[116:119]
	v_mfma_f32_16x16x32_bf16 v[120:123], v[230:233], v[222:225], v[120:123]
	v_mfma_f32_16x16x32_bf16 v[124:127], v[238:241], v[222:225], v[124:127]
	s_barrier
	ds_read_b128 v[136:139], v166
	ds_read_b128 v[174:177], v166 offset:1024
	ds_read_b128 v[178:181], v166 offset:2048
	ds_read_b128 v[182:185], v166 offset:3072
	ds_read_b128 v[186:189], v163 offset:32768
	ds_read_b128 v[190:193], v163 offset:33792
	ds_read_b128 v[194:197], v162 offset:32768
	ds_read_b128 v[198:201], v162 offset:33792
	ds_read_b128 v[202:205], v161 offset:32768
	ds_read_b128 v[208:211], v161 offset:33792
	ds_read_b128 v[218:221], v160 offset:32768
	ds_read_b128 v[222:225], v160 offset:33792
	v_add_u32_e32 v134, 0x4000, v158
	v_lshl_add_u64 v[226:227], v[214:215], 0, s[12:13]
	v_readfirstlane_b32 s56, v134
	v_add_u32_e32 v134, 0x6000, v158
	s_mov_b32 m0, s56
	v_readfirstlane_b32 s56, v134
	global_load_lds_dwordx4 v[226:227], off
	s_mov_b32 m0, s56
	v_lshl_add_u64 v[226:227], v[216:217], 0, s[12:13]
	global_load_lds_dwordx4 v[226:227], off
	s_waitcnt lgkmcnt(8)
	s_barrier
	s_waitcnt lgkmcnt(0)
	s_waitcnt lgkmcnt(0)
	v_mfma_f32_16x16x32_bf16 v[0:3], v[136:139], v[186:189], v[0:3]
	v_mfma_f32_16x16x32_bf16 v[4:7], v[178:181], v[186:189], v[4:7]
	v_mfma_f32_16x16x32_bf16 v[8:11], v[136:139], v[194:197], v[8:11]
	v_mfma_f32_16x16x32_bf16 v[16:19], v[178:181], v[194:197], v[16:19]
	v_mfma_f32_16x16x32_bf16 v[28:31], v[136:139], v[202:205], v[28:31]
	v_mfma_f32_16x16x32_bf16 v[40:43], v[178:181], v[202:205], v[40:43]
	v_mfma_f32_16x16x32_bf16 v[52:55], v[136:139], v[218:221], v[52:55]
	v_mfma_f32_16x16x32_bf16 v[64:67], v[178:181], v[218:221], v[64:67]
	v_mfma_f32_16x16x32_bf16 v[0:3], v[174:177], v[190:193], v[0:3]
	v_mfma_f32_16x16x32_bf16 v[4:7], v[182:185], v[190:193], v[4:7]
	v_mfma_f32_16x16x32_bf16 v[8:11], v[174:177], v[198:201], v[8:11]
	v_mfma_f32_16x16x32_bf16 v[16:19], v[182:185], v[198:201], v[16:19]
	v_mfma_f32_16x16x32_bf16 v[28:31], v[174:177], v[208:211], v[28:31]
	v_mfma_f32_16x16x32_bf16 v[40:43], v[182:185], v[208:211], v[40:43]
	v_mfma_f32_16x16x32_bf16 v[52:55], v[174:177], v[222:225], v[52:55]
	v_mfma_f32_16x16x32_bf16 v[64:67], v[182:185], v[222:225], v[64:67]
	s_barrier
	ds_read_b128 v[226:229], v164
	ds_read_b128 v[230:233], v164 offset:1024
	ds_read_b128 v[234:237], v164 offset:2048
	ds_read_b128 v[238:241], v164 offset:3072
	v_readfirstlane_b32 s56, v165
	v_add_u32_e32 v134, 0x2000, v165
	v_lshl_add_u64 v[246:247], v[242:243], 0, s[80:81]
	s_mov_b32 m0, s56
	v_readfirstlane_b32 s56, v134
	global_load_lds_dwordx4 v[246:247], off
	s_mov_b32 m0, s56
	v_lshl_add_u64 v[246:247], v[244:245], 0, s[80:81]
	global_load_lds_dwordx4 v[246:247], off
	s_barrier
	s_waitcnt lgkmcnt(0)
	s_waitcnt lgkmcnt(0)
	v_mfma_f32_16x16x32_bf16 v[12:15], v[226:229], v[186:189], v[12:15]
	v_mfma_f32_16x16x32_bf16 v[24:27], v[234:237], v[186:189], v[24:27]
	v_mfma_f32_16x16x32_bf16 v[36:39], v[226:229], v[194:197], v[36:39]
	v_mfma_f32_16x16x32_bf16 v[48:51], v[234:237], v[194:197], v[48:51]
	v_mfma_f32_16x16x32_bf16 v[60:63], v[226:229], v[202:205], v[60:63]
	v_mfma_f32_16x16x32_bf16 v[72:75], v[234:237], v[202:205], v[72:75]
	v_mfma_f32_16x16x32_bf16 v[80:83], v[226:229], v[218:221], v[80:83]
	v_mfma_f32_16x16x32_bf16 v[88:91], v[234:237], v[218:221], v[88:91]
	v_mfma_f32_16x16x32_bf16 v[12:15], v[230:233], v[190:193], v[12:15]
	v_mfma_f32_16x16x32_bf16 v[24:27], v[238:241], v[190:193], v[24:27]
	v_mfma_f32_16x16x32_bf16 v[36:39], v[230:233], v[198:201], v[36:39]
	v_mfma_f32_16x16x32_bf16 v[48:51], v[238:241], v[198:201], v[48:51]
	v_mfma_f32_16x16x32_bf16 v[60:63], v[230:233], v[208:211], v[60:63]
	v_mfma_f32_16x16x32_bf16 v[72:75], v[238:241], v[208:211], v[72:75]
	v_mfma_f32_16x16x32_bf16 v[80:83], v[230:233], v[222:225], v[80:83]
	v_mfma_f32_16x16x32_bf16 v[88:91], v[238:241], v[222:225], v[88:91]
	v_readfirstlane_b32 s56, v167
	v_lshl_add_u64 v[214:215], v[214:215], 0, s[16:17]
	s_mov_b32 m0, s56
	v_readfirstlane_b32 s56, v168
	s_barrier
	ds_read_b128 v[186:189], v163 offset:49152
	ds_read_b128 v[190:193], v163 offset:50176
	ds_read_b128 v[194:197], v162 offset:49152
	ds_read_b128 v[198:201], v162 offset:50176
	ds_read_b128 v[202:205], v161 offset:49152
	ds_read_b128 v[208:211], v161 offset:50176
	ds_read_b128 v[218:221], v160 offset:49152
	ds_read_b128 v[222:225], v160 offset:50176
	global_load_lds_dwordx4 v[214:215], off
	s_mov_b32 m0, s56
	v_lshl_add_u64 v[214:215], v[216:217], 0, s[16:17]
	global_load_lds_dwordx4 v[214:215], off
	s_barrier
; #define STAGE(P, BASE, br, kt) STAGET(tid_, P, BASE, br, kt)
; #define LDA(dst, b, h) UFOR(m, 4) UFOR(k, 2) \
;     dst[m][k] = *reinterpret_cast<const bf16x8*>((char*)SA(b, h) + lds_byte(wr * 64 + m * 16 + fr, k * 32 + fq * 8))
; #define LDB(dst, b, h) UFOR(n, 2) UFOR(k, 2) \
;     dst[n][k] = *reinterpret_cast<const bf16x8*>((char*)SB(b, h) + lds_byte(wc * 32 + n * 16 + fr, k * 32 + fq * 8))
; #define MMA(ai, bj, At, Bq) do { __builtin_amdgcn_s_setprio(1); \
;     UFOR(m, 4) UFOR(n, 2) UFOR(k, 2) \
;       acc[ai][bj][m][n] = __builtin_amdgcn_mfma_f32_16x16x32_bf16(Bq[n][k], At[m][k], acc[ai][bj][m][n], 0, 0, 0); \
;     __builtin_amdgcn_s_setprio(0); } while (0)
; #define WAIT_V(n) asm volatile("s_waitcnt vmcnt(" #n ")" ::: "memory")
; #define WAIT_L(n) asm volatile("s_waitcnt lgkmcnt(" #n ")" ::: "memory")
; #define BAR __builtin_amdgcn_s_barrier()
; #define SCHED __builtin_amdgcn_sched_barrier(0)
; template <int EPI, int K, int KL> ...
;     ...
;     STAGE(SB(0, 1), Bt, bcol + HALF, t + 2);
;     WAIT_V(6); BAR; MMA(1, 1, At, B1); BAR;
;     LDB(B0, 1, 0); SCHED; LDA(At, 1, 0); STAGE(SA(0, 1), A, brow + HALF, t + 2);
;     WAIT_L(8); BAR; WAIT_L(0); MMA(0, 0, At, B0); BAR; SCHED;
;     LDB(B1, 1, 1); STAGE(SB(1, 0), Bt, bcol, t + 3);
;     BAR; WAIT_L(0); MMA(0, 1, At, B1); BAR;
;     LDA(At, 1, 1); STAGE(SA(1, 0), A, brow, t + 3);
;     BAR; WAIT_L(0); MMA(1, 0, At, B0); BAR; SCHED;
;     STAGE(SB(1, 1), Bt, bcol + HALF, t + 3);
;     WAIT_V(6); BAR; MMA(1, 1, At, B1); BAR;
;   }
;   { LDB(B0, 0, 0); LDA(At, 0, 0); STAGE(SA(1, 1), A, brow + HALF, nt - 1);
;     BAR; WAIT_L(0); MMA(0, 0, At, B0); BAR;
;     LDB(B1, 0, 1); BAR; WAIT_L(0); MMA(0, 1, At, B1); BAR;
;     LDA(At, 0, 1); WAIT_V(4); BAR; WAIT_L(0); MMA(1, 0, At, B0); MMA(1, 1, At, B1); BAR; }
	s_waitcnt lgkmcnt(0)
	s_waitcnt lgkmcnt(0)
	v_mfma_f32_16x16x32_bf16 v[20:23], v[136:139], v[186:189], v[20:23]
	v_mfma_f32_16x16x32_bf16 v[32:35], v[178:181], v[186:189], v[32:35]
	v_mfma_f32_16x16x32_bf16 v[44:47], v[136:139], v[194:197], v[44:47]
	v_mfma_f32_16x16x32_bf16 v[56:59], v[178:181], v[194:197], v[56:59]
	v_mfma_f32_16x16x32_bf16 v[68:71], v[136:139], v[202:205], v[68:71]
	v_mfma_f32_16x16x32_bf16 v[76:79], v[178:181], v[202:205], v[76:79]
	v_mfma_f32_16x16x32_bf16 v[84:87], v[136:139], v[218:221], v[84:87]
	v_mfma_f32_16x16x32_bf16 v[92:95], v[178:181], v[218:221], v[92:95]
	v_mfma_f32_16x16x32_bf16 v[20:23], v[174:177], v[190:193], v[20:23]
	v_mfma_f32_16x16x32_bf16 v[32:35], v[182:185], v[190:193], v[32:35]
	v_mfma_f32_16x16x32_bf16 v[44:47], v[174:177], v[198:201], v[44:47]
	v_mfma_f32_16x16x32_bf16 v[56:59], v[182:185], v[198:201], v[56:59]
	v_mfma_f32_16x16x32_bf16 v[68:71], v[174:177], v[208:211], v[68:71]
	v_mfma_f32_16x16x32_bf16 v[76:79], v[182:185], v[208:211], v[76:79]
	v_mfma_f32_16x16x32_bf16 v[84:87], v[174:177], v[222:225], v[84:87]
	v_mfma_f32_16x16x32_bf16 v[92:95], v[182:185], v[222:225], v[92:95]
	s_barrier
	v_readfirstlane_b32 s56, v170
	v_add_u32_e32 v134, 0x2000, v170
	v_lshl_add_u64 v[136:137], v[242:243], 0, s[90:91]
	s_mov_b32 m0, s56
	v_readfirstlane_b32 s56, v134
	global_load_lds_dwordx4 v[136:137], off
	s_mov_b32 m0, s56
	v_lshl_add_u64 v[136:137], v[244:245], 0, s[90:91]
	global_load_lds_dwordx4 v[136:137], off
	s_waitcnt vmcnt(6)
	s_barrier
	v_mfma_f32_16x16x32_bf16 v[96:99], v[226:229], v[186:189], v[96:99]
	v_mfma_f32_16x16x32_bf16 v[100:103], v[234:237], v[186:189], v[100:103]
	v_mfma_f32_16x16x32_bf16 v[104:107], v[226:229], v[194:197], v[104:107]
	v_mfma_f32_16x16x32_bf16 v[108:111], v[234:237], v[194:197], v[108:111]
	v_mfma_f32_16x16x32_bf16 v[112:115], v[226:229], v[202:205], v[112:115]
	v_mfma_f32_16x16x32_bf16 v[116:119], v[234:237], v[202:205], v[116:119]
	v_mfma_f32_16x16x32_bf16 v[120:123], v[226:229], v[218:221], v[120:123]
	v_mfma_f32_16x16x32_bf16 v[124:127], v[234:237], v[218:221], v[124:127]
	v_mfma_f32_16x16x32_bf16 v[96:99], v[230:233], v[190:193], v[96:99]
	v_mfma_f32_16x16x32_bf16 v[100:103], v[238:241], v[190:193], v[100:103]
	v_mfma_f32_16x16x32_bf16 v[104:107], v[230:233], v[198:201], v[104:107]
	v_mfma_f32_16x16x32_bf16 v[108:111], v[238:241], v[198:201], v[108:111]
	v_mfma_f32_16x16x32_bf16 v[112:115], v[230:233], v[208:211], v[112:115]
	v_mfma_f32_16x16x32_bf16 v[116:119], v[238:241], v[208:211], v[116:119]
	v_mfma_f32_16x16x32_bf16 v[120:123], v[230:233], v[222:225], v[120:123]
	v_mfma_f32_16x16x32_bf16 v[124:127], v[238:241], v[222:225], v[124:127]
	s_add_i32 s53, s53, 2
	v_lshl_add_u64 v[144:145], v[144:145], 0, s[20:21]
	v_lshl_add_u64 v[146:147], v[146:147], 0, s[20:21]
	v_lshl_add_u64 v[148:149], v[148:149], 0, s[20:21]
	s_cmp_lt_u32 s53, 28
	v_lshl_add_u64 v[150:151], v[150:151], 0, s[20:21]
	s_cbranch_scc1 .Lkrot_1107
	s_barrier
	s_add_u32 s40, s40, 0x80f80
	s_addc_u32 s41, s41, 0
	v_lshl_add_u64 v[130:131], s[40:41], 0, v[130:131]
	v_readfirstlane_b32 s53, v172
	v_lshl_add_u64 v[128:129], v[128:129], 1, v[130:131]
	s_mov_b32 m0, s53
	ds_read_b128 v[136:139], v171
	ds_read_b128 v[144:147], v171 offset:1024
	ds_read_b128 v[148:151], v171 offset:2048
	ds_read_b128 v[174:177], v171 offset:3072
	ds_read_b128 v[178:181], v163
	ds_read_b128 v[182:185], v163 offset:1024
	ds_read_b128 v[186:189], v162
	ds_read_b128 v[190:193], v162 offset:1024
	ds_read_b128 v[194:197], v161
	ds_read_b128 v[198:201], v161 offset:1024
	ds_read_b128 v[202:205], v160
	ds_read_b128 v[208:211], v160 offset:1024
	global_load_lds_dwordx4 v[128:129], off
	v_lshl_add_u64 v[128:129], s[40:41], 0, v[142:143]
	v_readfirstlane_b32 s40, v173
	v_lshl_add_u64 v[128:129], v[140:141], 1, v[128:129]
	s_mov_b32 m0, s40
	s_nop 0
	global_load_lds_dwordx4 v[128:129], off
	s_barrier
	s_waitcnt lgkmcnt(0)
	s_waitcnt lgkmcnt(0)
	v_mfma_f32_16x16x32_bf16 v[0:3], v[136:139], v[178:181], v[0:3]
	v_mfma_f32_16x16x32_bf16 v[4:7], v[148:151], v[178:181], v[4:7]
	v_mfma_f32_16x16x32_bf16 v[8:11], v[136:139], v[186:189], v[8:11]
	v_mfma_f32_16x16x32_bf16 v[16:19], v[148:151], v[186:189], v[16:19]
	v_mfma_f32_16x16x32_bf16 v[28:31], v[136:139], v[194:197], v[28:31]
	v_mfma_f32_16x16x32_bf16 v[40:43], v[148:151], v[194:197], v[40:43]
	v_mfma_f32_16x16x32_bf16 v[52:55], v[136:139], v[202:205], v[52:55]
	v_mfma_f32_16x16x32_bf16 v[64:67], v[148:151], v[202:205], v[64:67]
	v_mfma_f32_16x16x32_bf16 v[0:3], v[144:147], v[182:185], v[0:3]
	v_mfma_f32_16x16x32_bf16 v[4:7], v[174:177], v[182:185], v[4:7]
	v_mfma_f32_16x16x32_bf16 v[8:11], v[144:147], v[190:193], v[8:11]
	v_mfma_f32_16x16x32_bf16 v[16:19], v[174:177], v[190:193], v[16:19]
	v_mfma_f32_16x16x32_bf16 v[28:31], v[144:147], v[198:201], v[28:31]
	v_mfma_f32_16x16x32_bf16 v[40:43], v[174:177], v[198:201], v[40:43]
	v_mfma_f32_16x16x32_bf16 v[52:55], v[144:147], v[208:211], v[52:55]
	v_mfma_f32_16x16x32_bf16 v[64:67], v[174:177], v[208:211], v[64:67]
	s_barrier
	ds_read_b128 v[128:131], v169
	ds_read_b128 v[140:143], v169 offset:1024
	ds_read_b128 v[170:173], v169 offset:2048
	ds_read_b128 v[218:221], v169 offset:3072
	s_barrier
; #define LDA(dst, b, h) UFOR(m, 4) UFOR(k, 2) \
;     dst[m][k] = *reinterpret_cast<const bf16x8*>((char*)SA(b, h) + lds_byte(wr * 64 + m * 16 + fr, k * 32 + fq * 8))
; #define LDB(dst, b, h) UFOR(n, 2) UFOR(k, 2) \
;     dst[n][k] = *reinterpret_cast<const bf16x8*>((char*)SB(b, h) + lds_byte(wc * 32 + n * 16 + fr, k * 32 + fq * 8))
; #define MMA(ai, bj, At, Bq) do { __builtin_amdgcn_s_setprio(1); \
;     UFOR(m, 4) UFOR(n, 2) UFOR(k, 2) \
;       acc[ai][bj][m][n] = __builtin_amdgcn_mfma_f32_16x16x32_bf16(Bq[n][k], At[m][k], acc[ai][bj][m][n], 0, 0, 0); \
;     __builtin_amdgcn_s_setprio(0); } while (0)
; #define WAIT_V(n) asm volatile("s_waitcnt vmcnt(" #n ")" ::: "memory")
; #define WAIT_L(n) asm volatile("s_waitcnt lgkmcnt(" #n ")" ::: "memory")
; #define BAR __builtin_amdgcn_s_barrier()
; template <int EPI, int K, int KL> ...
;     ...
;     BAR; WAIT_L(0); MMA(0, 0, At, B0); BAR;
;     LDB(B1, 0, 1); BAR; WAIT_L(0); MMA(0, 1, At, B1); BAR;
;     LDA(At, 0, 1); WAIT_V(4); BAR; WAIT_L(0); MMA(1, 0, At, B0); MMA(1, 1, At, B1); BAR; }
;   { LDB(B0, 1, 0); LDA(At, 1, 0); WAIT_V(2); BAR; WAIT_L(0); MMA(0, 0, At, B0); BAR;
	s_waitcnt lgkmcnt(0)
	s_waitcnt lgkmcnt(0)
	v_mfma_f32_16x16x32_bf16 v[12:15], v[128:131], v[178:181], v[12:15]
	v_mfma_f32_16x16x32_bf16 v[24:27], v[170:173], v[178:181], v[24:27]
	v_mfma_f32_16x16x32_bf16 v[36:39], v[128:131], v[186:189], v[36:39]
	v_mfma_f32_16x16x32_bf16 v[48:51], v[170:173], v[186:189], v[48:51]
	v_mfma_f32_16x16x32_bf16 v[60:63], v[128:131], v[194:197], v[60:63]
	v_mfma_f32_16x16x32_bf16 v[72:75], v[170:173], v[194:197], v[72:75]
	v_mfma_f32_16x16x32_bf16 v[80:83], v[128:131], v[202:205], v[80:83]
	v_mfma_f32_16x16x32_bf16 v[12:15], v[140:143], v[182:185], v[12:15]
	v_mfma_f32_16x16x32_bf16 v[24:27], v[218:221], v[182:185], v[24:27]
	v_mfma_f32_16x16x32_bf16 v[36:39], v[140:143], v[190:193], v[36:39]
	v_mfma_f32_16x16x32_bf16 v[48:51], v[218:221], v[190:193], v[48:51]
	v_mfma_f32_16x16x32_bf16 v[60:63], v[140:143], v[198:201], v[60:63]
	v_mfma_f32_16x16x32_bf16 v[72:75], v[218:221], v[198:201], v[72:75]
	v_mfma_f32_16x16x32_bf16 v[178:181], v[140:143], v[208:211], v[80:83]
	v_mfma_f32_16x16x32_bf16 v[80:83], v[170:173], v[202:205], v[88:91]
	v_mfma_f32_16x16x32_bf16 v[182:185], v[218:221], v[208:211], v[80:83]
	s_barrier
	s_nop 5
	ds_read_b128 v[80:83], v163 offset:16384
	ds_read_b128 v[88:91], v163 offset:17408
	ds_read_b128 v[186:189], v162 offset:16384
	ds_read_b128 v[190:193], v162 offset:17408
	ds_read_b128 v[194:197], v161 offset:16384
	ds_read_b128 v[198:201], v161 offset:17408
	ds_read_b128 v[202:205], v160 offset:16384
	ds_read_b128 v[208:211], v160 offset:17408
	s_waitcnt vmcnt(4)
	s_barrier
	s_waitcnt lgkmcnt(0)
	s_waitcnt lgkmcnt(0)
	v_mfma_f32_16x16x32_bf16 v[56:59], v[148:151], v[186:189], v[56:59]
	v_mfma_f32_16x16x32_bf16 v[222:225], v[174:177], v[190:193], v[56:59]
	v_mfma_f32_16x16x32_bf16 v[56:59], v[136:139], v[194:197], v[68:71]
	v_mfma_f32_16x16x32_bf16 v[226:229], v[144:147], v[198:201], v[56:59]
	v_mfma_f32_16x16x32_bf16 v[56:59], v[148:151], v[194:197], v[76:79]
	v_mfma_f32_16x16x32_bf16 v[20:23], v[136:139], v[80:83], v[20:23]
	v_mfma_f32_16x16x32_bf16 v[32:35], v[148:151], v[80:83], v[32:35]
	v_mfma_f32_16x16x32_bf16 v[44:47], v[136:139], v[186:189], v[44:47]
	v_mfma_f32_16x16x32_bf16 v[230:233], v[174:177], v[198:201], v[56:59]
	v_mfma_f32_16x16x32_bf16 v[56:59], v[136:139], v[202:205], v[84:87]
	v_mfma_f32_16x16x32_bf16 v[20:23], v[144:147], v[88:91], v[20:23]
	v_mfma_f32_16x16x32_bf16 v[32:35], v[174:177], v[88:91], v[32:35]
	v_mfma_f32_16x16x32_bf16 v[44:47], v[144:147], v[190:193], v[44:47]
	v_mfma_f32_16x16x32_bf16 v[136:139], v[144:147], v[208:211], v[56:59]
	v_mfma_f32_16x16x32_bf16 v[56:59], v[148:151], v[202:205], v[92:95]
	v_mfma_f32_16x16x32_bf16 v[144:147], v[174:177], v[208:211], v[56:59]
	v_mfma_f32_16x16x32_bf16 v[56:59], v[128:131], v[80:83], v[96:99]
	v_mfma_f32_16x16x32_bf16 v[148:151], v[140:143], v[88:91], v[56:59]
	v_mfma_f32_16x16x32_bf16 v[56:59], v[170:173], v[80:83], v[100:103]
	v_mfma_f32_16x16x32_bf16 v[174:177], v[218:221], v[88:91], v[56:59]
	v_mfma_f32_16x16x32_bf16 v[56:59], v[128:131], v[186:189], v[104:107]
	v_mfma_f32_16x16x32_bf16 v[234:237], v[140:143], v[190:193], v[56:59]
	v_mfma_f32_16x16x32_bf16 v[56:59], v[170:173], v[186:189], v[108:111]
	v_mfma_f32_16x16x32_bf16 v[186:189], v[218:221], v[190:193], v[56:59]
	v_mfma_f32_16x16x32_bf16 v[56:59], v[128:131], v[194:197], v[112:115]
	v_mfma_f32_16x16x32_bf16 v[190:193], v[140:143], v[198:201], v[56:59]
	v_mfma_f32_16x16x32_bf16 v[56:59], v[170:173], v[194:197], v[116:119]
	v_mfma_f32_16x16x32_bf16 v[194:197], v[218:221], v[198:201], v[56:59]
	v_mfma_f32_16x16x32_bf16 v[56:59], v[128:131], v[202:205], v[120:123]
	v_mfma_f32_16x16x32_bf16 v[128:131], v[140:143], v[208:211], v[56:59]
	v_mfma_f32_16x16x32_bf16 v[56:59], v[170:173], v[202:205], v[124:127]
	v_mfma_f32_16x16x32_bf16 v[140:143], v[218:221], v[208:211], v[56:59]
	s_barrier
	ds_read_b128 v[168:171], v166
	ds_read_b128 v[198:201], v166 offset:1024
	ds_read_b128 v[202:205], v166 offset:2048
	ds_read_b128 v[208:211], v166 offset:3072
	s_nop 1
	ds_read_b128 v[56:59], v163 offset:32768
	ds_read_b128 v[68:71], v163 offset:33792
	ds_read_b128 v[76:79], v162 offset:32768
	ds_read_b128 v[80:83], v162 offset:33792
	ds_read_b128 v[218:221], v161 offset:32768
	ds_read_b128 v[238:241], v161 offset:33792
	ds_read_b128 v[242:245], v160 offset:32768
	ds_read_b128 v[246:249], v160 offset:33792
	s_waitcnt vmcnt(2)
	s_barrier
; #define LDA(dst, b, h) UFOR(m, 4) UFOR(k, 2) \
;     dst[m][k] = *reinterpret_cast<const bf16x8*>((char*)SA(b, h) + lds_byte(wr * 64 + m * 16 + fr, k * 32 + fq * 8))
; #define LDB(dst, b, h) UFOR(n, 2) UFOR(k, 2) \
;     dst[n][k] = *reinterpret_cast<const bf16x8*>((char*)SB(b, h) + lds_byte(wc * 32 + n * 16 + fr, k * 32 + fq * 8))
; #define MMA(ai, bj, At, Bq) do { __builtin_amdgcn_s_setprio(1); \
;     UFOR(m, 4) UFOR(n, 2) UFOR(k, 2) \
;       acc[ai][bj][m][n] = __builtin_amdgcn_mfma_f32_16x16x32_bf16(Bq[n][k], At[m][k], acc[ai][bj][m][n], 0, 0, 0); \
;     __builtin_amdgcn_s_setprio(0); } while (0)
; #define WAIT_V(n) asm volatile("s_waitcnt vmcnt(" #n ")" ::: "memory")
; #define WAIT_L(n) asm volatile("s_waitcnt lgkmcnt(" #n ")" ::: "memory")
; #define BAR __builtin_amdgcn_s_barrier()
; template <int EPI, int K, int KL> ...
;     ...
;   { LDB(B0, 1, 0); LDA(At, 1, 0); WAIT_V(2); BAR; WAIT_L(0); MMA(0, 0, At, B0); BAR;
;     LDB(B1, 1, 1); WAIT_V(0); BAR; WAIT_L(0); MMA(0, 1, At, B1); BAR;
;     LDA(At, 1, 1); BAR; WAIT_L(0); MMA(1, 0, At, B0); MMA(1, 1, At, B1); BAR; }
;   if (wr == 0) BAR;
	s_waitcnt lgkmcnt(0)
	s_waitcnt lgkmcnt(0)
	v_mfma_f32_16x16x32_bf16 v[0:3], v[168:171], v[56:59], v[0:3]
	v_mfma_f32_16x16x32_bf16 v[124:127], v[198:201], v[68:71], v[0:3]
	v_mfma_f32_16x16x32_bf16 v[0:3], v[202:205], v[56:59], v[4:7]
	v_mfma_f32_16x16x32_bf16 v[120:123], v[208:211], v[68:71], v[0:3]
	v_mfma_f32_16x16x32_bf16 v[0:3], v[168:171], v[76:79], v[8:11]
	v_mfma_f32_16x16x32_bf16 v[116:119], v[198:201], v[80:83], v[0:3]
	v_mfma_f32_16x16x32_bf16 v[0:3], v[202:205], v[76:79], v[16:19]
	v_mfma_f32_16x16x32_bf16 v[112:115], v[208:211], v[80:83], v[0:3]
	v_mfma_f32_16x16x32_bf16 v[0:3], v[168:171], v[218:221], v[28:31]
	v_mfma_f32_16x16x32_bf16 v[108:111], v[198:201], v[238:241], v[0:3]
	v_mfma_f32_16x16x32_bf16 v[0:3], v[202:205], v[218:221], v[40:43]
	v_mfma_f32_16x16x32_bf16 v[104:107], v[208:211], v[238:241], v[0:3]
	v_mfma_f32_16x16x32_bf16 v[0:3], v[168:171], v[242:245], v[52:55]
	v_mfma_f32_16x16x32_bf16 v[100:103], v[198:201], v[246:249], v[0:3]
	v_mfma_f32_16x16x32_bf16 v[0:3], v[202:205], v[242:245], v[64:67]
	v_mfma_f32_16x16x32_bf16 v[96:99], v[208:211], v[246:249], v[0:3]
	s_barrier
	s_nop 5
	ds_read_b128 v[0:3], v164
	ds_read_b128 v[4:7], v164 offset:1024
	ds_read_b128 v[214:217], v164 offset:2048
	ds_read_b128 v[164:167], v164 offset:3072
	s_waitcnt vmcnt(0)
	s_barrier
	s_waitcnt lgkmcnt(0)
	s_waitcnt lgkmcnt(0)
	v_mfma_f32_16x16x32_bf16 v[8:11], v[0:3], v[56:59], v[12:15]
	v_mfma_f32_16x16x32_bf16 v[92:95], v[4:7], v[68:71], v[8:11]
	v_mfma_f32_16x16x32_bf16 v[8:11], v[214:217], v[56:59], v[24:27]
	v_mfma_f32_16x16x32_bf16 v[88:91], v[164:167], v[68:71], v[8:11]
	v_mfma_f32_16x16x32_bf16 v[8:11], v[0:3], v[76:79], v[36:39]
	v_mfma_f32_16x16x32_bf16 v[84:87], v[4:7], v[80:83], v[8:11]
	v_mfma_f32_16x16x32_bf16 v[8:11], v[214:217], v[76:79], v[48:51]
	v_mfma_f32_16x16x32_bf16 v[80:83], v[164:167], v[80:83], v[8:11]
	v_mfma_f32_16x16x32_bf16 v[8:11], v[0:3], v[218:221], v[60:63]
	v_mfma_f32_16x16x32_bf16 v[76:79], v[4:7], v[238:241], v[8:11]
	v_mfma_f32_16x16x32_bf16 v[8:11], v[214:217], v[218:221], v[72:75]
	v_mfma_f32_16x16x32_bf16 v[72:75], v[164:167], v[238:241], v[8:11]
	v_mfma_f32_16x16x32_bf16 v[8:11], v[0:3], v[242:245], v[178:181]
	v_mfma_f32_16x16x32_bf16 v[68:71], v[4:7], v[246:249], v[8:11]
	v_mfma_f32_16x16x32_bf16 v[8:11], v[214:217], v[242:245], v[182:185]
	v_mfma_f32_16x16x32_bf16 v[64:67], v[164:167], v[246:249], v[8:11]
	s_barrier
	s_nop 5
	ds_read_b128 v[8:11], v163 offset:49152
	ds_read_b128 v[12:15], v163 offset:50176
	ds_read_b128 v[16:19], v162 offset:49152
	ds_read_b128 v[178:181], v162 offset:50176
	ds_read_b128 v[182:185], v161 offset:49152
	ds_read_b128 v[218:221], v161 offset:50176
	ds_read_b128 v[238:241], v160 offset:49152
	ds_read_b128 v[158:161], v160 offset:50176
	s_barrier
	s_waitcnt lgkmcnt(0)
	s_waitcnt lgkmcnt(0)
	v_mfma_f32_16x16x32_bf16 v[20:23], v[168:171], v[8:11], v[20:23]
	v_mfma_f32_16x16x32_bf16 v[60:63], v[198:201], v[12:15], v[20:23]
	v_mfma_f32_16x16x32_bf16 v[20:23], v[202:205], v[8:11], v[32:35]
	v_mfma_f32_16x16x32_bf16 v[56:59], v[208:211], v[12:15], v[20:23]
	v_mfma_f32_16x16x32_bf16 v[20:23], v[168:171], v[16:19], v[44:47]
	v_mfma_f32_16x16x32_bf16 v[52:55], v[198:201], v[178:181], v[20:23]
	v_mfma_f32_16x16x32_bf16 v[20:23], v[202:205], v[16:19], v[222:225]
	v_mfma_f32_16x16x32_bf16 v[48:51], v[208:211], v[178:181], v[20:23]
	v_mfma_f32_16x16x32_bf16 v[20:23], v[168:171], v[182:185], v[226:229]
	v_mfma_f32_16x16x32_bf16 v[44:47], v[198:201], v[218:221], v[20:23]
	v_mfma_f32_16x16x32_bf16 v[20:23], v[202:205], v[182:185], v[230:233]
	v_mfma_f32_16x16x32_bf16 v[40:43], v[208:211], v[218:221], v[20:23]
	v_mfma_f32_16x16x32_bf16 v[20:23], v[168:171], v[238:241], v[136:139]
	v_mfma_f32_16x16x32_bf16 v[36:39], v[198:201], v[158:161], v[20:23]
	v_mfma_f32_16x16x32_bf16 v[20:23], v[202:205], v[238:241], v[144:147]
	v_mfma_f32_16x16x32_bf16 v[32:35], v[208:211], v[158:161], v[20:23]
	v_mfma_f32_16x16x32_bf16 v[20:23], v[0:3], v[8:11], v[148:151]
	v_mfma_f32_16x16x32_bf16 v[8:11], v[214:217], v[8:11], v[174:177]
	v_mfma_f32_16x16x32_bf16 v[24:27], v[164:167], v[12:15], v[8:11]
	v_mfma_f32_16x16x32_bf16 v[8:11], v[0:3], v[16:19], v[234:237]
	v_mfma_f32_16x16x32_bf16 v[28:31], v[4:7], v[12:15], v[20:23]
	v_mfma_f32_16x16x32_bf16 v[20:23], v[4:7], v[178:181], v[8:11]
	v_mfma_f32_16x16x32_bf16 v[8:11], v[214:217], v[16:19], v[186:189]
	v_mfma_f32_16x16x32_bf16 v[16:19], v[164:167], v[178:181], v[8:11]
	v_mfma_f32_16x16x32_bf16 v[8:11], v[0:3], v[182:185], v[190:193]
	v_mfma_f32_16x16x32_bf16 v[0:3], v[0:3], v[238:241], v[128:131]
	v_mfma_f32_16x16x32_bf16 v[12:15], v[4:7], v[218:221], v[8:11]
	v_mfma_f32_16x16x32_bf16 v[8:11], v[214:217], v[182:185], v[194:197]
	v_mfma_f32_16x16x32_bf16 v[4:7], v[4:7], v[158:161], v[0:3]
	v_mfma_f32_16x16x32_bf16 v[0:3], v[214:217], v[238:241], v[140:143]
	v_mfma_f32_16x16x32_bf16 v[8:11], v[164:167], v[218:221], v[8:11]
	v_mfma_f32_16x16x32_bf16 v[0:3], v[164:167], v[158:161], v[0:3]
	s_movk_i32 s40, 0x100
	v_cmp_gt_u32_e32 vcc, s40, v152
	s_barrier
	s_and_saveexec_b64 s[40:41], vcc
	s_cbranch_execz .LBB0_1110
	s_barrier

; #define STAGE(P, BASE, br, kt) STAGET(tid_, P, BASE, br, kt)
; #define LDA(dst, b, h) UFOR(m, 4) UFOR(k, 2) \
;     dst[m][k] = *reinterpret_cast<const bf16x8*>((char*)SA(b, h) + lds_byte(wr * 64 + m * 16 + fr, k * 32 + fq * 8))
; #define LDB(dst, b, h) UFOR(n, 2) UFOR(k, 2) \
;     dst[n][k] = *reinterpret_cast<const bf16x8*>((char*)SB(b, h) + lds_byte(wc * 32 + n * 16 + fr, k * 32 + fq * 8))
; #define MMA(ai, bj, At, Bq) do { __builtin_amdgcn_s_setprio(1); \
;     UFOR(m, 4) UFOR(n, 2) UFOR(k, 2) \
;       acc[ai][bj][m][n] = __builtin_amdgcn_mfma_f32_16x16x32_bf16(Bq[n][k], At[m][k], acc[ai][bj][m][n], 0, 0, 0); \
;     __builtin_amdgcn_s_setprio(0); } while (0)
; #define WAIT_V(n) asm volatile("s_waitcnt vmcnt(" #n ")" ::: "memory")
; #define WAIT_L(n) asm volatile("s_waitcnt lgkmcnt(" #n ")" ::: "memory")
; #define BAR __builtin_amdgcn_s_barrier()
; #define SCHED __builtin_amdgcn_sched_barrier(0)
; template <int EPI, int K, int KL> ...
;     ...
;     LDB(B0, 0, 0); SCHED; LDA(At, 0, 0); STAGE(SA(1, 1), A, brow + HALF, t + 1);
;     WAIT_L(8); BAR; WAIT_L(0); MMA(0, 0, At, B0); BAR; SCHED;
;     LDB(B1, 0, 1); STAGE(SB(0, 0), Bt, bcol, t + 2);
;     BAR; WAIT_L(0); MMA(0, 1, At, B1); BAR;
;     LDA(At, 0, 1); STAGE(SA(0, 0), A, brow, t + 2);
;     BAR; WAIT_L(0); MMA(1, 0, At, B0); BAR; SCHED;
;     STAGE(SB(0, 1), Bt, bcol + HALF, t + 2);
;     WAIT_V(6); BAR; MMA(1, 1, At, B1); BAR;
;     LDB(B0, 1, 0); SCHED; LDA(At, 1, 0); STAGE(SA(0, 1), A, brow + HALF, t + 2);
;     WAIT_L(8); BAR; WAIT_L(0); MMA(0, 0, At, B0); BAR; SCHED;
.LBB0_1184:
	ds_read_b128 v[136:139], v170
	ds_read_b128 v[174:177], v170 offset:1024
	ds_read_b128 v[178:181], v170 offset:2048
	ds_read_b128 v[182:185], v170 offset:3072
	ds_read_b128 v[186:189], v162
	ds_read_b128 v[190:193], v162 offset:1024
	ds_read_b128 v[194:197], v161
	ds_read_b128 v[198:201], v161 offset:1024
	ds_read_b128 v[202:205], v160
	ds_read_b128 v[208:211], v160 offset:1024
	ds_read_b128 v[214:217], v159
	ds_read_b128 v[218:221], v159 offset:1024
	v_add_u32_e32 v171, 0xc000, v157
	v_lshl_add_u64 v[238:239], s[92:93], 0, v[148:149]
	v_readfirstlane_b32 s54, v171
	s_mov_b32 m0, s54
	v_lshl_add_u64 v[172:173], v[238:239], 0, s[86:87]
	global_load_lds_dwordx4 v[172:173], off
	v_add_u32_e32 v172, 0xe000, v157
	v_lshl_add_u64 v[240:241], s[92:93], 0, v[150:151]
	v_readfirstlane_b32 s54, v172
	s_mov_b32 m0, s54
	v_lshl_add_u64 v[222:223], v[240:241], 0, s[86:87]
	global_load_lds_dwordx4 v[222:223], off
	s_waitcnt lgkmcnt(8)
	s_barrier
	s_waitcnt lgkmcnt(0)
	s_waitcnt lgkmcnt(0)
	v_mfma_f32_16x16x32_bf16 v[124:127], v[136:139], v[186:189], v[124:127]
	v_mfma_f32_16x16x32_bf16 v[120:123], v[178:181], v[186:189], v[120:123]
	v_mfma_f32_16x16x32_bf16 v[116:119], v[136:139], v[194:197], v[116:119]
	v_mfma_f32_16x16x32_bf16 v[112:115], v[178:181], v[194:197], v[112:115]
	v_mfma_f32_16x16x32_bf16 v[108:111], v[136:139], v[202:205], v[108:111]
	v_mfma_f32_16x16x32_bf16 v[104:107], v[178:181], v[202:205], v[104:107]
	v_mfma_f32_16x16x32_bf16 v[100:103], v[136:139], v[214:217], v[100:103]
	v_mfma_f32_16x16x32_bf16 v[96:99], v[178:181], v[214:217], v[96:99]
	v_mfma_f32_16x16x32_bf16 v[124:127], v[174:177], v[190:193], v[124:127]
	v_mfma_f32_16x16x32_bf16 v[120:123], v[182:185], v[190:193], v[120:123]
	v_mfma_f32_16x16x32_bf16 v[116:119], v[174:177], v[198:201], v[116:119]
	v_mfma_f32_16x16x32_bf16 v[112:115], v[182:185], v[198:201], v[112:115]
	v_mfma_f32_16x16x32_bf16 v[108:111], v[174:177], v[208:211], v[108:111]
	v_mfma_f32_16x16x32_bf16 v[104:107], v[182:185], v[208:211], v[104:107]
	v_mfma_f32_16x16x32_bf16 v[100:103], v[174:177], v[218:221], v[100:103]
	v_mfma_f32_16x16x32_bf16 v[96:99], v[182:185], v[218:221], v[96:99]
	s_barrier
	ds_read_b128 v[222:225], v169
	ds_read_b128 v[226:229], v169 offset:1024
	ds_read_b128 v[230:233], v169 offset:2048
	ds_read_b128 v[234:237], v169 offset:3072
	v_lshl_add_u64 v[242:243], s[92:93], 0, v[144:145]
	v_readfirstlane_b32 s54, v156
	v_lshl_add_u64 v[244:245], v[242:243], 0, s[22:23]
	s_mov_b32 m0, s54
	v_add_u32_e32 v134, 0x2000, v156
	global_load_lds_dwordx4 v[244:245], off
	v_lshl_add_u64 v[244:245], s[92:93], 0, v[146:147]
	v_readfirstlane_b32 s54, v134
	s_mov_b32 m0, s54
	v_lshl_add_u64 v[246:247], v[244:245], 0, s[22:23]
	global_load_lds_dwordx4 v[246:247], off
	s_barrier
	s_waitcnt lgkmcnt(0)
	s_waitcnt lgkmcnt(0)
	v_mfma_f32_16x16x32_bf16 v[92:95], v[222:225], v[186:189], v[92:95]
	v_mfma_f32_16x16x32_bf16 v[88:91], v[230:233], v[186:189], v[88:91]
	v_mfma_f32_16x16x32_bf16 v[84:87], v[222:225], v[194:197], v[84:87]
	v_mfma_f32_16x16x32_bf16 v[80:83], v[230:233], v[194:197], v[80:83]
	v_mfma_f32_16x16x32_bf16 v[76:79], v[222:225], v[202:205], v[76:79]
	v_mfma_f32_16x16x32_bf16 v[72:75], v[230:233], v[202:205], v[72:75]
	v_mfma_f32_16x16x32_bf16 v[68:71], v[222:225], v[214:217], v[68:71]
	v_mfma_f32_16x16x32_bf16 v[64:67], v[230:233], v[214:217], v[64:67]
	v_mfma_f32_16x16x32_bf16 v[92:95], v[226:229], v[190:193], v[92:95]
	v_mfma_f32_16x16x32_bf16 v[88:91], v[234:237], v[190:193], v[88:91]
	v_mfma_f32_16x16x32_bf16 v[84:87], v[226:229], v[198:201], v[84:87]
	v_mfma_f32_16x16x32_bf16 v[80:83], v[234:237], v[198:201], v[80:83]
	v_mfma_f32_16x16x32_bf16 v[76:79], v[226:229], v[208:211], v[76:79]
	v_mfma_f32_16x16x32_bf16 v[72:75], v[234:237], v[208:211], v[72:75]
	v_mfma_f32_16x16x32_bf16 v[68:71], v[226:229], v[218:221], v[68:71]
	v_mfma_f32_16x16x32_bf16 v[64:67], v[234:237], v[218:221], v[64:67]
	v_readfirstlane_b32 s54, v157
	v_add_u32_e32 v134, 0x2000, v157
	v_lshl_add_u64 v[246:247], v[238:239], 0, s[34:35]
	s_mov_b32 m0, s54
	v_readfirstlane_b32 s54, v134
	s_barrier
	ds_read_b128 v[186:189], v162 offset:16384
	ds_read_b128 v[190:193], v162 offset:17408
	ds_read_b128 v[194:197], v161 offset:16384
	ds_read_b128 v[198:201], v161 offset:17408
	ds_read_b128 v[202:205], v160 offset:16384
	ds_read_b128 v[208:211], v160 offset:17408
	ds_read_b128 v[214:217], v159 offset:16384
	ds_read_b128 v[218:221], v159 offset:17408
	global_load_lds_dwordx4 v[246:247], off
	s_mov_b32 m0, s54
	v_lshl_add_u64 v[246:247], v[240:241], 0, s[34:35]
	global_load_lds_dwordx4 v[246:247], off
	s_barrier
	s_waitcnt lgkmcnt(0)
	s_waitcnt lgkmcnt(0)
	v_mfma_f32_16x16x32_bf16 v[60:63], v[136:139], v[186:189], v[60:63]
	v_mfma_f32_16x16x32_bf16 v[56:59], v[178:181], v[186:189], v[56:59]
	v_mfma_f32_16x16x32_bf16 v[52:55], v[136:139], v[194:197], v[52:55]
	v_mfma_f32_16x16x32_bf16 v[48:51], v[178:181], v[194:197], v[48:51]
	v_mfma_f32_16x16x32_bf16 v[44:47], v[136:139], v[202:205], v[44:47]
	v_mfma_f32_16x16x32_bf16 v[40:43], v[178:181], v[202:205], v[40:43]
	v_mfma_f32_16x16x32_bf16 v[36:39], v[136:139], v[214:217], v[36:39]
	v_mfma_f32_16x16x32_bf16 v[32:35], v[178:181], v[214:217], v[32:35]
	v_mfma_f32_16x16x32_bf16 v[60:63], v[174:177], v[190:193], v[60:63]
	v_mfma_f32_16x16x32_bf16 v[56:59], v[182:185], v[190:193], v[56:59]
	v_mfma_f32_16x16x32_bf16 v[52:55], v[174:177], v[198:201], v[52:55]
	v_mfma_f32_16x16x32_bf16 v[48:51], v[182:185], v[198:201], v[48:51]
	v_mfma_f32_16x16x32_bf16 v[44:47], v[174:177], v[208:211], v[44:47]
	v_mfma_f32_16x16x32_bf16 v[40:43], v[182:185], v[208:211], v[40:43]
	v_mfma_f32_16x16x32_bf16 v[36:39], v[174:177], v[218:221], v[36:39]
	v_mfma_f32_16x16x32_bf16 v[32:35], v[182:185], v[218:221], v[32:35]
	s_barrier
; #define STAGE(P, BASE, br, kt) STAGET(tid_, P, BASE, br, kt)
; #define LDA(dst, b, h) UFOR(m, 4) UFOR(k, 2) \
;     dst[m][k] = *reinterpret_cast<const bf16x8*>((char*)SA(b, h) + lds_byte(wr * 64 + m * 16 + fr, k * 32 + fq * 8))
; #define LDB(dst, b, h) UFOR(n, 2) UFOR(k, 2) \
;     dst[n][k] = *reinterpret_cast<const bf16x8*>((char*)SB(b, h) + lds_byte(wc * 32 + n * 16 + fr, k * 32 + fq * 8))
; #define MMA(ai, bj, At, Bq) do { __builtin_amdgcn_s_setprio(1); \
;     UFOR(m, 4) UFOR(n, 2) UFOR(k, 2) \
;       acc[ai][bj][m][n] = __builtin_amdgcn_mfma_f32_16x16x32_bf16(Bq[n][k], At[m][k], acc[ai][bj][m][n], 0, 0, 0); \
;     __builtin_amdgcn_s_setprio(0); } while (0)
; #define WAIT_V(n) asm volatile("s_waitcnt vmcnt(" #n ")" ::: "memory")
; #define WAIT_L(n) asm volatile("s_waitcnt lgkmcnt(" #n ")" ::: "memory")
; #define BAR __builtin_amdgcn_s_barrier()
; #define SCHED __builtin_amdgcn_sched_barrier(0)
; template <int EPI, int K, int KL> ...
;     ...
;     STAGE(SB(0, 1), Bt, bcol + HALF, t + 2);
;     WAIT_V(6); BAR; MMA(1, 1, At, B1); BAR;
;     LDB(B0, 1, 0); SCHED; LDA(At, 1, 0); STAGE(SA(0, 1), A, brow + HALF, t + 2);
;     WAIT_L(8); BAR; WAIT_L(0); MMA(0, 0, At, B0); BAR; SCHED;
;     LDB(B1, 1, 1); STAGE(SB(1, 0), Bt, bcol, t + 3);
;     BAR; WAIT_L(0); MMA(0, 1, At, B1); BAR;
;     LDA(At, 1, 1); STAGE(SA(1, 0), A, brow, t + 3);
;     BAR; WAIT_L(0); MMA(1, 0, At, B0); BAR; SCHED;
;     STAGE(SB(1, 1), Bt, bcol + HALF, t + 3);
	v_readfirstlane_b32 s54, v158
	v_add_u32_e32 v134, 0x2000, v158
	v_lshl_add_u64 v[136:137], v[242:243], 0, s[24:25]
	s_mov_b32 m0, s54
	v_readfirstlane_b32 s54, v134
	global_load_lds_dwordx4 v[136:137], off
	s_mov_b32 m0, s54
	v_lshl_add_u64 v[136:137], v[244:245], 0, s[24:25]
	global_load_lds_dwordx4 v[136:137], off
	s_waitcnt vmcnt(6)
	s_barrier
	v_mfma_f32_16x16x32_bf16 v[28:31], v[222:225], v[186:189], v[28:31]
	v_mfma_f32_16x16x32_bf16 v[24:27], v[230:233], v[186:189], v[24:27]
	v_mfma_f32_16x16x32_bf16 v[20:23], v[222:225], v[194:197], v[20:23]
	v_mfma_f32_16x16x32_bf16 v[16:19], v[230:233], v[194:197], v[16:19]
	v_mfma_f32_16x16x32_bf16 v[12:15], v[222:225], v[202:205], v[12:15]
	v_mfma_f32_16x16x32_bf16 v[8:11], v[230:233], v[202:205], v[8:11]
	v_mfma_f32_16x16x32_bf16 v[4:7], v[222:225], v[214:217], v[4:7]
	v_mfma_f32_16x16x32_bf16 v[0:3], v[230:233], v[214:217], v[0:3]
	v_mfma_f32_16x16x32_bf16 v[28:31], v[226:229], v[190:193], v[28:31]
	v_mfma_f32_16x16x32_bf16 v[24:27], v[234:237], v[190:193], v[24:27]
	v_mfma_f32_16x16x32_bf16 v[20:23], v[226:229], v[198:201], v[20:23]
	v_mfma_f32_16x16x32_bf16 v[16:19], v[234:237], v[198:201], v[16:19]
	v_mfma_f32_16x16x32_bf16 v[12:15], v[226:229], v[208:211], v[12:15]
	v_mfma_f32_16x16x32_bf16 v[8:11], v[234:237], v[208:211], v[8:11]
	v_mfma_f32_16x16x32_bf16 v[4:7], v[226:229], v[218:221], v[4:7]
	v_mfma_f32_16x16x32_bf16 v[0:3], v[234:237], v[218:221], v[0:3]
	s_barrier
	ds_read_b128 v[136:139], v165
	ds_read_b128 v[174:177], v165 offset:1024
	ds_read_b128 v[178:181], v165 offset:2048
	ds_read_b128 v[182:185], v165 offset:3072
	ds_read_b128 v[186:189], v162 offset:32768
	ds_read_b128 v[190:193], v162 offset:33792
	ds_read_b128 v[194:197], v161 offset:32768
	ds_read_b128 v[198:201], v161 offset:33792
	ds_read_b128 v[202:205], v160 offset:32768
	ds_read_b128 v[208:211], v160 offset:33792
	ds_read_b128 v[214:217], v159 offset:32768
	ds_read_b128 v[218:221], v159 offset:33792
	v_add_u32_e32 v134, 0x4000, v157
	v_lshl_add_u64 v[222:223], v[238:239], 0, s[28:29]
	v_readfirstlane_b32 s54, v134
	v_add_u32_e32 v134, 0x6000, v157
	s_mov_b32 m0, s54
	v_readfirstlane_b32 s54, v134
	global_load_lds_dwordx4 v[222:223], off
	s_mov_b32 m0, s54
	v_lshl_add_u64 v[222:223], v[240:241], 0, s[28:29]
	global_load_lds_dwordx4 v[222:223], off
	s_waitcnt lgkmcnt(8)
	s_barrier
	s_waitcnt lgkmcnt(0)
	s_waitcnt lgkmcnt(0)
	v_mfma_f32_16x16x32_bf16 v[124:127], v[136:139], v[186:189], v[124:127]
	v_mfma_f32_16x16x32_bf16 v[120:123], v[178:181], v[186:189], v[120:123]
	v_mfma_f32_16x16x32_bf16 v[116:119], v[136:139], v[194:197], v[116:119]
	v_mfma_f32_16x16x32_bf16 v[112:115], v[178:181], v[194:197], v[112:115]
	v_mfma_f32_16x16x32_bf16 v[108:111], v[136:139], v[202:205], v[108:111]
	v_mfma_f32_16x16x32_bf16 v[104:107], v[178:181], v[202:205], v[104:107]
	v_mfma_f32_16x16x32_bf16 v[100:103], v[136:139], v[214:217], v[100:103]
	v_mfma_f32_16x16x32_bf16 v[96:99], v[178:181], v[214:217], v[96:99]
	v_mfma_f32_16x16x32_bf16 v[124:127], v[174:177], v[190:193], v[124:127]
	v_mfma_f32_16x16x32_bf16 v[120:123], v[182:185], v[190:193], v[120:123]
	v_mfma_f32_16x16x32_bf16 v[116:119], v[174:177], v[198:201], v[116:119]
	v_mfma_f32_16x16x32_bf16 v[112:115], v[182:185], v[198:201], v[112:115]
	v_mfma_f32_16x16x32_bf16 v[108:111], v[174:177], v[208:211], v[108:111]
	v_mfma_f32_16x16x32_bf16 v[104:107], v[182:185], v[208:211], v[104:107]
	v_mfma_f32_16x16x32_bf16 v[100:103], v[174:177], v[218:221], v[100:103]
	v_mfma_f32_16x16x32_bf16 v[96:99], v[182:185], v[218:221], v[96:99]
	s_barrier
	ds_read_b128 v[222:225], v163
	ds_read_b128 v[226:229], v163 offset:1024
	ds_read_b128 v[230:233], v163 offset:2048
	ds_read_b128 v[234:237], v163 offset:3072
	v_readfirstlane_b32 s54, v164
	v_add_u32_e32 v134, 0x2000, v164
	v_lshl_add_u64 v[246:247], v[242:243], 0, s[94:95]
	s_mov_b32 m0, s54
	v_readfirstlane_b32 s54, v134
	global_load_lds_dwordx4 v[246:247], off
	s_mov_b32 m0, s54
	v_lshl_add_u64 v[246:247], v[244:245], 0, s[94:95]
	global_load_lds_dwordx4 v[246:247], off
	s_barrier
	s_waitcnt lgkmcnt(0)
	s_waitcnt lgkmcnt(0)
	v_mfma_f32_16x16x32_bf16 v[92:95], v[222:225], v[186:189], v[92:95]
	v_mfma_f32_16x16x32_bf16 v[88:91], v[230:233], v[186:189], v[88:91]
	v_mfma_f32_16x16x32_bf16 v[84:87], v[222:225], v[194:197], v[84:87]
	v_mfma_f32_16x16x32_bf16 v[80:83], v[230:233], v[194:197], v[80:83]
	v_mfma_f32_16x16x32_bf16 v[76:79], v[222:225], v[202:205], v[76:79]
	v_mfma_f32_16x16x32_bf16 v[72:75], v[230:233], v[202:205], v[72:75]
	v_mfma_f32_16x16x32_bf16 v[68:71], v[222:225], v[214:217], v[68:71]
	v_mfma_f32_16x16x32_bf16 v[64:67], v[230:233], v[214:217], v[64:67]
	v_mfma_f32_16x16x32_bf16 v[92:95], v[226:229], v[190:193], v[92:95]
	v_mfma_f32_16x16x32_bf16 v[88:91], v[234:237], v[190:193], v[88:91]
	v_mfma_f32_16x16x32_bf16 v[84:87], v[226:229], v[198:201], v[84:87]
	v_mfma_f32_16x16x32_bf16 v[80:83], v[234:237], v[198:201], v[80:83]
	v_mfma_f32_16x16x32_bf16 v[76:79], v[226:229], v[208:211], v[76:79]
	v_mfma_f32_16x16x32_bf16 v[72:75], v[234:237], v[208:211], v[72:75]
	v_mfma_f32_16x16x32_bf16 v[68:71], v[226:229], v[218:221], v[68:71]
	v_mfma_f32_16x16x32_bf16 v[64:67], v[234:237], v[218:221], v[64:67]
	v_readfirstlane_b32 s54, v166
	v_lshl_add_u64 v[238:239], v[238:239], 0, s[4:5]
	s_mov_b32 m0, s54
	v_readfirstlane_b32 s54, v167
	s_barrier
	ds_read_b128 v[186:189], v162 offset:49152
	ds_read_b128 v[190:193], v162 offset:50176
	ds_read_b128 v[194:197], v161 offset:49152
	ds_read_b128 v[198:201], v161 offset:50176
	ds_read_b128 v[202:205], v160 offset:49152
	ds_read_b128 v[208:211], v160 offset:50176
	ds_read_b128 v[214:217], v159 offset:49152
	ds_read_b128 v[218:221], v159 offset:50176
	global_load_lds_dwordx4 v[238:239], off
	s_mov_b32 m0, s54
	v_lshl_add_u64 v[238:239], v[240:241], 0, s[4:5]
	global_load_lds_dwordx4 v[238:239], off
	s_barrier
; #define STAGE(P, BASE, br, kt) STAGET(tid_, P, BASE, br, kt)
; #define LDA(dst, b, h) UFOR(m, 4) UFOR(k, 2) \
;     dst[m][k] = *reinterpret_cast<const bf16x8*>((char*)SA(b, h) + lds_byte(wr * 64 + m * 16 + fr, k * 32 + fq * 8))
; #define LDB(dst, b, h) UFOR(n, 2) UFOR(k, 2) \
;     dst[n][k] = *reinterpret_cast<const bf16x8*>((char*)SB(b, h) + lds_byte(wc * 32 + n * 16 + fr, k * 32 + fq * 8))
; #define MMA(ai, bj, At, Bq) do { __builtin_amdgcn_s_setprio(1); \
;     UFOR(m, 4) UFOR(n, 2) UFOR(k, 2) \
;       acc[ai][bj][m][n] = __builtin_amdgcn_mfma_f32_16x16x32_bf16(Bq[n][k], At[m][k], acc[ai][bj][m][n], 0, 0, 0); \
;     __builtin_amdgcn_s_setprio(0); } while (0)
; #define WAIT_V(n) asm volatile("s_waitcnt vmcnt(" #n ")" ::: "memory")
; #define WAIT_L(n) asm volatile("s_waitcnt lgkmcnt(" #n ")" ::: "memory")
; #define BAR __builtin_amdgcn_s_barrier()
; template <int EPI, int K, int KL> ...
;     ...
;     STAGE(SB(1, 1), Bt, bcol + HALF, t + 3);
;     WAIT_V(6); BAR; MMA(1, 1, At, B1); BAR;
;   }
;   { LDB(B0, 0, 0); LDA(At, 0, 0); STAGE(SA(1, 1), A, brow + HALF, nt - 1);
;     BAR; WAIT_L(0); MMA(0, 0, At, B0); BAR;
;     LDB(B1, 0, 1); BAR; WAIT_L(0); MMA(0, 1, At, B1); BAR;
;     LDA(At, 0, 1); WAIT_V(4); BAR; WAIT_L(0); MMA(1, 0, At, B0); MMA(1, 1, At, B1); BAR; }
	s_waitcnt lgkmcnt(0)
	s_waitcnt lgkmcnt(0)
	v_mfma_f32_16x16x32_bf16 v[60:63], v[136:139], v[186:189], v[60:63]
	v_mfma_f32_16x16x32_bf16 v[56:59], v[178:181], v[186:189], v[56:59]
	v_mfma_f32_16x16x32_bf16 v[52:55], v[136:139], v[194:197], v[52:55]
	v_mfma_f32_16x16x32_bf16 v[48:51], v[178:181], v[194:197], v[48:51]
	v_mfma_f32_16x16x32_bf16 v[44:47], v[136:139], v[202:205], v[44:47]
	v_mfma_f32_16x16x32_bf16 v[40:43], v[178:181], v[202:205], v[40:43]
	v_mfma_f32_16x16x32_bf16 v[36:39], v[136:139], v[214:217], v[36:39]
	v_mfma_f32_16x16x32_bf16 v[32:35], v[178:181], v[214:217], v[32:35]
	v_mfma_f32_16x16x32_bf16 v[60:63], v[174:177], v[190:193], v[60:63]
	v_mfma_f32_16x16x32_bf16 v[56:59], v[182:185], v[190:193], v[56:59]
	v_mfma_f32_16x16x32_bf16 v[52:55], v[174:177], v[198:201], v[52:55]
	v_mfma_f32_16x16x32_bf16 v[48:51], v[182:185], v[198:201], v[48:51]
	v_mfma_f32_16x16x32_bf16 v[44:47], v[174:177], v[208:211], v[44:47]
	v_mfma_f32_16x16x32_bf16 v[40:43], v[182:185], v[208:211], v[40:43]
	v_mfma_f32_16x16x32_bf16 v[36:39], v[174:177], v[218:221], v[36:39]
	v_mfma_f32_16x16x32_bf16 v[32:35], v[182:185], v[218:221], v[32:35]
	s_barrier
	v_readfirstlane_b32 s54, v168
	v_add_u32_e32 v134, 0x2000, v168
	v_lshl_add_u64 v[136:137], v[242:243], 0, s[10:11]
	s_mov_b32 m0, s54
	v_readfirstlane_b32 s54, v134
	global_load_lds_dwordx4 v[136:137], off
	s_mov_b32 m0, s54
	v_lshl_add_u64 v[136:137], v[244:245], 0, s[10:11]
	global_load_lds_dwordx4 v[136:137], off
	s_waitcnt vmcnt(6)
	s_barrier
	v_mfma_f32_16x16x32_bf16 v[28:31], v[222:225], v[186:189], v[28:31]
	v_mfma_f32_16x16x32_bf16 v[24:27], v[230:233], v[186:189], v[24:27]
	v_mfma_f32_16x16x32_bf16 v[20:23], v[222:225], v[194:197], v[20:23]
	v_mfma_f32_16x16x32_bf16 v[16:19], v[230:233], v[194:197], v[16:19]
	v_mfma_f32_16x16x32_bf16 v[12:15], v[222:225], v[202:205], v[12:15]
	v_mfma_f32_16x16x32_bf16 v[8:11], v[230:233], v[202:205], v[8:11]
	v_mfma_f32_16x16x32_bf16 v[4:7], v[222:225], v[214:217], v[4:7]
	v_mfma_f32_16x16x32_bf16 v[0:3], v[230:233], v[214:217], v[0:3]
	v_mfma_f32_16x16x32_bf16 v[28:31], v[226:229], v[190:193], v[28:31]
	v_mfma_f32_16x16x32_bf16 v[24:27], v[234:237], v[190:193], v[24:27]
	v_mfma_f32_16x16x32_bf16 v[20:23], v[226:229], v[198:201], v[20:23]
	v_mfma_f32_16x16x32_bf16 v[16:19], v[234:237], v[198:201], v[16:19]
	v_mfma_f32_16x16x32_bf16 v[12:15], v[226:229], v[208:211], v[12:15]
	v_mfma_f32_16x16x32_bf16 v[8:11], v[234:237], v[208:211], v[8:11]
	v_mfma_f32_16x16x32_bf16 v[4:7], v[226:229], v[218:221], v[4:7]
	v_mfma_f32_16x16x32_bf16 v[0:3], v[234:237], v[218:221], v[0:3]
	s_add_i32 s19, s19, 2
	v_lshl_add_u64 v[144:145], v[144:145], 0, s[20:21]
	v_lshl_add_u64 v[146:147], v[146:147], 0, s[20:21]
	v_lshl_add_u64 v[148:149], v[148:149], 0, s[20:21]
	s_cmpk_lt_u32 s19, 0x54
	v_lshl_add_u64 v[150:151], v[150:151], 0, s[20:21]
	s_cbranch_scc1 .Lkrot_1184
	s_barrier
	s_add_u32 s52, s52, 0x162b80
	s_addc_u32 s53, s53, 0
	v_lshl_add_u64 v[130:131], s[52:53], 0, v[130:131]
	v_readfirstlane_b32 s19, v171
	v_lshl_add_u64 v[128:129], v[128:129], 1, v[130:131]
	s_mov_b32 m0, s19
	ds_read_b128 v[136:139], v170
	ds_read_b128 v[144:147], v170 offset:1024
	ds_read_b128 v[148:151], v170 offset:2048
	ds_read_b128 v[174:177], v170 offset:3072
	ds_read_b128 v[178:181], v162
	ds_read_b128 v[182:185], v162 offset:1024
	ds_read_b128 v[186:189], v161
	ds_read_b128 v[190:193], v161 offset:1024
	ds_read_b128 v[194:197], v160
	ds_read_b128 v[198:201], v160 offset:1024
	ds_read_b128 v[202:205], v159
	ds_read_b128 v[208:211], v159 offset:1024
	global_load_lds_dwordx4 v[128:129], off
	v_lshl_add_u64 v[128:129], s[52:53], 0, v[142:143]
	v_readfirstlane_b32 s19, v172
	v_lshl_add_u64 v[128:129], v[140:141], 1, v[128:129]
	s_mov_b32 m0, s19
	s_nop 0
	global_load_lds_dwordx4 v[128:129], off
	s_barrier
	s_waitcnt lgkmcnt(0)
	s_waitcnt lgkmcnt(0)
	v_mfma_f32_16x16x32_bf16 v[120:123], v[148:151], v[178:181], v[120:123]
	v_mfma_f32_16x16x32_bf16 v[116:119], v[136:139], v[186:189], v[116:119]
	v_mfma_f32_16x16x32_bf16 v[112:115], v[148:151], v[186:189], v[112:115]
	v_mfma_f32_16x16x32_bf16 v[108:111], v[136:139], v[194:197], v[108:111]
	v_mfma_f32_16x16x32_bf16 v[104:107], v[148:151], v[194:197], v[104:107]
	v_mfma_f32_16x16x32_bf16 v[100:103], v[136:139], v[202:205], v[100:103]
	v_mfma_f32_16x16x32_bf16 v[96:99], v[148:151], v[202:205], v[96:99]
	v_mfma_f32_16x16x32_bf16 v[124:127], v[136:139], v[178:181], v[124:127]
	v_mfma_f32_16x16x32_bf16 v[120:123], v[174:177], v[182:185], v[120:123]
	v_mfma_f32_16x16x32_bf16 v[116:119], v[144:147], v[190:193], v[116:119]
	v_mfma_f32_16x16x32_bf16 v[112:115], v[174:177], v[190:193], v[112:115]
	v_mfma_f32_16x16x32_bf16 v[108:111], v[144:147], v[198:201], v[108:111]
	v_mfma_f32_16x16x32_bf16 v[104:107], v[174:177], v[198:201], v[104:107]
	v_mfma_f32_16x16x32_bf16 v[100:103], v[144:147], v[208:211], v[100:103]
	v_mfma_f32_16x16x32_bf16 v[96:99], v[174:177], v[208:211], v[96:99]
	v_mfma_f32_16x16x32_bf16 v[124:127], v[144:147], v[182:185], v[124:127]
	s_barrier
	ds_read_b128 v[128:131], v169
	ds_read_b128 v[140:143], v169 offset:1024
	ds_read_b128 v[170:173], v169 offset:2048
	ds_read_b128 v[166:169], v169 offset:3072
	s_barrier
; #define LDA(dst, b, h) UFOR(m, 4) UFOR(k, 2) \
;     dst[m][k] = *reinterpret_cast<const bf16x8*>((char*)SA(b, h) + lds_byte(wr * 64 + m * 16 + fr, k * 32 + fq * 8))
; #define LDB(dst, b, h) UFOR(n, 2) UFOR(k, 2) \
;     dst[n][k] = *reinterpret_cast<const bf16x8*>((char*)SB(b, h) + lds_byte(wc * 32 + n * 16 + fr, k * 32 + fq * 8))
; #define MMA(ai, bj, At, Bq) do { __builtin_amdgcn_s_setprio(1); \
;     UFOR(m, 4) UFOR(n, 2) UFOR(k, 2) \
;       acc[ai][bj][m][n] = __builtin_amdgcn_mfma_f32_16x16x32_bf16(Bq[n][k], At[m][k], acc[ai][bj][m][n], 0, 0, 0); \
;     __builtin_amdgcn_s_setprio(0); } while (0)
; #define WAIT_V(n) asm volatile("s_waitcnt vmcnt(" #n ")" ::: "memory")
; #define WAIT_L(n) asm volatile("s_waitcnt lgkmcnt(" #n ")" ::: "memory")
; #define BAR __builtin_amdgcn_s_barrier()
; template <int EPI, int K, int KL> ...
;     ...
;     LDB(B1, 0, 1); BAR; WAIT_L(0); MMA(0, 1, At, B1); BAR;
;     LDA(At, 0, 1); WAIT_V(4); BAR; WAIT_L(0); MMA(1, 0, At, B0); MMA(1, 1, At, B1); BAR; }
;   { LDB(B0, 1, 0); LDA(At, 1, 0); WAIT_V(2); BAR; WAIT_L(0); MMA(0, 0, At, B0); BAR;
	s_waitcnt lgkmcnt(0)
	s_waitcnt lgkmcnt(0)
	v_mfma_f32_16x16x32_bf16 v[80:83], v[170:173], v[186:189], v[80:83]
	v_mfma_f32_16x16x32_bf16 v[76:79], v[128:131], v[194:197], v[76:79]
	v_mfma_f32_16x16x32_bf16 v[68:71], v[128:131], v[202:205], v[68:71]
	v_mfma_f32_16x16x32_bf16 v[64:67], v[170:173], v[202:205], v[64:67]
	v_mfma_f32_16x16x32_bf16 v[92:95], v[128:131], v[178:181], v[92:95]
	v_mfma_f32_16x16x32_bf16 v[88:91], v[170:173], v[178:181], v[88:91]
	v_mfma_f32_16x16x32_bf16 v[84:87], v[128:131], v[186:189], v[84:87]
	v_mfma_f32_16x16x32_bf16 v[80:83], v[166:169], v[190:193], v[80:83]
	v_mfma_f32_16x16x32_bf16 v[76:79], v[140:143], v[198:201], v[76:79]
	v_mfma_f32_16x16x32_bf16 v[72:75], v[170:173], v[194:197], v[72:75]
	v_mfma_f32_16x16x32_bf16 v[68:71], v[140:143], v[208:211], v[68:71]
	v_mfma_f32_16x16x32_bf16 v[64:67], v[166:169], v[208:211], v[64:67]
	v_mfma_f32_16x16x32_bf16 v[214:217], v[140:143], v[182:185], v[92:95]
	v_mfma_f32_16x16x32_bf16 v[178:181], v[166:169], v[182:185], v[88:91]
	v_mfma_f32_16x16x32_bf16 v[182:185], v[140:143], v[190:193], v[84:87]
	v_mfma_f32_16x16x32_bf16 v[186:189], v[166:169], v[198:201], v[72:75]
	s_barrier
	s_nop 0
	ds_read_b128 v[72:75], v162 offset:16384
	ds_read_b128 v[84:87], v162 offset:17408
	ds_read_b128 v[88:91], v161 offset:16384
	ds_read_b128 v[92:95], v161 offset:17408
	ds_read_b128 v[190:193], v160 offset:16384
	ds_read_b128 v[194:197], v160 offset:17408
	ds_read_b128 v[198:201], v159 offset:16384
	ds_read_b128 v[202:205], v159 offset:17408
	s_waitcnt vmcnt(4)
	s_barrier
	s_waitcnt lgkmcnt(0)
	s_waitcnt lgkmcnt(0)
	v_mfma_f32_16x16x32_bf16 v[48:51], v[148:151], v[88:91], v[48:51]
	v_mfma_f32_16x16x32_bf16 v[40:43], v[148:151], v[190:193], v[40:43]
	v_mfma_f32_16x16x32_bf16 v[36:39], v[136:139], v[198:201], v[36:39]
	v_mfma_f32_16x16x32_bf16 v[32:35], v[148:151], v[198:201], v[32:35]
	v_mfma_f32_16x16x32_bf16 v[60:63], v[136:139], v[72:75], v[60:63]
	v_mfma_f32_16x16x32_bf16 v[56:59], v[148:151], v[72:75], v[56:59]
	v_mfma_f32_16x16x32_bf16 v[52:55], v[136:139], v[88:91], v[52:55]
	v_mfma_f32_16x16x32_bf16 v[48:51], v[174:177], v[92:95], v[48:51]
	v_mfma_f32_16x16x32_bf16 v[44:47], v[136:139], v[190:193], v[44:47]
	v_mfma_f32_16x16x32_bf16 v[40:43], v[174:177], v[194:197], v[40:43]
	v_mfma_f32_16x16x32_bf16 v[36:39], v[144:147], v[202:205], v[36:39]
	v_mfma_f32_16x16x32_bf16 v[32:35], v[174:177], v[202:205], v[32:35]
	v_mfma_f32_16x16x32_bf16 v[208:211], v[144:147], v[84:87], v[60:63]
	v_mfma_f32_16x16x32_bf16 v[218:221], v[174:177], v[84:87], v[56:59]
	v_mfma_f32_16x16x32_bf16 v[222:225], v[144:147], v[92:95], v[52:55]
	v_mfma_f32_16x16x32_bf16 v[226:229], v[144:147], v[194:197], v[44:47]
	v_mfma_f32_16x16x32_bf16 v[0:3], v[170:173], v[198:201], v[0:3]
	v_mfma_f32_16x16x32_bf16 v[28:31], v[128:131], v[72:75], v[28:31]
	v_mfma_f32_16x16x32_bf16 v[24:27], v[170:173], v[72:75], v[24:27]
	v_mfma_f32_16x16x32_bf16 v[20:23], v[128:131], v[88:91], v[20:23]
	v_mfma_f32_16x16x32_bf16 v[16:19], v[170:173], v[88:91], v[16:19]
	v_mfma_f32_16x16x32_bf16 v[12:15], v[128:131], v[190:193], v[12:15]
	v_mfma_f32_16x16x32_bf16 v[8:11], v[170:173], v[190:193], v[8:11]
	v_mfma_f32_16x16x32_bf16 v[4:7], v[128:131], v[198:201], v[4:7]
	v_mfma_f32_16x16x32_bf16 v[0:3], v[166:169], v[202:205], v[0:3]
	v_mfma_f32_16x16x32_bf16 v[136:139], v[140:143], v[84:87], v[28:31]
	v_mfma_f32_16x16x32_bf16 v[144:147], v[166:169], v[84:87], v[24:27]
	v_mfma_f32_16x16x32_bf16 v[148:151], v[140:143], v[92:95], v[20:23]
	v_mfma_f32_16x16x32_bf16 v[174:177], v[166:169], v[92:95], v[16:19]
	v_mfma_f32_16x16x32_bf16 v[230:233], v[140:143], v[194:197], v[12:15]
	v_mfma_f32_16x16x32_bf16 v[190:193], v[166:169], v[194:197], v[8:11]
	v_mfma_f32_16x16x32_bf16 v[140:143], v[140:143], v[202:205], v[4:7]
	s_barrier
	s_nop 0
	ds_read_b128 v[4:7], v165
	ds_read_b128 v[8:11], v165 offset:1024
	ds_read_b128 v[16:19], v165 offset:2048
	ds_read_b128 v[164:167], v165 offset:3072
	ds_read_b128 v[12:15], v162 offset:32768
	ds_read_b128 v[20:23], v162 offset:33792
	ds_read_b128 v[24:27], v161 offset:32768
	ds_read_b128 v[44:47], v161 offset:33792
	ds_read_b128 v[168:171], v160 offset:32768
	ds_read_b128 v[194:197], v160 offset:33792
	ds_read_b128 v[198:201], v159 offset:32768
	ds_read_b128 v[202:205], v159 offset:33792
	s_waitcnt vmcnt(2)
	s_barrier
; #define LDA(dst, b, h) UFOR(m, 4) UFOR(k, 2) \
;     dst[m][k] = *reinterpret_cast<const bf16x8*>((char*)SA(b, h) + lds_byte(wr * 64 + m * 16 + fr, k * 32 + fq * 8))
; #define LDB(dst, b, h) UFOR(n, 2) UFOR(k, 2) \
;     dst[n][k] = *reinterpret_cast<const bf16x8*>((char*)SB(b, h) + lds_byte(wc * 32 + n * 16 + fr, k * 32 + fq * 8))
; #define MMA(ai, bj, At, Bq) do { __builtin_amdgcn_s_setprio(1); \
;     UFOR(m, 4) UFOR(n, 2) UFOR(k, 2) \
;       acc[ai][bj][m][n] = __builtin_amdgcn_mfma_f32_16x16x32_bf16(Bq[n][k], At[m][k], acc[ai][bj][m][n], 0, 0, 0); \
;     __builtin_amdgcn_s_setprio(0); } while (0)
; #define WAIT_V(n) asm volatile("s_waitcnt vmcnt(" #n ")" ::: "memory")
; #define WAIT_L(n) asm volatile("s_waitcnt lgkmcnt(" #n ")" ::: "memory")
; #define BAR __builtin_amdgcn_s_barrier()
; template <int EPI, int K, int KL> ...
;     ...
;   { LDB(B0, 1, 0); LDA(At, 1, 0); WAIT_V(2); BAR; WAIT_L(0); MMA(0, 0, At, B0); BAR;
;     LDB(B1, 1, 1); WAIT_V(0); BAR; WAIT_L(0); MMA(0, 1, At, B1); BAR;
;     LDA(At, 1, 1); BAR; WAIT_L(0); MMA(1, 0, At, B0); MMA(1, 1, At, B1); BAR; }
;   if (wr == 0) BAR;
;   if (EPI != EPI_UPG && EPI != EPI_PART && has_next) {
	s_waitcnt lgkmcnt(0)
	s_waitcnt lgkmcnt(0)
	v_mfma_f32_16x16x32_bf16 v[28:31], v[4:7], v[12:15], v[124:127]
	v_mfma_f32_16x16x32_bf16 v[128:131], v[8:11], v[20:23], v[28:31]
	v_mfma_f32_16x16x32_bf16 v[28:31], v[16:19], v[12:15], v[120:123]
	v_mfma_f32_16x16x32_bf16 v[92:95], v[164:167], v[20:23], v[28:31]
	v_mfma_f32_16x16x32_bf16 v[28:31], v[4:7], v[24:27], v[116:119]
	v_mfma_f32_16x16x32_bf16 v[120:123], v[8:11], v[44:47], v[28:31]
	v_mfma_f32_16x16x32_bf16 v[28:31], v[16:19], v[24:27], v[112:115]
	v_mfma_f32_16x16x32_bf16 v[88:91], v[164:167], v[44:47], v[28:31]
	v_mfma_f32_16x16x32_bf16 v[28:31], v[4:7], v[168:171], v[108:111]
	v_mfma_f32_16x16x32_bf16 v[116:119], v[8:11], v[194:197], v[28:31]
	v_mfma_f32_16x16x32_bf16 v[28:31], v[16:19], v[168:171], v[104:107]
	v_mfma_f32_16x16x32_bf16 v[84:87], v[164:167], v[194:197], v[28:31]
	v_mfma_f32_16x16x32_bf16 v[28:31], v[4:7], v[198:201], v[100:103]
	v_mfma_f32_16x16x32_bf16 v[108:111], v[8:11], v[202:205], v[28:31]
	v_mfma_f32_16x16x32_bf16 v[28:31], v[16:19], v[198:201], v[96:99]
	v_mfma_f32_16x16x32_bf16 v[72:75], v[164:167], v[202:205], v[28:31]
	s_barrier
	ds_read_b128 v[124:127], v163
	ds_read_b128 v[234:237], v163 offset:1024
	ds_read_b128 v[238:241], v163 offset:2048
	ds_read_b128 v[242:245], v163 offset:3072
	s_waitcnt vmcnt(0)
	s_barrier
	s_waitcnt lgkmcnt(0)
	s_waitcnt lgkmcnt(0)
	v_mfma_f32_16x16x32_bf16 v[28:31], v[124:127], v[12:15], v[214:217]
	v_mfma_f32_16x16x32_bf16 v[12:15], v[238:241], v[12:15], v[178:181]
	v_mfma_f32_16x16x32_bf16 v[60:63], v[234:237], v[20:23], v[28:31]
	v_mfma_f32_16x16x32_bf16 v[28:31], v[242:245], v[20:23], v[12:15]
	v_mfma_f32_16x16x32_bf16 v[12:15], v[124:127], v[24:27], v[182:185]
	v_mfma_f32_16x16x32_bf16 v[56:59], v[234:237], v[44:47], v[12:15]
	v_mfma_f32_16x16x32_bf16 v[12:15], v[238:241], v[24:27], v[80:83]
	v_mfma_f32_16x16x32_bf16 v[24:27], v[242:245], v[44:47], v[12:15]
	v_mfma_f32_16x16x32_bf16 v[12:15], v[124:127], v[168:171], v[76:79]
	v_mfma_f32_16x16x32_bf16 v[52:55], v[234:237], v[194:197], v[12:15]
	v_mfma_f32_16x16x32_bf16 v[12:15], v[238:241], v[168:171], v[186:189]
	v_mfma_f32_16x16x32_bf16 v[20:23], v[242:245], v[194:197], v[12:15]
	v_mfma_f32_16x16x32_bf16 v[12:15], v[124:127], v[198:201], v[68:71]
	v_mfma_f32_16x16x32_bf16 v[44:47], v[234:237], v[202:205], v[12:15]
	v_mfma_f32_16x16x32_bf16 v[12:15], v[238:241], v[198:201], v[64:67]
	v_mfma_f32_16x16x32_bf16 v[12:15], v[242:245], v[202:205], v[12:15]
	s_barrier
	ds_read_b128 v[168:171], v162 offset:49152
	ds_read_b128 v[178:181], v162 offset:50176
	ds_read_b128 v[182:185], v161 offset:49152
	ds_read_b128 v[186:189], v161 offset:50176
	ds_read_b128 v[194:197], v160 offset:49152
	ds_read_b128 v[160:163], v160 offset:50176
	ds_read_b128 v[198:201], v159 offset:49152
	ds_read_b128 v[156:159], v159 offset:50176
	s_barrier
	s_waitcnt lgkmcnt(0)
	s_waitcnt lgkmcnt(0)
	v_mfma_f32_16x16x32_bf16 v[64:67], v[4:7], v[168:171], v[208:211]
	v_mfma_f32_16x16x32_bf16 v[112:115], v[8:11], v[178:181], v[64:67]
	v_mfma_f32_16x16x32_bf16 v[64:67], v[16:19], v[168:171], v[218:221]
	v_mfma_f32_16x16x32_bf16 v[48:51], v[16:19], v[182:185], v[48:51]
	v_mfma_f32_16x16x32_bf16 v[80:83], v[164:167], v[178:181], v[64:67]
	v_mfma_f32_16x16x32_bf16 v[64:67], v[4:7], v[182:185], v[222:225]
	v_mfma_f32_16x16x32_bf16 v[76:79], v[164:167], v[186:189], v[48:51]
	v_mfma_f32_16x16x32_bf16 v[48:51], v[4:7], v[194:197], v[226:229]
	v_mfma_f32_16x16x32_bf16 v[4:7], v[4:7], v[198:201], v[36:39]
	v_mfma_f32_16x16x32_bf16 v[40:43], v[16:19], v[194:197], v[40:43]
	v_mfma_f32_16x16x32_bf16 v[96:99], v[8:11], v[156:159], v[4:7]
	v_mfma_f32_16x16x32_bf16 v[4:7], v[16:19], v[198:201], v[32:35]
	v_mfma_f32_16x16x32_bf16 v[104:107], v[8:11], v[186:189], v[64:67]
	v_mfma_f32_16x16x32_bf16 v[100:103], v[8:11], v[160:163], v[48:51]
	v_mfma_f32_16x16x32_bf16 v[68:71], v[164:167], v[160:163], v[40:43]
	v_mfma_f32_16x16x32_bf16 v[64:67], v[164:167], v[156:159], v[4:7]
	v_mfma_f32_16x16x32_bf16 v[4:7], v[124:127], v[168:171], v[136:139]
	v_mfma_f32_16x16x32_bf16 v[48:51], v[234:237], v[178:181], v[4:7]
	v_mfma_f32_16x16x32_bf16 v[4:7], v[238:241], v[168:171], v[144:147]
	v_mfma_f32_16x16x32_bf16 v[16:19], v[242:245], v[178:181], v[4:7]
	v_mfma_f32_16x16x32_bf16 v[4:7], v[124:127], v[182:185], v[148:151]
	v_mfma_f32_16x16x32_bf16 v[40:43], v[234:237], v[186:189], v[4:7]
	v_mfma_f32_16x16x32_bf16 v[4:7], v[238:241], v[182:185], v[174:177]
	v_mfma_f32_16x16x32_bf16 v[8:11], v[242:245], v[186:189], v[4:7]
	v_mfma_f32_16x16x32_bf16 v[4:7], v[124:127], v[194:197], v[230:233]
	v_mfma_f32_16x16x32_bf16 v[36:39], v[234:237], v[160:163], v[4:7]
	v_mfma_f32_16x16x32_bf16 v[4:7], v[238:241], v[194:197], v[190:193]
	v_mfma_f32_16x16x32_bf16 v[32:35], v[124:127], v[198:201], v[140:143]
	v_mfma_f32_16x16x32_bf16 v[0:3], v[238:241], v[198:201], v[0:3]
	v_mfma_f32_16x16x32_bf16 v[4:7], v[242:245], v[160:163], v[4:7]
	v_mfma_f32_16x16x32_bf16 v[32:35], v[234:237], v[156:159], v[32:35]
	v_mfma_f32_16x16x32_bf16 v[0:3], v[242:245], v[156:159], v[0:3]
	s_movk_i32 s19, 0x100
	v_cmp_gt_u32_e32 vcc, s19, v154
	s_barrier
	s_and_saveexec_b64 s[52:53], vcc
	s_cbranch_execnz .LBB0_1189
	s_or_b64 exec, exec, s[52:53]
	s_andn2_b64 vcc, exec, s[50:51]
	s_cbranch_vccz .LBB0_1190

; #define STAGE(P, BASE, br, kt) STAGET(tid_, P, BASE, br, kt)
; #define LDA(dst, b, h) UFOR(m, 4) UFOR(k, 2) \
;     dst[m][k] = *reinterpret_cast<const bf16x8*>((char*)SA(b, h) + lds_byte(wr * 64 + m * 16 + fr, k * 32 + fq * 8))
; #define LDB(dst, b, h) UFOR(n, 2) UFOR(k, 2) \
;     dst[n][k] = *reinterpret_cast<const bf16x8*>((char*)SB(b, h) + lds_byte(wc * 32 + n * 16 + fr, k * 32 + fq * 8))
; #define MMA(ai, bj, At, Bq) do { __builtin_amdgcn_s_setprio(1); \
;     UFOR(m, 4) UFOR(n, 2) UFOR(k, 2) \
;       acc[ai][bj][m][n] = __builtin_amdgcn_mfma_f32_16x16x32_bf16(Bq[n][k], At[m][k], acc[ai][bj][m][n], 0, 0, 0); \
;     __builtin_amdgcn_s_setprio(0); } while (0)
; #define WAIT_V(n) asm volatile("s_waitcnt vmcnt(" #n ")" ::: "memory")
; #define WAIT_L(n) asm volatile("s_waitcnt lgkmcnt(" #n ")" ::: "memory")
; #define BAR __builtin_amdgcn_s_barrier()
; #define SCHED __builtin_amdgcn_sched_barrier(0)
; template <int EPI, int K, int KL> ...
;     ...
;     LDB(B0, 0, 0); SCHED; LDA(At, 0, 0); STAGE(SA(1, 1), A, brow + HALF, t + 1);
;     WAIT_L(8); BAR; WAIT_L(0); MMA(0, 0, At, B0); BAR; SCHED;
;     LDB(B1, 0, 1); STAGE(SB(0, 0), Bt, bcol, t + 2);
;     BAR; WAIT_L(0); MMA(0, 1, At, B1); BAR;
;     LDA(At, 0, 1); STAGE(SA(0, 0), A, brow, t + 2);
;     BAR; WAIT_L(0); MMA(1, 0, At, B0); BAR; SCHED;
;     STAGE(SB(0, 1), Bt, bcol + HALF, t + 2);
;     WAIT_V(6); BAR; MMA(1, 1, At, B1); BAR;
;     LDB(B0, 1, 0); SCHED; LDA(At, 1, 0); STAGE(SA(0, 1), A, brow + HALF, t + 2);
;     WAIT_L(8); BAR; WAIT_L(0); MMA(0, 0, At, B0); BAR; SCHED;
.LBB0_1204:
	ds_read_b128 v[136:139], v175
	ds_read_b128 v[178:181], v175 offset:1024
	ds_read_b128 v[182:185], v175 offset:2048
	ds_read_b128 v[186:189], v175 offset:3072
	ds_read_b128 v[190:193], v160
	ds_read_b128 v[194:197], v160 offset:1024
	ds_read_b128 v[198:201], v159
	ds_read_b128 v[202:205], v159 offset:1024
	ds_read_b128 v[208:211], v158
	ds_read_b128 v[214:217], v158 offset:1024
	ds_read_b128 v[218:221], v157
	ds_read_b128 v[222:225], v157 offset:1024
	v_add_u32_e32 v176, 0xc000, v161
	v_lshl_add_u64 v[152:153], v[148:149], 0, s[44:45]
	v_readfirstlane_b32 s15, v176
	v_lshl_add_u64 v[154:155], v[152:153], 0, s[58:59]
	s_mov_b32 m0, s15
	v_add_u32_e32 v177, 0xe000, v161
	global_load_lds_dwordx4 v[154:155], off
	v_lshl_add_u64 v[154:155], v[150:151], 0, s[44:45]
	v_readfirstlane_b32 s15, v177
	s_mov_b32 m0, s15
	v_lshl_add_u64 v[226:227], v[154:155], 0, s[58:59]
	global_load_lds_dwordx4 v[226:227], off
	s_waitcnt lgkmcnt(8)
	s_barrier
	s_waitcnt lgkmcnt(0)
	s_waitcnt lgkmcnt(0)
	v_mfma_f32_16x16x32_bf16 v[124:127], v[136:139], v[190:193], v[124:127]
	v_mfma_f32_16x16x32_bf16 v[120:123], v[182:185], v[190:193], v[120:123]
	v_mfma_f32_16x16x32_bf16 v[116:119], v[136:139], v[198:201], v[116:119]
	v_mfma_f32_16x16x32_bf16 v[112:115], v[182:185], v[198:201], v[112:115]
	v_mfma_f32_16x16x32_bf16 v[108:111], v[136:139], v[208:211], v[108:111]
	v_mfma_f32_16x16x32_bf16 v[104:107], v[182:185], v[208:211], v[104:107]
	v_mfma_f32_16x16x32_bf16 v[100:103], v[136:139], v[218:221], v[100:103]
	v_mfma_f32_16x16x32_bf16 v[96:99], v[182:185], v[218:221], v[96:99]
	v_mfma_f32_16x16x32_bf16 v[124:127], v[178:181], v[194:197], v[124:127]
	v_mfma_f32_16x16x32_bf16 v[120:123], v[186:189], v[194:197], v[120:123]
	v_mfma_f32_16x16x32_bf16 v[116:119], v[178:181], v[202:205], v[116:119]
	v_mfma_f32_16x16x32_bf16 v[112:115], v[186:189], v[202:205], v[112:115]
	v_mfma_f32_16x16x32_bf16 v[108:111], v[178:181], v[214:217], v[108:111]
	v_mfma_f32_16x16x32_bf16 v[104:107], v[186:189], v[214:217], v[104:107]
	v_mfma_f32_16x16x32_bf16 v[100:103], v[178:181], v[222:225], v[100:103]
	v_mfma_f32_16x16x32_bf16 v[96:99], v[186:189], v[222:225], v[96:99]
	s_barrier
	ds_read_b128 v[226:229], v173
	ds_read_b128 v[230:233], v173 offset:1024
	ds_read_b128 v[234:237], v173 offset:2048
	ds_read_b128 v[238:241], v173 offset:3072
	v_lshl_add_u64 v[242:243], v[144:145], 0, s[44:45]
	v_readfirstlane_b32 s15, v156
	v_lshl_add_u64 v[244:245], v[242:243], 0, s[22:23]
	s_mov_b32 m0, s15
	v_add_u32_e32 v248, 0x2000, v156
	global_load_lds_dwordx4 v[244:245], off
	v_lshl_add_u64 v[244:245], v[146:147], 0, s[44:45]
	v_readfirstlane_b32 s15, v248
	s_mov_b32 m0, s15
	v_lshl_add_u64 v[246:247], v[244:245], 0, s[22:23]
	global_load_lds_dwordx4 v[246:247], off
	s_barrier
	s_waitcnt lgkmcnt(0)
	s_waitcnt lgkmcnt(0)
	v_mfma_f32_16x16x32_bf16 v[92:95], v[226:229], v[190:193], v[92:95]
	v_mfma_f32_16x16x32_bf16 v[88:91], v[234:237], v[190:193], v[88:91]
	v_mfma_f32_16x16x32_bf16 v[84:87], v[226:229], v[198:201], v[84:87]
	v_mfma_f32_16x16x32_bf16 v[80:83], v[234:237], v[198:201], v[80:83]
	v_mfma_f32_16x16x32_bf16 v[76:79], v[226:229], v[208:211], v[76:79]
	v_mfma_f32_16x16x32_bf16 v[72:75], v[234:237], v[208:211], v[72:75]
	v_mfma_f32_16x16x32_bf16 v[68:71], v[226:229], v[218:221], v[68:71]
	v_mfma_f32_16x16x32_bf16 v[64:67], v[234:237], v[218:221], v[64:67]
	v_mfma_f32_16x16x32_bf16 v[92:95], v[230:233], v[194:197], v[92:95]
	v_mfma_f32_16x16x32_bf16 v[88:91], v[238:241], v[194:197], v[88:91]
	v_mfma_f32_16x16x32_bf16 v[84:87], v[230:233], v[202:205], v[84:87]
	v_mfma_f32_16x16x32_bf16 v[80:83], v[238:241], v[202:205], v[80:83]
	v_mfma_f32_16x16x32_bf16 v[76:79], v[230:233], v[214:217], v[76:79]
	v_mfma_f32_16x16x32_bf16 v[72:75], v[238:241], v[214:217], v[72:75]
	v_mfma_f32_16x16x32_bf16 v[68:71], v[230:233], v[222:225], v[68:71]
	v_mfma_f32_16x16x32_bf16 v[64:67], v[238:241], v[222:225], v[64:67]
	v_readfirstlane_b32 s15, v161
	v_lshl_add_u64 v[246:247], v[152:153], 0, s[60:61]
	s_mov_b32 m0, s15
	v_readfirstlane_b32 s15, v162
	s_barrier
	ds_read_b128 v[190:193], v160 offset:16384
	ds_read_b128 v[194:197], v160 offset:17408
	ds_read_b128 v[198:201], v159 offset:16384
	ds_read_b128 v[202:205], v159 offset:17408
	ds_read_b128 v[208:211], v158 offset:16384
	ds_read_b128 v[214:217], v158 offset:17408
	ds_read_b128 v[218:221], v157 offset:16384
	ds_read_b128 v[222:225], v157 offset:17408
	global_load_lds_dwordx4 v[246:247], off
	s_mov_b32 m0, s15
	v_lshl_add_u64 v[246:247], v[154:155], 0, s[60:61]
	global_load_lds_dwordx4 v[246:247], off
	s_barrier
	s_waitcnt lgkmcnt(0)
	s_waitcnt lgkmcnt(0)
	v_mfma_f32_16x16x32_bf16 v[60:63], v[136:139], v[190:193], v[60:63]
	v_mfma_f32_16x16x32_bf16 v[56:59], v[182:185], v[190:193], v[56:59]
	v_mfma_f32_16x16x32_bf16 v[52:55], v[136:139], v[198:201], v[52:55]
	v_mfma_f32_16x16x32_bf16 v[48:51], v[182:185], v[198:201], v[48:51]
	v_mfma_f32_16x16x32_bf16 v[44:47], v[136:139], v[208:211], v[44:47]
	v_mfma_f32_16x16x32_bf16 v[40:43], v[182:185], v[208:211], v[40:43]
	v_mfma_f32_16x16x32_bf16 v[36:39], v[136:139], v[218:221], v[36:39]
	v_mfma_f32_16x16x32_bf16 v[32:35], v[182:185], v[218:221], v[32:35]
	v_mfma_f32_16x16x32_bf16 v[60:63], v[178:181], v[194:197], v[60:63]
	v_mfma_f32_16x16x32_bf16 v[56:59], v[186:189], v[194:197], v[56:59]
	v_mfma_f32_16x16x32_bf16 v[52:55], v[178:181], v[202:205], v[52:55]
	v_mfma_f32_16x16x32_bf16 v[48:51], v[186:189], v[202:205], v[48:51]
	v_mfma_f32_16x16x32_bf16 v[44:47], v[178:181], v[214:217], v[44:47]
	v_mfma_f32_16x16x32_bf16 v[40:43], v[186:189], v[214:217], v[40:43]
	v_mfma_f32_16x16x32_bf16 v[36:39], v[178:181], v[222:225], v[36:39]
	v_mfma_f32_16x16x32_bf16 v[32:35], v[186:189], v[222:225], v[32:35]
	s_barrier
; #define STAGE(P, BASE, br, kt) STAGET(tid_, P, BASE, br, kt)
; #define LDA(dst, b, h) UFOR(m, 4) UFOR(k, 2) \
;     dst[m][k] = *reinterpret_cast<const bf16x8*>((char*)SA(b, h) + lds_byte(wr * 64 + m * 16 + fr, k * 32 + fq * 8))
; #define LDB(dst, b, h) UFOR(n, 2) UFOR(k, 2) \
;     dst[n][k] = *reinterpret_cast<const bf16x8*>((char*)SB(b, h) + lds_byte(wc * 32 + n * 16 + fr, k * 32 + fq * 8))
; #define MMA(ai, bj, At, Bq) do { __builtin_amdgcn_s_setprio(1); \
;     UFOR(m, 4) UFOR(n, 2) UFOR(k, 2) \
;       acc[ai][bj][m][n] = __builtin_amdgcn_mfma_f32_16x16x32_bf16(Bq[n][k], At[m][k], acc[ai][bj][m][n], 0, 0, 0); \
;     __builtin_amdgcn_s_setprio(0); } while (0)
; #define WAIT_V(n) asm volatile("s_waitcnt vmcnt(" #n ")" ::: "memory")
; #define WAIT_L(n) asm volatile("s_waitcnt lgkmcnt(" #n ")" ::: "memory")
; #define BAR __builtin_amdgcn_s_barrier()
; #define SCHED __builtin_amdgcn_sched_barrier(0)
; template <int EPI, int K, int KL> ...
;     ...
;     STAGE(SB(0, 1), Bt, bcol + HALF, t + 2);
;     WAIT_V(6); BAR; MMA(1, 1, At, B1); BAR;
;     LDB(B0, 1, 0); SCHED; LDA(At, 1, 0); STAGE(SA(0, 1), A, brow + HALF, t + 2);
;     WAIT_L(8); BAR; WAIT_L(0); MMA(0, 0, At, B0); BAR; SCHED;
;     LDB(B1, 1, 1); STAGE(SB(1, 0), Bt, bcol, t + 3);
;     BAR; WAIT_L(0); MMA(0, 1, At, B1); BAR;
;     LDA(At, 1, 1); STAGE(SA(1, 0), A, brow, t + 3);
;     BAR; WAIT_L(0); MMA(1, 0, At, B0); BAR; SCHED;
;     STAGE(SB(1, 1), Bt, bcol + HALF, t + 3);
	v_readfirstlane_b32 s15, v164
	v_add_u32_e32 v138, 0x2000, v164
	v_lshl_add_u64 v[136:137], v[242:243], 0, s[24:25]
	s_mov_b32 m0, s15
	v_readfirstlane_b32 s15, v138
	global_load_lds_dwordx4 v[136:137], off
	s_mov_b32 m0, s15
	v_lshl_add_u64 v[136:137], v[244:245], 0, s[24:25]
	global_load_lds_dwordx4 v[136:137], off
	s_waitcnt vmcnt(6)
	s_barrier
	v_mfma_f32_16x16x32_bf16 v[28:31], v[226:229], v[190:193], v[28:31]
	v_mfma_f32_16x16x32_bf16 v[24:27], v[234:237], v[190:193], v[24:27]
	v_mfma_f32_16x16x32_bf16 v[20:23], v[226:229], v[198:201], v[20:23]
	v_mfma_f32_16x16x32_bf16 v[16:19], v[234:237], v[198:201], v[16:19]
	v_mfma_f32_16x16x32_bf16 v[12:15], v[226:229], v[208:211], v[12:15]
	v_mfma_f32_16x16x32_bf16 v[8:11], v[234:237], v[208:211], v[8:11]
	v_mfma_f32_16x16x32_bf16 v[4:7], v[226:229], v[218:221], v[4:7]
	v_mfma_f32_16x16x32_bf16 v[0:3], v[234:237], v[218:221], v[0:3]
	v_mfma_f32_16x16x32_bf16 v[28:31], v[230:233], v[194:197], v[28:31]
	v_mfma_f32_16x16x32_bf16 v[24:27], v[238:241], v[194:197], v[24:27]
	v_mfma_f32_16x16x32_bf16 v[20:23], v[230:233], v[202:205], v[20:23]
	v_mfma_f32_16x16x32_bf16 v[16:19], v[238:241], v[202:205], v[16:19]
	v_mfma_f32_16x16x32_bf16 v[12:15], v[230:233], v[214:217], v[12:15]
	v_mfma_f32_16x16x32_bf16 v[8:11], v[238:241], v[214:217], v[8:11]
	v_mfma_f32_16x16x32_bf16 v[4:7], v[230:233], v[222:225], v[4:7]
	v_mfma_f32_16x16x32_bf16 v[0:3], v[238:241], v[222:225], v[0:3]
	s_barrier
	ds_read_b128 v[136:139], v166
	ds_read_b128 v[178:181], v166 offset:1024
	ds_read_b128 v[182:185], v166 offset:2048
	ds_read_b128 v[186:189], v166 offset:3072
	ds_read_b128 v[190:193], v160 offset:32768
	ds_read_b128 v[194:197], v160 offset:33792
	ds_read_b128 v[198:201], v159 offset:32768
	ds_read_b128 v[202:205], v159 offset:33792
	ds_read_b128 v[208:211], v158 offset:32768
	ds_read_b128 v[214:217], v158 offset:33792
	ds_read_b128 v[218:221], v157 offset:32768
	ds_read_b128 v[222:225], v157 offset:33792
	v_readfirstlane_b32 s15, v165
	v_lshl_add_u64 v[226:227], v[152:153], 0, s[62:63]
	s_mov_b32 m0, s15
	v_readfirstlane_b32 s15, v167
	global_load_lds_dwordx4 v[226:227], off
	s_mov_b32 m0, s15
	v_lshl_add_u64 v[226:227], v[154:155], 0, s[62:63]
	global_load_lds_dwordx4 v[226:227], off
	s_waitcnt lgkmcnt(8)
	s_barrier
	s_waitcnt lgkmcnt(0)
	s_waitcnt lgkmcnt(0)
	v_mfma_f32_16x16x32_bf16 v[124:127], v[136:139], v[190:193], v[124:127]
	v_mfma_f32_16x16x32_bf16 v[120:123], v[182:185], v[190:193], v[120:123]
	v_mfma_f32_16x16x32_bf16 v[116:119], v[136:139], v[198:201], v[116:119]
	v_mfma_f32_16x16x32_bf16 v[112:115], v[182:185], v[198:201], v[112:115]
	v_mfma_f32_16x16x32_bf16 v[108:111], v[136:139], v[208:211], v[108:111]
	v_mfma_f32_16x16x32_bf16 v[104:107], v[182:185], v[208:211], v[104:107]
	v_mfma_f32_16x16x32_bf16 v[100:103], v[136:139], v[218:221], v[100:103]
	v_mfma_f32_16x16x32_bf16 v[96:99], v[182:185], v[218:221], v[96:99]
	v_mfma_f32_16x16x32_bf16 v[124:127], v[178:181], v[194:197], v[124:127]
	v_mfma_f32_16x16x32_bf16 v[120:123], v[186:189], v[194:197], v[120:123]
	v_mfma_f32_16x16x32_bf16 v[116:119], v[178:181], v[202:205], v[116:119]
	v_mfma_f32_16x16x32_bf16 v[112:115], v[186:189], v[202:205], v[112:115]
	v_mfma_f32_16x16x32_bf16 v[108:111], v[178:181], v[214:217], v[108:111]
	v_mfma_f32_16x16x32_bf16 v[104:107], v[186:189], v[214:217], v[104:107]
	v_mfma_f32_16x16x32_bf16 v[100:103], v[178:181], v[222:225], v[100:103]
	v_mfma_f32_16x16x32_bf16 v[96:99], v[186:189], v[222:225], v[96:99]
	s_barrier
	ds_read_b128 v[226:229], v163
	ds_read_b128 v[230:233], v163 offset:1024
	ds_read_b128 v[234:237], v163 offset:2048
	ds_read_b128 v[238:241], v163 offset:3072
	v_readfirstlane_b32 s15, v168
	v_lshl_add_u64 v[246:247], v[242:243], 0, s[94:95]
	s_mov_b32 m0, s15
	v_readfirstlane_b32 s15, v169
	global_load_lds_dwordx4 v[246:247], off
	s_mov_b32 m0, s15
	v_lshl_add_u64 v[246:247], v[244:245], 0, s[94:95]
	global_load_lds_dwordx4 v[246:247], off
	s_barrier
	s_waitcnt lgkmcnt(0)
	s_waitcnt lgkmcnt(0)
	v_mfma_f32_16x16x32_bf16 v[92:95], v[226:229], v[190:193], v[92:95]
	v_mfma_f32_16x16x32_bf16 v[88:91], v[234:237], v[190:193], v[88:91]
	v_mfma_f32_16x16x32_bf16 v[84:87], v[226:229], v[198:201], v[84:87]
	v_mfma_f32_16x16x32_bf16 v[80:83], v[234:237], v[198:201], v[80:83]
	v_mfma_f32_16x16x32_bf16 v[76:79], v[226:229], v[208:211], v[76:79]
	v_mfma_f32_16x16x32_bf16 v[72:75], v[234:237], v[208:211], v[72:75]
	v_mfma_f32_16x16x32_bf16 v[68:71], v[226:229], v[218:221], v[68:71]
	v_mfma_f32_16x16x32_bf16 v[64:67], v[234:237], v[218:221], v[64:67]
	v_mfma_f32_16x16x32_bf16 v[92:95], v[230:233], v[194:197], v[92:95]
	v_mfma_f32_16x16x32_bf16 v[88:91], v[238:241], v[194:197], v[88:91]
	v_mfma_f32_16x16x32_bf16 v[84:87], v[230:233], v[202:205], v[84:87]
	v_mfma_f32_16x16x32_bf16 v[80:83], v[238:241], v[202:205], v[80:83]
	v_mfma_f32_16x16x32_bf16 v[76:79], v[230:233], v[214:217], v[76:79]
	v_mfma_f32_16x16x32_bf16 v[72:75], v[238:241], v[214:217], v[72:75]
	v_mfma_f32_16x16x32_bf16 v[68:71], v[230:233], v[222:225], v[68:71]
	v_mfma_f32_16x16x32_bf16 v[64:67], v[238:241], v[222:225], v[64:67]
	v_readfirstlane_b32 s15, v170
	v_lshl_add_u64 v[152:153], v[152:153], 0, s[64:65]
	s_mov_b32 m0, s15
	v_readfirstlane_b32 s15, v171
	s_barrier
	ds_read_b128 v[190:193], v160 offset:49152
	ds_read_b128 v[194:197], v160 offset:50176
	ds_read_b128 v[198:201], v159 offset:49152
	ds_read_b128 v[202:205], v159 offset:50176
	ds_read_b128 v[208:211], v158 offset:49152
	ds_read_b128 v[214:217], v158 offset:50176
	ds_read_b128 v[218:221], v157 offset:49152
	ds_read_b128 v[222:225], v157 offset:50176
	global_load_lds_dwordx4 v[152:153], off
	s_mov_b32 m0, s15
	v_lshl_add_u64 v[152:153], v[154:155], 0, s[64:65]
	global_load_lds_dwordx4 v[152:153], off
	s_barrier
; #define STAGE(P, BASE, br, kt) STAGET(tid_, P, BASE, br, kt)
; #define LDA(dst, b, h) UFOR(m, 4) UFOR(k, 2) \
;     dst[m][k] = *reinterpret_cast<const bf16x8*>((char*)SA(b, h) + lds_byte(wr * 64 + m * 16 + fr, k * 32 + fq * 8))
; #define LDB(dst, b, h) UFOR(n, 2) UFOR(k, 2) \
;     dst[n][k] = *reinterpret_cast<const bf16x8*>((char*)SB(b, h) + lds_byte(wc * 32 + n * 16 + fr, k * 32 + fq * 8))
; #define MMA(ai, bj, At, Bq) do { __builtin_amdgcn_s_setprio(1); \
;     UFOR(m, 4) UFOR(n, 2) UFOR(k, 2) \
;       acc[ai][bj][m][n] = __builtin_amdgcn_mfma_f32_16x16x32_bf16(Bq[n][k], At[m][k], acc[ai][bj][m][n], 0, 0, 0); \
;     __builtin_amdgcn_s_setprio(0); } while (0)
; #define WAIT_V(n) asm volatile("s_waitcnt vmcnt(" #n ")" ::: "memory")
; #define WAIT_L(n) asm volatile("s_waitcnt lgkmcnt(" #n ")" ::: "memory")
; #define BAR __builtin_amdgcn_s_barrier()
; template <int EPI, int K, int KL> ...
;     ...
;     STAGE(SB(1, 1), Bt, bcol + HALF, t + 3);
;     WAIT_V(6); BAR; MMA(1, 1, At, B1); BAR;
;   }
;   { LDB(B0, 0, 0); LDA(At, 0, 0); STAGE(SA(1, 1), A, brow + HALF, nt - 1);
;     BAR; WAIT_L(0); MMA(0, 0, At, B0); BAR;
;     LDB(B1, 0, 1); BAR; WAIT_L(0); MMA(0, 1, At, B1); BAR;
;     LDA(At, 0, 1); WAIT_V(4); BAR; WAIT_L(0); MMA(1, 0, At, B0); MMA(1, 1, At, B1); BAR; }
	s_waitcnt lgkmcnt(0)
	s_waitcnt lgkmcnt(0)
	v_mfma_f32_16x16x32_bf16 v[60:63], v[136:139], v[190:193], v[60:63]
	v_mfma_f32_16x16x32_bf16 v[56:59], v[182:185], v[190:193], v[56:59]
	v_mfma_f32_16x16x32_bf16 v[52:55], v[136:139], v[198:201], v[52:55]
	v_mfma_f32_16x16x32_bf16 v[48:51], v[182:185], v[198:201], v[48:51]
	v_mfma_f32_16x16x32_bf16 v[44:47], v[136:139], v[208:211], v[44:47]
	v_mfma_f32_16x16x32_bf16 v[40:43], v[182:185], v[208:211], v[40:43]
	v_mfma_f32_16x16x32_bf16 v[36:39], v[136:139], v[218:221], v[36:39]
	v_mfma_f32_16x16x32_bf16 v[32:35], v[182:185], v[218:221], v[32:35]
	v_mfma_f32_16x16x32_bf16 v[60:63], v[178:181], v[194:197], v[60:63]
	v_mfma_f32_16x16x32_bf16 v[56:59], v[186:189], v[194:197], v[56:59]
	v_mfma_f32_16x16x32_bf16 v[52:55], v[178:181], v[202:205], v[52:55]
	v_mfma_f32_16x16x32_bf16 v[48:51], v[186:189], v[202:205], v[48:51]
	v_mfma_f32_16x16x32_bf16 v[44:47], v[178:181], v[214:217], v[44:47]
	v_mfma_f32_16x16x32_bf16 v[40:43], v[186:189], v[214:217], v[40:43]
	v_mfma_f32_16x16x32_bf16 v[36:39], v[178:181], v[222:225], v[36:39]
	v_mfma_f32_16x16x32_bf16 v[32:35], v[186:189], v[222:225], v[32:35]
	s_barrier
	v_readfirstlane_b32 s15, v172
	v_lshl_add_u64 v[136:137], v[242:243], 0, s[10:11]
	s_mov_b32 m0, s15
	v_readfirstlane_b32 s15, v174
	global_load_lds_dwordx4 v[136:137], off
	s_mov_b32 m0, s15
	v_lshl_add_u64 v[136:137], v[244:245], 0, s[10:11]
	global_load_lds_dwordx4 v[136:137], off
	s_waitcnt vmcnt(6)
	s_barrier
	v_mfma_f32_16x16x32_bf16 v[28:31], v[226:229], v[190:193], v[28:31]
	v_mfma_f32_16x16x32_bf16 v[24:27], v[234:237], v[190:193], v[24:27]
	v_mfma_f32_16x16x32_bf16 v[20:23], v[226:229], v[198:201], v[20:23]
	v_mfma_f32_16x16x32_bf16 v[16:19], v[234:237], v[198:201], v[16:19]
	v_mfma_f32_16x16x32_bf16 v[12:15], v[226:229], v[208:211], v[12:15]
	v_mfma_f32_16x16x32_bf16 v[8:11], v[234:237], v[208:211], v[8:11]
	v_mfma_f32_16x16x32_bf16 v[4:7], v[226:229], v[218:221], v[4:7]
	v_mfma_f32_16x16x32_bf16 v[0:3], v[234:237], v[218:221], v[0:3]
	v_mfma_f32_16x16x32_bf16 v[28:31], v[230:233], v[194:197], v[28:31]
	v_mfma_f32_16x16x32_bf16 v[24:27], v[238:241], v[194:197], v[24:27]
	v_mfma_f32_16x16x32_bf16 v[20:23], v[230:233], v[202:205], v[20:23]
	v_mfma_f32_16x16x32_bf16 v[16:19], v[238:241], v[202:205], v[16:19]
	v_mfma_f32_16x16x32_bf16 v[12:15], v[230:233], v[214:217], v[12:15]
	v_mfma_f32_16x16x32_bf16 v[8:11], v[238:241], v[214:217], v[8:11]
	v_mfma_f32_16x16x32_bf16 v[4:7], v[230:233], v[222:225], v[4:7]
	v_mfma_f32_16x16x32_bf16 v[0:3], v[238:241], v[222:225], v[0:3]
	s_add_i32 s14, s14, 2
	v_lshl_add_u64 v[144:145], v[144:145], 0, s[20:21]
	v_lshl_add_u64 v[146:147], v[146:147], 0, s[20:21]
	v_lshl_add_u64 v[148:149], v[148:149], 0, s[20:21]
	s_cmp_lt_u32 s14, 4
	v_lshl_add_u64 v[150:151], v[150:151], 0, s[20:21]
	s_cbranch_scc1 .Lkrot_1204
	s_barrier
	s_add_u32 s14, s46, 0x160380
	s_addc_u32 s15, s47, 0
	v_lshl_add_u64 v[142:143], s[14:15], 0, v[142:143]
	v_readfirstlane_b32 s18, v176
	v_lshl_add_u64 v[128:129], v[128:129], 1, v[142:143]
	s_mov_b32 m0, s18
	ds_read_b128 v[136:139], v175
	ds_read_b128 v[144:147], v175 offset:1024
	ds_read_b128 v[148:151], v175 offset:2048
	ds_read_b128 v[168:171], v175 offset:3072
	ds_read_b128 v[178:181], v160
	ds_read_b128 v[182:185], v160 offset:1024
	ds_read_b128 v[186:189], v159
	ds_read_b128 v[190:193], v159 offset:1024
	ds_read_b128 v[194:197], v158
	ds_read_b128 v[198:201], v158 offset:1024
	ds_read_b128 v[202:205], v157
	ds_read_b128 v[208:211], v157 offset:1024
	global_load_lds_dwordx4 v[128:129], off
	v_lshl_add_u64 v[128:129], s[14:15], 0, v[140:141]
	v_readfirstlane_b32 s14, v177
	v_lshl_add_u64 v[128:129], v[130:131], 1, v[128:129]
	s_mov_b32 m0, s14
	s_nop 0
	global_load_lds_dwordx4 v[128:129], off
	s_barrier
	s_waitcnt lgkmcnt(0)
	s_waitcnt lgkmcnt(0)
	v_mfma_f32_16x16x32_bf16 v[124:127], v[136:139], v[178:181], v[124:127]
	v_mfma_f32_16x16x32_bf16 v[120:123], v[148:151], v[178:181], v[120:123]
	v_mfma_f32_16x16x32_bf16 v[116:119], v[136:139], v[186:189], v[116:119]
	v_mfma_f32_16x16x32_bf16 v[112:115], v[148:151], v[186:189], v[112:115]
	v_mfma_f32_16x16x32_bf16 v[108:111], v[136:139], v[194:197], v[108:111]
	v_mfma_f32_16x16x32_bf16 v[104:107], v[148:151], v[194:197], v[104:107]
	v_mfma_f32_16x16x32_bf16 v[100:103], v[136:139], v[202:205], v[100:103]
	v_mfma_f32_16x16x32_bf16 v[96:99], v[148:151], v[202:205], v[96:99]
	v_mfma_f32_16x16x32_bf16 v[124:127], v[144:147], v[182:185], v[124:127]
	v_mfma_f32_16x16x32_bf16 v[120:123], v[168:171], v[182:185], v[120:123]
	v_mfma_f32_16x16x32_bf16 v[116:119], v[144:147], v[190:193], v[116:119]
	v_mfma_f32_16x16x32_bf16 v[112:115], v[168:171], v[190:193], v[112:115]
	v_mfma_f32_16x16x32_bf16 v[108:111], v[144:147], v[198:201], v[108:111]
	v_mfma_f32_16x16x32_bf16 v[104:107], v[168:171], v[198:201], v[104:107]
	v_mfma_f32_16x16x32_bf16 v[100:103], v[144:147], v[208:211], v[100:103]
	v_mfma_f32_16x16x32_bf16 v[96:99], v[168:171], v[208:211], v[96:99]
	s_barrier
	ds_read_b128 v[128:131], v173
	ds_read_b128 v[140:143], v173 offset:1024
	ds_read_b128 v[174:177], v173 offset:2048
	ds_read_b128 v[214:217], v173 offset:3072
	s_barrier
; #define LDA(dst, b, h) UFOR(m, 4) UFOR(k, 2) \
;     dst[m][k] = *reinterpret_cast<const bf16x8*>((char*)SA(b, h) + lds_byte(wr * 64 + m * 16 + fr, k * 32 + fq * 8))
; #define LDB(dst, b, h) UFOR(n, 2) UFOR(k, 2) \
;     dst[n][k] = *reinterpret_cast<const bf16x8*>((char*)SB(b, h) + lds_byte(wc * 32 + n * 16 + fr, k * 32 + fq * 8))
; #define MMA(ai, bj, At, Bq) do { __builtin_amdgcn_s_setprio(1); \
;     UFOR(m, 4) UFOR(n, 2) UFOR(k, 2) \
;       acc[ai][bj][m][n] = __builtin_amdgcn_mfma_f32_16x16x32_bf16(Bq[n][k], At[m][k], acc[ai][bj][m][n], 0, 0, 0); \
;     __builtin_amdgcn_s_setprio(0); } while (0)
; #define WAIT_V(n) asm volatile("s_waitcnt vmcnt(" #n ")" ::: "memory")
; #define WAIT_L(n) asm volatile("s_waitcnt lgkmcnt(" #n ")" ::: "memory")
; #define BAR __builtin_amdgcn_s_barrier()
; template <int EPI, int K, int KL> ...
;     ...
;     LDB(B1, 0, 1); BAR; WAIT_L(0); MMA(0, 1, At, B1); BAR;
;     LDA(At, 0, 1); WAIT_V(4); BAR; WAIT_L(0); MMA(1, 0, At, B0); MMA(1, 1, At, B1); BAR; }
;   { LDB(B0, 1, 0); LDA(At, 1, 0); WAIT_V(2); BAR; WAIT_L(0); MMA(0, 0, At, B0); BAR;
	s_waitcnt lgkmcnt(0)
	s_waitcnt lgkmcnt(0)
	v_mfma_f32_16x16x32_bf16 v[92:95], v[128:131], v[178:181], v[92:95]
	v_mfma_f32_16x16x32_bf16 v[88:91], v[174:177], v[178:181], v[88:91]
	v_mfma_f32_16x16x32_bf16 v[84:87], v[128:131], v[186:189], v[84:87]
	v_mfma_f32_16x16x32_bf16 v[80:83], v[174:177], v[186:189], v[80:83]
	v_mfma_f32_16x16x32_bf16 v[76:79], v[128:131], v[194:197], v[76:79]
	v_mfma_f32_16x16x32_bf16 v[68:71], v[128:131], v[202:205], v[68:71]
	v_mfma_f32_16x16x32_bf16 v[64:67], v[174:177], v[202:205], v[64:67]
	v_mfma_f32_16x16x32_bf16 v[92:95], v[140:143], v[182:185], v[92:95]
	v_mfma_f32_16x16x32_bf16 v[88:91], v[214:217], v[182:185], v[88:91]
	v_mfma_f32_16x16x32_bf16 v[84:87], v[140:143], v[190:193], v[84:87]
	v_mfma_f32_16x16x32_bf16 v[80:83], v[214:217], v[190:193], v[80:83]
	v_mfma_f32_16x16x32_bf16 v[76:79], v[140:143], v[198:201], v[76:79]
	v_mfma_f32_16x16x32_bf16 v[72:75], v[174:177], v[194:197], v[72:75]
	v_mfma_f32_16x16x32_bf16 v[68:71], v[140:143], v[208:211], v[68:71]
	v_mfma_f32_16x16x32_bf16 v[64:67], v[214:217], v[208:211], v[64:67]
	v_mfma_f32_16x16x32_bf16 v[178:181], v[214:217], v[198:201], v[72:75]
	s_barrier
	s_nop 3
	ds_read_b128 v[72:75], v160 offset:16384
	ds_read_b128 v[182:185], v160 offset:17408
	ds_read_b128 v[186:189], v159 offset:16384
	ds_read_b128 v[190:193], v159 offset:17408
	ds_read_b128 v[194:197], v158 offset:16384
	ds_read_b128 v[198:201], v158 offset:17408
	ds_read_b128 v[202:205], v157 offset:16384
	ds_read_b128 v[208:211], v157 offset:17408
	s_waitcnt vmcnt(4)
	s_barrier
	s_waitcnt lgkmcnt(0)
	s_waitcnt lgkmcnt(0)
	v_mfma_f32_16x16x32_bf16 v[48:51], v[148:151], v[186:189], v[48:51]
	v_mfma_f32_16x16x32_bf16 v[60:63], v[136:139], v[72:75], v[60:63]
	v_mfma_f32_16x16x32_bf16 v[56:59], v[148:151], v[72:75], v[56:59]
	v_mfma_f32_16x16x32_bf16 v[52:55], v[136:139], v[186:189], v[52:55]
	v_mfma_f32_16x16x32_bf16 v[48:51], v[168:171], v[190:193], v[48:51]
	v_mfma_f32_16x16x32_bf16 v[44:47], v[136:139], v[194:197], v[44:47]
	v_mfma_f32_16x16x32_bf16 v[40:43], v[148:151], v[194:197], v[40:43]
	v_mfma_f32_16x16x32_bf16 v[36:39], v[136:139], v[202:205], v[36:39]
	v_mfma_f32_16x16x32_bf16 v[32:35], v[148:151], v[202:205], v[32:35]
	v_mfma_f32_16x16x32_bf16 v[218:221], v[144:147], v[182:185], v[60:63]
	v_mfma_f32_16x16x32_bf16 v[222:225], v[168:171], v[182:185], v[56:59]
	v_mfma_f32_16x16x32_bf16 v[226:229], v[144:147], v[190:193], v[52:55]
	v_mfma_f32_16x16x32_bf16 v[230:233], v[144:147], v[198:201], v[44:47]
	v_mfma_f32_16x16x32_bf16 v[234:237], v[168:171], v[198:201], v[40:43]
	v_mfma_f32_16x16x32_bf16 v[136:139], v[144:147], v[208:211], v[36:39]
	v_mfma_f32_16x16x32_bf16 v[144:147], v[168:171], v[208:211], v[32:35]
	v_mfma_f32_16x16x32_bf16 v[28:31], v[128:131], v[72:75], v[28:31]
	v_mfma_f32_16x16x32_bf16 v[24:27], v[174:177], v[72:75], v[24:27]
	v_mfma_f32_16x16x32_bf16 v[20:23], v[128:131], v[186:189], v[20:23]
	v_mfma_f32_16x16x32_bf16 v[16:19], v[174:177], v[186:189], v[16:19]
	v_mfma_f32_16x16x32_bf16 v[12:15], v[128:131], v[194:197], v[12:15]
	v_mfma_f32_16x16x32_bf16 v[8:11], v[174:177], v[194:197], v[8:11]
	v_mfma_f32_16x16x32_bf16 v[4:7], v[128:131], v[202:205], v[4:7]
	v_mfma_f32_16x16x32_bf16 v[0:3], v[174:177], v[202:205], v[0:3]
	v_mfma_f32_16x16x32_bf16 v[148:151], v[140:143], v[182:185], v[28:31]
	v_mfma_f32_16x16x32_bf16 v[168:171], v[214:217], v[182:185], v[24:27]
	v_mfma_f32_16x16x32_bf16 v[182:185], v[140:143], v[190:193], v[20:23]
	v_mfma_f32_16x16x32_bf16 v[186:189], v[214:217], v[190:193], v[16:19]
	v_mfma_f32_16x16x32_bf16 v[190:193], v[140:143], v[198:201], v[12:15]
	v_mfma_f32_16x16x32_bf16 v[194:197], v[214:217], v[198:201], v[8:11]
	v_mfma_f32_16x16x32_bf16 v[128:131], v[140:143], v[208:211], v[4:7]
	v_mfma_f32_16x16x32_bf16 v[140:143], v[214:217], v[208:211], v[0:3]
	s_barrier
	ds_read_b128 v[172:175], v166
	ds_read_b128 v[198:201], v166 offset:1024
	ds_read_b128 v[202:205], v166 offset:2048
	ds_read_b128 v[164:167], v166 offset:3072
	ds_read_b128 v[20:23], v160 offset:32768
	ds_read_b128 v[24:27], v160 offset:33792
	ds_read_b128 v[28:31], v159 offset:32768
	ds_read_b128 v[32:35], v159 offset:33792
	ds_read_b128 v[36:39], v158 offset:32768
	ds_read_b128 v[208:211], v158 offset:33792
	ds_read_b128 v[214:217], v157 offset:32768
	ds_read_b128 v[238:241], v157 offset:33792
	s_waitcnt vmcnt(2)
	s_barrier
; #define LDA(dst, b, h) UFOR(m, 4) UFOR(k, 2) \
;     dst[m][k] = *reinterpret_cast<const bf16x8*>((char*)SA(b, h) + lds_byte(wr * 64 + m * 16 + fr, k * 32 + fq * 8))
; #define LDB(dst, b, h) UFOR(n, 2) UFOR(k, 2) \
;     dst[n][k] = *reinterpret_cast<const bf16x8*>((char*)SB(b, h) + lds_byte(wc * 32 + n * 16 + fr, k * 32 + fq * 8))
; #define MMA(ai, bj, At, Bq) do { __builtin_amdgcn_s_setprio(1); \
;     UFOR(m, 4) UFOR(n, 2) UFOR(k, 2) \
;       acc[ai][bj][m][n] = __builtin_amdgcn_mfma_f32_16x16x32_bf16(Bq[n][k], At[m][k], acc[ai][bj][m][n], 0, 0, 0); \
;     __builtin_amdgcn_s_setprio(0); } while (0)
; #define WAIT_V(n) asm volatile("s_waitcnt vmcnt(" #n ")" ::: "memory")
; #define WAIT_L(n) asm volatile("s_waitcnt lgkmcnt(" #n ")" ::: "memory")
; #define BAR __builtin_amdgcn_s_barrier()
; template <int EPI, int K, int KL> ...
;     ...
;   { LDB(B0, 1, 0); LDA(At, 1, 0); WAIT_V(2); BAR; WAIT_L(0); MMA(0, 0, At, B0); BAR;
;     LDB(B1, 1, 1); WAIT_V(0); BAR; WAIT_L(0); MMA(0, 1, At, B1); BAR;
;     LDA(At, 1, 1); BAR; WAIT_L(0); MMA(1, 0, At, B0); MMA(1, 1, At, B1); BAR; }
;   if (wr == 0) BAR;
; __device__ __forceinline__ void gemm_ctx_splitk_down(const u16* A, const u16* Bt, float* P2, const EpiArgs& e0) {
;     ...
;   for (int u = bid_; u < 16 * P2_PARTS; u += gridDim.x) {
;     const int tile = u / P2_PARTS, part = u % P2_PARTS, pm = 128 + (tile >> 3), pn = tile & 7;
;     EpiArgs e = e0; e.part = P2 + (size_t)part * 512 * DM;
;     const long koff = (long)part * (DFF / P2_PARTS);
;     gemm_tile<EPI_PART, DFF, DFF / P2_PARTS>(A + koff, Bt + koff, (long)pm * BM, pn * BM, pn, 0, 0, e, true, false, 0, 0);
;   }
	s_waitcnt lgkmcnt(0)
	s_waitcnt lgkmcnt(0)
	v_mfma_f32_16x16x32_bf16 v[0:3], v[172:175], v[20:23], v[124:127]
	v_mfma_f32_16x16x32_bf16 v[44:47], v[198:201], v[24:27], v[0:3]
	v_mfma_f32_16x16x32_bf16 v[0:3], v[202:205], v[20:23], v[120:123]
	v_mfma_f32_16x16x32_bf16 v[52:55], v[164:167], v[24:27], v[0:3]
	v_mfma_f32_16x16x32_bf16 v[0:3], v[172:175], v[28:31], v[116:119]
	v_mfma_f32_16x16x32_bf16 v[40:43], v[198:201], v[32:35], v[0:3]
	v_mfma_f32_16x16x32_bf16 v[0:3], v[202:205], v[28:31], v[112:115]
	v_mfma_f32_16x16x32_bf16 v[16:19], v[164:167], v[32:35], v[0:3]
	v_mfma_f32_16x16x32_bf16 v[0:3], v[172:175], v[36:39], v[108:111]
	v_mfma_f32_16x16x32_bf16 v[8:11], v[198:201], v[208:211], v[0:3]
	v_mfma_f32_16x16x32_bf16 v[0:3], v[202:205], v[36:39], v[104:107]
	v_mfma_f32_16x16x32_bf16 v[12:15], v[164:167], v[208:211], v[0:3]
	v_mfma_f32_16x16x32_bf16 v[0:3], v[172:175], v[214:217], v[100:103]
	v_mfma_f32_16x16x32_bf16 v[4:7], v[202:205], v[214:217], v[96:99]
	v_mfma_f32_16x16x32_bf16 v[0:3], v[198:201], v[238:241], v[0:3]
	v_mfma_f32_16x16x32_bf16 v[4:7], v[164:167], v[238:241], v[4:7]
	s_barrier
	ds_read_b128 v[108:111], v163
	ds_read_b128 v[242:245], v163 offset:1024
	ds_read_b128 v[246:249], v163 offset:2048
	ds_read_b128 v[152:155], v163 offset:3072
	s_waitcnt vmcnt(0)
	s_barrier
	s_waitcnt lgkmcnt(0)
	s_waitcnt lgkmcnt(0)
	v_mfma_f32_16x16x32_bf16 v[56:59], v[108:111], v[20:23], v[92:95]
	v_mfma_f32_16x16x32_bf16 v[20:23], v[246:249], v[20:23], v[88:91]
	v_mfma_f32_16x16x32_bf16 v[72:75], v[152:155], v[24:27], v[20:23]
	v_mfma_f32_16x16x32_bf16 v[20:23], v[108:111], v[28:31], v[84:87]
	v_mfma_f32_16x16x32_bf16 v[60:63], v[242:245], v[24:27], v[56:59]
	v_mfma_f32_16x16x32_bf16 v[56:59], v[242:245], v[32:35], v[20:23]
	v_mfma_f32_16x16x32_bf16 v[20:23], v[246:249], v[28:31], v[80:83]
	v_mfma_f32_16x16x32_bf16 v[20:23], v[152:155], v[32:35], v[20:23]
	v_mfma_f32_16x16x32_bf16 v[24:27], v[108:111], v[36:39], v[76:79]
	v_mfma_f32_16x16x32_bf16 v[28:31], v[246:249], v[36:39], v[178:181]
	v_mfma_f32_16x16x32_bf16 v[32:35], v[108:111], v[214:217], v[68:71]
	v_mfma_f32_16x16x32_bf16 v[36:39], v[246:249], v[214:217], v[64:67]
	v_mfma_f32_16x16x32_bf16 v[24:27], v[242:245], v[208:211], v[24:27]
	v_mfma_f32_16x16x32_bf16 v[28:31], v[152:155], v[208:211], v[28:31]
	v_mfma_f32_16x16x32_bf16 v[32:35], v[242:245], v[238:241], v[32:35]
	v_mfma_f32_16x16x32_bf16 v[36:39], v[152:155], v[238:241], v[36:39]
	s_barrier
	ds_read_b128 v[88:91], v160 offset:49152
	ds_read_b128 v[92:95], v160 offset:50176
	ds_read_b128 v[96:99], v159 offset:49152
	ds_read_b128 v[100:103], v159 offset:50176
	ds_read_b128 v[104:107], v158 offset:49152
	ds_read_b128 v[158:161], v158 offset:50176
	ds_read_b128 v[176:179], v157 offset:49152
	ds_read_b128 v[208:211], v157 offset:50176
	s_barrier
	s_waitcnt lgkmcnt(0)
	s_waitcnt lgkmcnt(0)
	v_mfma_f32_16x16x32_bf16 v[48:51], v[202:205], v[96:99], v[48:51]
	v_mfma_f32_16x16x32_bf16 v[64:67], v[172:175], v[88:91], v[218:221]
	v_mfma_f32_16x16x32_bf16 v[116:119], v[164:167], v[100:103], v[48:51]
	v_mfma_f32_16x16x32_bf16 v[48:51], v[172:175], v[104:107], v[230:233]
	v_mfma_f32_16x16x32_bf16 v[120:123], v[198:201], v[92:95], v[64:67]
	v_mfma_f32_16x16x32_bf16 v[64:67], v[202:205], v[88:91], v[222:225]
	v_mfma_f32_16x16x32_bf16 v[76:79], v[198:201], v[158:161], v[48:51]
	v_mfma_f32_16x16x32_bf16 v[48:51], v[202:205], v[104:107], v[234:237]
	v_mfma_f32_16x16x32_bf16 v[124:127], v[164:167], v[92:95], v[64:67]
	v_mfma_f32_16x16x32_bf16 v[64:67], v[172:175], v[96:99], v[226:229]
	v_mfma_f32_16x16x32_bf16 v[80:83], v[164:167], v[158:161], v[48:51]
	v_mfma_f32_16x16x32_bf16 v[48:51], v[172:175], v[176:179], v[136:139]
	v_mfma_f32_16x16x32_bf16 v[112:115], v[198:201], v[100:103], v[64:67]
	v_mfma_f32_16x16x32_bf16 v[64:67], v[198:201], v[208:211], v[48:51]
	v_mfma_f32_16x16x32_bf16 v[48:51], v[202:205], v[176:179], v[144:147]
	v_mfma_f32_16x16x32_bf16 v[68:71], v[164:167], v[208:211], v[48:51]
	v_mfma_f32_16x16x32_bf16 v[48:51], v[108:111], v[88:91], v[148:151]
	v_mfma_f32_16x16x32_bf16 v[84:87], v[242:245], v[92:95], v[48:51]
	v_mfma_f32_16x16x32_bf16 v[48:51], v[246:249], v[88:91], v[168:171]
	v_mfma_f32_16x16x32_bf16 v[88:91], v[152:155], v[92:95], v[48:51]
	v_mfma_f32_16x16x32_bf16 v[48:51], v[108:111], v[96:99], v[182:185]
	v_mfma_f32_16x16x32_bf16 v[92:95], v[242:245], v[100:103], v[48:51]
	v_mfma_f32_16x16x32_bf16 v[48:51], v[246:249], v[96:99], v[186:189]
	v_mfma_f32_16x16x32_bf16 v[96:99], v[152:155], v[100:103], v[48:51]
	v_mfma_f32_16x16x32_bf16 v[48:51], v[108:111], v[104:107], v[190:193]
	v_mfma_f32_16x16x32_bf16 v[100:103], v[242:245], v[158:161], v[48:51]
	v_mfma_f32_16x16x32_bf16 v[48:51], v[246:249], v[104:107], v[194:197]
	v_mfma_f32_16x16x32_bf16 v[104:107], v[152:155], v[158:161], v[48:51]
	v_mfma_f32_16x16x32_bf16 v[48:51], v[108:111], v[176:179], v[128:131]
	v_mfma_f32_16x16x32_bf16 v[108:111], v[242:245], v[208:211], v[48:51]
	v_mfma_f32_16x16x32_bf16 v[48:51], v[246:249], v[176:179], v[140:143]
	v_mfma_f32_16x16x32_bf16 v[48:51], v[152:155], v[208:211], v[48:51]
	s_movk_i32 s14, 0x100
	v_cmp_gt_u32_e32 vcc, s14, v132
	s_barrier
	s_and_saveexec_b64 s[44:45], vcc
	s_cbranch_execz .LBB0_1200
	s_barrier
	s_branch .LBB0_1200
